# adds: RSS partial sums stored as [16-row group][slice][row] so each epilogue RSS store is one 64-byte segment; fill_rstd reads 32 dwords, FINAL and PRO_C remapped
# baseline (speedup 1.0000x reference)
; __device__ __forceinline__ unsigned cvt_pk_bf16_c(float lo, float hi) { const f32x2_t v = {lo, hi}; return __builtin_bit_cast(unsigned, __builtin_convertvector(v, bf16x2_t)); }
; __device__ __forceinline__ float bperm(float v, int src_lane) { return __int_as_float(__builtin_amdgcn_ds_bpermute(src_lane << 2, __float_as_int(v))); }
; __host__ __device__ __forceinline__ size_t xs_off(int row, int col) { return (size_t)(row >> 8) * (256 * D) + (size_t)(col >> 6) * (256 * 64) + (size_t)((row & 255) * 64 + (col & 63)); }
; __device__ __forceinline__ void pro_c(LAS unsigned char* lds, const float* const* in, unsigned char* wsl, int cid, int G, int tid) {
;     ...
;     for (int row = cid * 8 + wave; row < M; row += G * 8) { const int b = row / SEQ;
;         const float* xr = in[0] + (size_t)row * D; bf16_t* xs = (bf16_t*)(wsl + O_XS); float* rss = (float*)(wsl + O_RSS1) + (size_t)row * 32;
; #pragma unroll
;         for (int j = 0; j < 8; ++j) { const int c = 4 * lane + 256 * j; const f32x4 v = __builtin_nontemporal_load((const f32x4*)(xr + c));
;             const f32x4 g = *(const f32x4*)(in[4] + c), sc = *(const f32x4*)(MOD + (size_t)b * 6 * D + D + c);
;             u32x2 o; o.x = cvt_pk_bf16_c(v.x * (g.x * (1.f + sc.x)), v.y * (g.y * (1.f + sc.y))); o.y = cvt_pk_bf16_c(v.z * (g.z * (1.f + sc.z)), v.w * (g.w * (1.f + sc.w)));
;             *(u32x2*)(xs + xs_off(row, c)) = o;
;             float ss = (v.x * v.x + v.y * v.y) + (v.z * v.z + v.w * v.w);
;             ss += bperm(ss, lane ^ 1); ss += bperm(ss, lane ^ 2); ss += bperm(ss, lane ^ 4); ss += bperm(ss, lane ^ 8);
;             if ((lane & 15) == 0) rss[4 * j + (lane >> 4)] = ss; }
.LBB0_234:
	v_readlane_b32 s12, v254, 30
	s_cmpk_gt_i32 s6, 0x3fff
	v_readlane_b32 s13, v254, 31
	v_readlane_b32 s20, v254, 38
	v_readlane_b32 s21, v254, 39
	v_readlane_b32 s40, v254, 14
	s_mov_b32 s63, s74
	v_readlane_b32 s14, v254, 32
	v_readlane_b32 s15, v254, 33
	v_readlane_b32 s16, v254, 34
	v_readlane_b32 s17, v254, 35
	v_readlane_b32 s18, v254, 36
	v_readlane_b32 s19, v254, 37
	v_readlane_b32 s22, v254, 40
	v_readlane_b32 s23, v254, 41
	v_readlane_b32 s24, v254, 42
	v_readlane_b32 s25, v254, 43
	v_readlane_b32 s26, v254, 44
	v_readlane_b32 s27, v254, 45
	v_readlane_b32 s41, v254, 15
	v_readlane_b32 s42, v254, 16
	v_readlane_b32 s43, v254, 17
	v_readlane_b32 s44, v254, 18
	v_readlane_b32 s45, v254, 19
	v_readlane_b32 s46, v254, 20
	v_readlane_b32 s47, v254, 21
	v_readlane_b32 s48, v254, 22
	v_readlane_b32 s49, v254, 23
	v_readlane_b32 s50, v254, 24
	v_readlane_b32 s51, v254, 25
	v_readlane_b32 s52, v254, 26
	v_readlane_b32 s53, v254, 27
	v_readlane_b32 s54, v254, 28
	v_readlane_b32 s55, v254, 29
	s_cbranch_scc1 .LBB0_253
	v_and_b32_e32 v0, 15, v53
	v_cmp_eq_u32_e32 vcc, 0, v0
	v_lshlrev_b32_e32 v0, 10, v55
	v_or_b32_e32 v18, 0x100, v52
	v_and_b32_e32 v16, 0xc000, v0
	v_lshlrev_b32_e32 v0, 8, v18
	v_or_b32_e32 v22, 0x200, v52
	v_and_b32_e32 v20, 0x1c000, v0
	v_lshlrev_b32_e32 v0, 8, v22
	v_or_b32_e32 v26, 0x300, v52
	v_and_b32_e32 v24, 0x2c000, v0
	v_lshlrev_b32_e32 v0, 8, v26
	v_or_b32_e32 v30, 0x400, v52
	s_add_u32 s3, s3, 0x20104000
	v_and_b32_e32 v28, 0x3c000, v0
	v_lshlrev_b32_e32 v0, 8, v30
	v_or_b32_e32 v44, 0x500, v52
	s_addc_u32 s16, s33, 0
	v_and_b32_e32 v32, 0x4c000, v0
	v_lshlrev_b32_e32 v0, 8, v44
	v_or_b32_e32 v48, 0x600, v52
	s_lshl_b32 s1, s7, 6
	s_ashr_i32 s7, s6, 31
	s_lshl_b32 s0, s38, 3
	v_and_b32_e32 v46, 0x5c000, v0
	v_lshlrev_b32_e32 v0, 8, v48
	v_or_b32_e32 v54, 0x700, v52
	s_add_i32 s2, s2, s1
	s_lshl_b32 s17, s38, 9
	s_lshl_b64 s[10:11], s[6:7], 13
	v_and_b32_e32 v50, 0x6c000, v0
	v_lshlrev_b32_e32 v0, 8, v54
	s_add_u32 s10, s12, s10
	s_waitcnt lgkmcnt(0)
	v_mov_b32_e32 v1, 0
	v_and_b32_e32 v56, 0x7c000, v0
	v_lshlrev_b32_e32 v0, 4, v55
	s_addc_u32 s11, s13, s11
	v_lshl_add_u64 v[12:13], s[10:11], 0, v[0:1]
	s_mov_b64 s[10:11], 0x1000
	s_ashr_i32 s1, s0, 31
	v_lshlrev_b32_e32 v4, 2, v30
	v_mov_b32_e32 v5, v1
	v_lshlrev_b32_e32 v6, 2, v44
	v_mov_b32_e32 v7, v1
	v_lshlrev_b32_e32 v8, 2, v48
	v_mov_b32_e32 v9, v1
	v_lshlrev_b32_e32 v10, 2, v54
	v_mov_b32_e32 v11, v1
	v_lshl_add_u64 v[12:13], v[12:13], 0, s[10:11]
	s_lshl_b64 s[10:11], s[0:1], 13
	s_and_b32 s100, s6, 15
	s_lshl_b32 s100, s100, 2
	s_andn2_b32 s12, s6, 15
	s_mov_b32 s13, s7
	s_lshl_b64 s[12:13], s[12:13], 7
	s_add_u32 s12, s12, s100
	s_addc_u32 s13, s13, 0
	v_lshl_add_u64 v[2:3], s[20:21], 0, v[0:1]
	v_lshl_add_u64 v[4:5], s[20:21], 0, v[4:5]
	v_lshl_add_u64 v[6:7], s[20:21], 0, v[6:7]
	v_lshl_add_u64 v[8:9], s[20:21], 0, v[8:9]
	v_lshl_add_u64 v[10:11], s[20:21], 0, v[10:11]
	s_add_u32 s7, s8, s12
	v_readlane_b32 s20, v254, 0
	s_addc_u32 s9, s9, s13
	v_readlane_b32 s24, v254, 4
	v_lshrrev_b32_e32 v0, 2, v55
	v_readlane_b32 s25, v254, 5
	s_add_u32 s8, s24, s7
	v_and_b32_e32 v0, 12, v0
	v_lshlrev_b32_e32 v0, 4, v0
	s_addc_u32 s9, s25, s9
	v_lshl_add_u64 v[14:15], s[8:9], 0, v[0:1]
	s_mov_b64 s[8:9], 0x304040
	v_and_b32_e32 v34, 28, v52
	v_and_b32_e32 v62, 32, v52
	v_lshl_or_b32 v34, v62, 4, v34
	v_xor_b32_e32 v35, 4, v52
	v_xor_b32_e32 v36, 8, v52
	v_xor_b32_e32 v37, 16, v52
	v_xor_b32_e32 v38, 32, v52
	v_lshl_add_u64 v[14:15], v[14:15], 0, s[8:9]
	s_lshl_b64 s[8:9], s[0:1], 7
	v_lshlrev_b32_e32 v39, 2, v52
	v_lshlrev_b32_e32 v16, 1, v16
	v_lshlrev_b32_e32 v40, 2, v18
	v_lshlrev_b32_e32 v18, 1, v20
	v_lshlrev_b32_e32 v41, 2, v22
	v_lshlrev_b32_e32 v20, 1, v24
	v_lshlrev_b32_e32 v42, 2, v26
	v_lshlrev_b32_e32 v22, 1, v28
	v_lshlrev_b32_e32 v43, 2, v30
	v_lshlrev_b32_e32 v24, 1, v32
	v_lshlrev_b32_e32 v44, 2, v44
	v_lshlrev_b32_e32 v26, 1, v46
	v_lshlrev_b32_e32 v45, 2, v48
	v_lshlrev_b32_e32 v28, 1, v50
	v_lshlrev_b32_e32 v46, 2, v54
	v_lshlrev_b32_e32 v30, 1, v56
	v_mov_b32_e32 v17, v1
	v_readlane_b32 s21, v254, 1
	v_readlane_b32 s22, v254, 2
	v_readlane_b32 s23, v254, 3
	v_readlane_b32 s26, v254, 6
	v_readlane_b32 s27, v254, 7
	s_branch .LBB0_237

; __device__ __forceinline__ unsigned cvt_pk_bf16_c(float lo, float hi) { const f32x2_t v = {lo, hi}; return __builtin_bit_cast(unsigned, __builtin_convertvector(v, bf16x2_t)); }
; __device__ __forceinline__ float bperm(float v, int src_lane) { return __int_as_float(__builtin_amdgcn_ds_bpermute(src_lane << 2, __float_as_int(v))); }
; __host__ __device__ __forceinline__ size_t xs_off(int row, int col) { return (size_t)(row >> 8) * (256 * D) + (size_t)(col >> 6) * (256 * 64) + (size_t)((row & 255) * 64 + (col & 63)); }
; __device__ __forceinline__ void pro_c(LAS unsigned char* lds, const float* const* in, unsigned char* wsl, int cid, int G, int tid) {
;     ...
;         for (int j = 0; j < 8; ++j) { const int c = 4 * lane + 256 * j; const f32x4 v = __builtin_nontemporal_load((const f32x4*)(xr + c));
;             const f32x4 g = *(const f32x4*)(in[4] + c), sc = *(const f32x4*)(MOD + (size_t)b * 6 * D + D + c);
;             u32x2 o; o.x = cvt_pk_bf16_c(v.x * (g.x * (1.f + sc.x)), v.y * (g.y * (1.f + sc.y))); o.y = cvt_pk_bf16_c(v.z * (g.z * (1.f + sc.z)), v.w * (g.w * (1.f + sc.w)));
;             *(u32x2*)(xs + xs_off(row, c)) = o;
;             float ss = (v.x * v.x + v.y * v.y) + (v.z * v.z + v.w * v.w);
;             ss += bperm(ss, lane ^ 1); ss += bperm(ss, lane ^ 2); ss += bperm(ss, lane ^ 4); ss += bperm(ss, lane ^ 8);
;             if ((lane & 15) == 0) rss[4 * j + (lane >> 4)] = ss; }
.LBB0_239:
	s_or_b64 exec, exec, s[14:15]
	global_load_dwordx4 v[48:51], v[12:13], off offset:-3072 nt
	global_load_dwordx4 v[52:55], v40, s[12:13]
	global_load_dwordx4 v[56:59], v[2:3], off offset:1024
	s_waitcnt vmcnt(2)
	v_mul_f32_e32 v0, v49, v49
	s_waitcnt lgkmcnt(0)
	v_mul_f32_e32 v19, v51, v51
	v_fmac_f32_e32 v0, v48, v48
	v_fmac_f32_e32 v19, v50, v50
	v_add_f32_e32 v0, v0, v19
	ds_bpermute_b32 v19, v35, v0
	s_waitcnt vmcnt(1)
	v_pk_add_f32 v[52:53], v[52:53], 1.0 op_sel_hi:[1,0]
	s_waitcnt lgkmcnt(0)
	v_add_f32_e32 v0, v0, v19
	ds_bpermute_b32 v19, v36, v0
	s_waitcnt vmcnt(0)
	v_pk_mul_f32 v[52:53], v[56:57], v[52:53]
	s_waitcnt lgkmcnt(0)
	v_add_f32_e32 v0, v0, v19
	ds_bpermute_b32 v19, v37, v0
	v_pk_mul_f32 v[48:49], v[48:49], v[52:53]
	v_pk_add_f32 v[52:53], v[54:55], 1.0 op_sel_hi:[1,0]
	v_cvt_pk_bf16_f32 v48, v48, v49
	v_pk_mul_f32 v[52:53], v[58:59], v[52:53]
	s_waitcnt lgkmcnt(0)
	v_add_f32_e32 v0, v0, v19
	ds_bpermute_b32 v21, v38, v0
	v_pk_mul_f32 v[50:51], v[50:51], v[52:53]
	v_mov_b32_e32 v19, v1
	v_cvt_pk_bf16_f32 v49, v50, v51
	v_lshl_add_u64 v[50:51], v[32:33], 0, v[18:19]
	global_store_dwordx2 v[50:51], v[48:49], off
	s_and_saveexec_b64 s[14:15], vcc
	s_cbranch_execz .LBB0_241
	s_waitcnt lgkmcnt(0)
	v_add_f32_e32 v0, v0, v21
	global_store_dword v[14:15], v0, off offset:192
.LBB0_241:
	s_or_b64 exec, exec, s[14:15]
	global_load_dwordx4 v[48:51], v[12:13], off offset:-2048 nt
	global_load_dwordx4 v[52:55], v41, s[12:13]
	global_load_dwordx4 v[56:59], v[2:3], off offset:2048
	s_waitcnt lgkmcnt(0)
	v_mov_b32_e32 v21, v1
	s_waitcnt vmcnt(2)
	v_mul_f32_e32 v0, v49, v49
	v_mul_f32_e32 v19, v51, v51
	v_fmac_f32_e32 v0, v48, v48
	v_fmac_f32_e32 v19, v50, v50
	v_add_f32_e32 v0, v0, v19
	ds_bpermute_b32 v19, v35, v0
	s_waitcnt vmcnt(1)
	v_pk_add_f32 v[52:53], v[52:53], 1.0 op_sel_hi:[1,0]
	s_waitcnt lgkmcnt(0)
	v_add_f32_e32 v0, v0, v19
	ds_bpermute_b32 v19, v36, v0
	s_waitcnt vmcnt(0)
	v_pk_mul_f32 v[52:53], v[56:57], v[52:53]
	s_waitcnt lgkmcnt(0)
	v_add_f32_e32 v0, v0, v19
	ds_bpermute_b32 v19, v37, v0
	v_pk_mul_f32 v[48:49], v[48:49], v[52:53]
	v_pk_add_f32 v[52:53], v[54:55], 1.0 op_sel_hi:[1,0]
	v_cvt_pk_bf16_f32 v48, v48, v49
	v_pk_mul_f32 v[52:53], v[58:59], v[52:53]
	s_waitcnt lgkmcnt(0)
	v_add_f32_e32 v0, v0, v19
	ds_bpermute_b32 v19, v38, v0
	v_pk_mul_f32 v[50:51], v[50:51], v[52:53]
	s_nop 0
	v_cvt_pk_bf16_f32 v49, v50, v51
	v_lshl_add_u64 v[50:51], v[32:33], 0, v[20:21]
	global_store_dwordx2 v[50:51], v[48:49], off
	s_and_saveexec_b64 s[14:15], vcc
	s_cbranch_execz .LBB0_243
	s_waitcnt lgkmcnt(0)
	v_add_f32_e32 v0, v0, v19
	global_store_dword v[14:15], v0, off offset:448
.LBB0_243:
	s_or_b64 exec, exec, s[14:15]
	global_load_dwordx4 v[48:51], v[12:13], off offset:-1024 nt
	global_load_dwordx4 v[52:55], v42, s[12:13]
	global_load_dwordx4 v[56:59], v[2:3], off offset:3072
	v_mov_b32_e32 v23, v1
	s_waitcnt vmcnt(2)
	v_mul_f32_e32 v0, v49, v49
	s_waitcnt lgkmcnt(0)
	v_mul_f32_e32 v19, v51, v51
	v_fmac_f32_e32 v0, v48, v48
	v_fmac_f32_e32 v19, v50, v50
	v_add_f32_e32 v0, v0, v19
	ds_bpermute_b32 v19, v35, v0
	s_waitcnt vmcnt(1)
	v_pk_add_f32 v[52:53], v[52:53], 1.0 op_sel_hi:[1,0]
	s_waitcnt lgkmcnt(0)
	v_add_f32_e32 v0, v0, v19
	ds_bpermute_b32 v19, v36, v0
	s_waitcnt vmcnt(0)
	v_pk_mul_f32 v[52:53], v[56:57], v[52:53]
	s_waitcnt lgkmcnt(0)
	v_add_f32_e32 v0, v0, v19
	ds_bpermute_b32 v19, v37, v0
	v_pk_mul_f32 v[48:49], v[48:49], v[52:53]
	v_pk_add_f32 v[52:53], v[54:55], 1.0 op_sel_hi:[1,0]
	v_cvt_pk_bf16_f32 v48, v48, v49
	v_pk_mul_f32 v[52:53], v[58:59], v[52:53]
	s_waitcnt lgkmcnt(0)
	v_add_f32_e32 v0, v0, v19
	ds_bpermute_b32 v19, v38, v0
	v_pk_mul_f32 v[50:51], v[50:51], v[52:53]
	s_nop 0
	v_cvt_pk_bf16_f32 v49, v50, v51
	v_lshl_add_u64 v[50:51], v[32:33], 0, v[22:23]
	global_store_dwordx2 v[50:51], v[48:49], off
	s_and_saveexec_b64 s[14:15], vcc
	s_cbranch_execz .LBB0_245
	s_waitcnt lgkmcnt(0)
	v_add_f32_e32 v0, v0, v19
	global_store_dword v[14:15], v0, off offset:704
; __device__ __forceinline__ unsigned cvt_pk_bf16_c(float lo, float hi) { const f32x2_t v = {lo, hi}; return __builtin_bit_cast(unsigned, __builtin_convertvector(v, bf16x2_t)); }
; __device__ __forceinline__ float bperm(float v, int src_lane) { return __int_as_float(__builtin_amdgcn_ds_bpermute(src_lane << 2, __float_as_int(v))); }
; __host__ __device__ __forceinline__ size_t xs_off(int row, int col) { return (size_t)(row >> 8) * (256 * D) + (size_t)(col >> 6) * (256 * 64) + (size_t)((row & 255) * 64 + (col & 63)); }
; __device__ __forceinline__ void pro_c(LAS unsigned char* lds, const float* const* in, unsigned char* wsl, int cid, int G, int tid) {
;     ...
;         for (int j = 0; j < 8; ++j) { const int c = 4 * lane + 256 * j; const f32x4 v = __builtin_nontemporal_load((const f32x4*)(xr + c));
;             const f32x4 g = *(const f32x4*)(in[4] + c), sc = *(const f32x4*)(MOD + (size_t)b * 6 * D + D + c);
;             u32x2 o; o.x = cvt_pk_bf16_c(v.x * (g.x * (1.f + sc.x)), v.y * (g.y * (1.f + sc.y))); o.y = cvt_pk_bf16_c(v.z * (g.z * (1.f + sc.z)), v.w * (g.w * (1.f + sc.w)));
;             *(u32x2*)(xs + xs_off(row, c)) = o;
;             float ss = (v.x * v.x + v.y * v.y) + (v.z * v.z + v.w * v.w);
;             ss += bperm(ss, lane ^ 1); ss += bperm(ss, lane ^ 2); ss += bperm(ss, lane ^ 4); ss += bperm(ss, lane ^ 8);
;             if ((lane & 15) == 0) rss[4 * j + (lane >> 4)] = ss; }
.LBB0_245:
	s_or_b64 exec, exec, s[14:15]
	global_load_dwordx4 v[48:51], v[12:13], off nt
	global_load_dwordx4 v[52:55], v43, s[12:13]
	global_load_dwordx4 v[56:59], v[4:5], off
	v_mov_b32_e32 v25, v1
	s_waitcnt vmcnt(2)
	v_mul_f32_e32 v0, v49, v49
	s_waitcnt lgkmcnt(0)
	v_mul_f32_e32 v19, v51, v51
	v_fmac_f32_e32 v0, v48, v48
	v_fmac_f32_e32 v19, v50, v50
	v_add_f32_e32 v0, v0, v19
	ds_bpermute_b32 v19, v35, v0
	s_waitcnt vmcnt(1)
	v_pk_add_f32 v[52:53], v[52:53], 1.0 op_sel_hi:[1,0]
	s_waitcnt lgkmcnt(0)
	v_add_f32_e32 v0, v0, v19
	ds_bpermute_b32 v19, v36, v0
	s_waitcnt vmcnt(0)
	v_pk_mul_f32 v[52:53], v[56:57], v[52:53]
	s_waitcnt lgkmcnt(0)
	v_add_f32_e32 v0, v0, v19
	ds_bpermute_b32 v19, v37, v0
	v_pk_mul_f32 v[48:49], v[48:49], v[52:53]
	v_pk_add_f32 v[52:53], v[54:55], 1.0 op_sel_hi:[1,0]
	v_cvt_pk_bf16_f32 v48, v48, v49
	v_pk_mul_f32 v[52:53], v[58:59], v[52:53]
	s_waitcnt lgkmcnt(0)
	v_add_f32_e32 v0, v0, v19
	ds_bpermute_b32 v19, v38, v0
	v_pk_mul_f32 v[50:51], v[50:51], v[52:53]
	s_nop 0
	v_cvt_pk_bf16_f32 v49, v50, v51
	v_lshl_add_u64 v[50:51], v[32:33], 0, v[24:25]
	global_store_dwordx2 v[50:51], v[48:49], off
	s_and_saveexec_b64 s[14:15], vcc
	s_cbranch_execz .LBB0_247
	s_waitcnt lgkmcnt(0)
	v_add_f32_e32 v0, v0, v19
	global_store_dword v[14:15], v0, off offset:960
.LBB0_247:
	s_or_b64 exec, exec, s[14:15]
	global_load_dwordx4 v[48:51], v[12:13], off offset:1024 nt
	global_load_dwordx4 v[52:55], v44, s[12:13]
	global_load_dwordx4 v[56:59], v[6:7], off
	v_mov_b32_e32 v27, v1
	s_waitcnt vmcnt(2)
	v_mul_f32_e32 v0, v49, v49
	s_waitcnt lgkmcnt(0)
	v_mul_f32_e32 v19, v51, v51
	v_fmac_f32_e32 v0, v48, v48
	v_fmac_f32_e32 v19, v50, v50
	v_add_f32_e32 v0, v0, v19
	ds_bpermute_b32 v19, v35, v0
	s_waitcnt vmcnt(1)
	v_pk_add_f32 v[52:53], v[52:53], 1.0 op_sel_hi:[1,0]
	s_waitcnt lgkmcnt(0)
	v_add_f32_e32 v0, v0, v19
	ds_bpermute_b32 v19, v36, v0
	s_waitcnt vmcnt(0)
	v_pk_mul_f32 v[52:53], v[56:57], v[52:53]
	s_waitcnt lgkmcnt(0)
	v_add_f32_e32 v0, v0, v19
	ds_bpermute_b32 v19, v37, v0
	v_pk_mul_f32 v[48:49], v[48:49], v[52:53]
	v_pk_add_f32 v[52:53], v[54:55], 1.0 op_sel_hi:[1,0]
	v_cvt_pk_bf16_f32 v48, v48, v49
	v_pk_mul_f32 v[52:53], v[58:59], v[52:53]
	s_waitcnt lgkmcnt(0)
	v_add_f32_e32 v0, v0, v19
	ds_bpermute_b32 v19, v38, v0
	v_pk_mul_f32 v[50:51], v[50:51], v[52:53]
	s_nop 0
	v_cvt_pk_bf16_f32 v49, v50, v51
	v_lshl_add_u64 v[50:51], v[32:33], 0, v[26:27]
	global_store_dwordx2 v[50:51], v[48:49], off
	s_and_saveexec_b64 s[14:15], vcc
	s_cbranch_execz .LBB0_249
	s_waitcnt lgkmcnt(0)
	v_add_f32_e32 v0, v0, v19
	global_store_dword v[14:15], v0, off offset:1216
.LBB0_249:
	s_or_b64 exec, exec, s[14:15]
	global_load_dwordx4 v[48:51], v[12:13], off offset:2048 nt
	global_load_dwordx4 v[52:55], v45, s[12:13]
	global_load_dwordx4 v[56:59], v[8:9], off
	v_mov_b32_e32 v29, v1
	s_waitcnt vmcnt(2)
	v_mul_f32_e32 v0, v49, v49
	s_waitcnt lgkmcnt(0)
	v_mul_f32_e32 v19, v51, v51
	v_fmac_f32_e32 v0, v48, v48
	v_fmac_f32_e32 v19, v50, v50
	v_add_f32_e32 v0, v0, v19
	ds_bpermute_b32 v19, v35, v0
	s_waitcnt vmcnt(1)
	v_pk_add_f32 v[52:53], v[52:53], 1.0 op_sel_hi:[1,0]
	s_waitcnt lgkmcnt(0)
	v_add_f32_e32 v0, v0, v19
	ds_bpermute_b32 v19, v36, v0
	s_waitcnt vmcnt(0)
	v_pk_mul_f32 v[52:53], v[56:57], v[52:53]
	s_waitcnt lgkmcnt(0)
	v_add_f32_e32 v0, v0, v19
	ds_bpermute_b32 v19, v37, v0
	v_pk_mul_f32 v[48:49], v[48:49], v[52:53]
	v_pk_add_f32 v[52:53], v[54:55], 1.0 op_sel_hi:[1,0]
	v_cvt_pk_bf16_f32 v48, v48, v49
	v_pk_mul_f32 v[52:53], v[58:59], v[52:53]
	s_waitcnt lgkmcnt(0)
	v_add_f32_e32 v0, v0, v19
	ds_bpermute_b32 v19, v38, v0
	v_pk_mul_f32 v[50:51], v[50:51], v[52:53]
	s_nop 0
	v_cvt_pk_bf16_f32 v49, v50, v51
	v_lshl_add_u64 v[50:51], v[32:33], 0, v[28:29]
	global_store_dwordx2 v[50:51], v[48:49], off
	s_and_saveexec_b64 s[14:15], vcc
	s_cbranch_execz .LBB0_251
	s_waitcnt lgkmcnt(0)
	v_add_f32_e32 v0, v0, v19
	global_store_dword v[14:15], v0, off offset:1472
.LBB0_251:
	s_or_b64 exec, exec, s[14:15]
	global_load_dwordx4 v[48:51], v[12:13], off offset:3072 nt
	global_load_dwordx4 v[52:55], v46, s[12:13]
	global_load_dwordx4 v[56:59], v[10:11], off
	v_mov_b32_e32 v31, v1
	v_lshl_add_u64 v[32:33], v[32:33], 0, v[30:31]
	s_waitcnt vmcnt(2)
	v_mul_f32_e32 v0, v49, v49
	s_waitcnt lgkmcnt(0)
	v_mul_f32_e32 v19, v51, v51
	v_fmac_f32_e32 v0, v48, v48
	v_fmac_f32_e32 v19, v50, v50
	v_add_f32_e32 v0, v0, v19
	ds_bpermute_b32 v19, v35, v0
	s_waitcnt vmcnt(1)
	v_pk_add_f32 v[52:53], v[52:53], 1.0 op_sel_hi:[1,0]
	s_waitcnt lgkmcnt(0)
	v_add_f32_e32 v0, v0, v19
	ds_bpermute_b32 v19, v36, v0
	s_waitcnt vmcnt(0)
	v_pk_mul_f32 v[52:53], v[56:57], v[52:53]
	s_waitcnt lgkmcnt(0)
	v_add_f32_e32 v0, v0, v19
	ds_bpermute_b32 v19, v37, v0
	v_pk_mul_f32 v[48:49], v[48:49], v[52:53]
	v_pk_add_f32 v[52:53], v[54:55], 1.0 op_sel_hi:[1,0]
	v_cvt_pk_bf16_f32 v48, v48, v49
	v_pk_mul_f32 v[52:53], v[58:59], v[52:53]
	s_waitcnt lgkmcnt(0)
	v_add_f32_e32 v0, v0, v19
	ds_bpermute_b32 v19, v38, v0
	v_pk_mul_f32 v[50:51], v[50:51], v[52:53]
	s_nop 0
	v_cvt_pk_bf16_f32 v49, v50, v51
	global_store_dwordx2 v[32:33], v[48:49], off
	s_and_saveexec_b64 s[12:13], vcc
	s_cbranch_execz .LBB0_236
	s_waitcnt lgkmcnt(0)
	v_add_f32_e32 v0, v0, v19
	global_store_dword v[14:15], v0, off offset:1728
	s_branch .LBB0_236

;     __host__ __device__ __forceinline__ bool next(int i, Unit& u) const { const int vv = vid + (i / 5) * G; if (vv >= 256) return false; u.pm = vv >> 2; u.pn = (vv & 3) + 4 * (i % 5); return true; }
;     __host__ __device__ __forceinline__ bool next(int i, pg8::Unit& u) const { const long Lx = (long)i * G + c; if (Lx >= 128) return false; const int Lq = (int)Lx; u.pm = 8 * (Lq >> 5) + (Lq & 7); u.pn = (Lq >> 3) & 3; return true; }
; template <class Sched> __device__ __forceinline__ void fill_rstd(LAS unsigned char* lds, const float* RSS, const Sched& S, int tid) {
;     ...
;     for (int i = tid >> 8; S.next(i, u); i += 2) {
;         if (u.pm != prev_pm) { const float* p = RSS + (size_t)(u.pm * 256 + row) * 32; float s_ = 0.f;
; #pragma unroll
;             for (int j = 0; j < 8; ++j) { const f32x4 a = *(const f32x4*)(p + 4 * j); s_ += (a.x + a.y) + (a.z + a.w); }
;             prev = rsqrtf(s_ * (1.f / D) + EPS); prev_pm = u.pm; }
.LBB0_318:
	v_mov_b32_e32 v15, v12
	v_ashrrev_i32_e32 v12, 2, v13
	v_cmp_ne_u32_e32 vcc, v12, v15
	s_and_saveexec_b64 s[22:23], vcc
	s_cbranch_execz .LBB0_317
	v_lshl_or_b32 v14, v12, 8, v9
	v_ashrrev_i32_e32 v15, 31, v14
	v_lshlrev_b64 v[14:15], 7, v[14:15]
	v_bfe_u32 v15, v14, 7, 4
	v_lshl_add_u32 v14, v15, 2, v14
	v_lshlrev_b32_e32 v15, 7, v15
	v_sub_u32_e32 v14, v14, v15
	v_mov_b32_e32 v15, 0
	v_lshl_add_u64 v[30:31], s[18:19], 0, v[14:15]
	global_load_dword v40, v[30:31], off
	global_load_dword v41, v[30:31], off offset:64
	global_load_dword v42, v[30:31], off offset:128
	global_load_dword v43, v[30:31], off offset:192
	global_load_dword v44, v[30:31], off offset:256
	global_load_dword v45, v[30:31], off offset:320
	global_load_dword v46, v[30:31], off offset:384
	global_load_dword v47, v[30:31], off offset:448
	global_load_dword v48, v[30:31], off offset:512
	global_load_dword v49, v[30:31], off offset:576
	global_load_dword v50, v[30:31], off offset:640
	global_load_dword v51, v[30:31], off offset:704
	global_load_dword v52, v[30:31], off offset:768
	global_load_dword v53, v[30:31], off offset:832
	global_load_dword v54, v[30:31], off offset:896
	global_load_dword v55, v[30:31], off offset:960
	global_load_dword v56, v[30:31], off offset:1024
	global_load_dword v57, v[30:31], off offset:1088
	global_load_dword v58, v[30:31], off offset:1152
	global_load_dword v59, v[30:31], off offset:1216
	global_load_dword v60, v[30:31], off offset:1280
	global_load_dword v61, v[30:31], off offset:1344
	global_load_dword v62, v[30:31], off offset:1408
	global_load_dword v63, v[30:31], off offset:1472
	global_load_dword v64, v[30:31], off offset:1536
	global_load_dword v65, v[30:31], off offset:1600
	global_load_dword v66, v[30:31], off offset:1664
	global_load_dword v67, v[30:31], off offset:1728
	global_load_dword v68, v[30:31], off offset:1792
	global_load_dword v69, v[30:31], off offset:1856
	global_load_dword v70, v[30:31], off offset:1920
	global_load_dword v71, v[30:31], off offset:1984
	s_waitcnt vmcnt(0)
	v_add_f32_e32 v40, v40, v41
	v_add_f32_e32 v42, v42, v43
	v_add_f32_e32 v44, v44, v45
	v_add_f32_e32 v46, v46, v47
	v_add_f32_e32 v48, v48, v49
	v_add_f32_e32 v50, v50, v51
	v_add_f32_e32 v52, v52, v53
	v_add_f32_e32 v54, v54, v55
	v_add_f32_e32 v56, v56, v57
	v_add_f32_e32 v58, v58, v59
	v_add_f32_e32 v60, v60, v61
	v_add_f32_e32 v62, v62, v63
	v_add_f32_e32 v64, v64, v65
	v_add_f32_e32 v66, v66, v67
	v_add_f32_e32 v68, v68, v69
	v_add_f32_e32 v70, v70, v71
	v_add_f32_e32 v40, v40, v42
	v_add_f32_e32 v44, v44, v46
	v_add_f32_e32 v48, v48, v50
	v_add_f32_e32 v52, v52, v54
	v_add_f32_e32 v56, v56, v58
	v_add_f32_e32 v60, v60, v62
	v_add_f32_e32 v64, v64, v66
	v_add_f32_e32 v68, v68, v70
	v_add_f32_e32 v40, v40, v44
	v_add_f32_e32 v48, v48, v52
	v_add_f32_e32 v56, v56, v60
	v_add_f32_e32 v64, v64, v68
	v_add_f32_e32 v40, v40, v48
	v_add_f32_e32 v56, v56, v64
	v_add_f32_e32 v40, v40, v56
	v_mov_b32_e32 v13, v40
	v_fmamk_f32 v13, v13, 0x3a000000, v240
	v_cmp_gt_f32_e32 vcc, s3, v13
	v_mul_f32_e32 v14, 0x4b800000, v13
	s_nop 0
	v_cndmask_b32_e32 v13, v13, v14, vcc
	v_rsq_f32_e32 v13, v13
	s_nop 0
	v_mul_f32_e32 v14, 0x45800000, v13
	v_cndmask_b32_e32 v14, v13, v14, vcc
	s_branch .LBB0_317

;     template <bool INF32, int M0, int M1> __device__ __forceinline__ void half(f32x4 (&acc)[2][2][4][2], int ai, int b, int row0, int col, int pn, int wc, int fr, int fq) const {
;     ...
;             for (int m = M0; m < M1; ++m)
; #pragma unroll
;                 for (int bj = 0; bj < 2; ++bj) hh[m][bj] = *(const f16x8_t*)((const bf16_t*)xin + (size_t)(row0 + ai * 128 + m * 16) * D + col + bj * 128);
; #pragma unroll
;             for (int m = M0; m < M1; ++m)
; #pragma unroll
;                 for (int bj = 0; bj < 2; ++bj) { const f32x8_t ff = __builtin_convertvector(hh[m][bj], f32x8_t); xv[m][bj][0] = (f32x4){ff[0], ff[1], ff[2], ff[3]}; xv[m][bj][1] = (f32x4){ff[4], ff[5], ff[6], ff[7]}; }
;         }
;         f32x4 gt[2][2], gs[2][2];
; #pragma unroll
;         for (int bj = 0; bj < 2; ++bj)
; #pragma unroll
;             for (int n = 0; n < 2; ++n) { gt[bj][n] = *(const f32x4*)(gate + (size_t)b * 6 * D + col + bj * 128 + n * 4); gs[bj][n] = XS ? *(const f32x4*)(GS + (size_t)b * D + col + bj * 128 + n * 4) : (f32x4){0.f, 0.f, 0.f, 0.f}; }
;         __builtin_amdgcn_sched_barrier(0);
; #pragma unroll
;         for (int m = M0; m < M1; ++m) { const int row = row0 + ai * 128 + m * 16; float ss = 0.f;
; #pragma unroll
;             for (int bj = 0; bj < 2; ++bj) { const size_t o = (size_t)row * D + col + bj * 128;
;                 const f32x4 x0 = xv[m][bj][0] + gt[bj][0] * acc[ai][bj][m][0], x1 = xv[m][bj][1] + gt[bj][1] * acc[ai][bj][m][1];
;                 if (out_f32) { *(f32x4*)((float*)xout + o) = x0; *(f32x4*)((float*)xout + o + 4) = x1; }
;                 else { const f32x8_t ff = {x0.x, x0.y, x0.z, x0.w, x1.x, x1.y, x1.z, x1.w}; *(f16x8_t*)((bf16_t*)xout + o) = __builtin_convertvector(ff, f16x8_t); }
;                 ss += ((x0.x * x0.x + x0.y * x0.y) + (x0.z * x0.z + x0.w * x0.w)) + ((x1.x * x1.x + x1.y * x1.y) + (x1.z * x1.z + x1.w * x1.w));
;                 if (XS) *(u32x4*)(XS + xs_off(row0, col) + (ai * 128 + m * 16) * 64 + bj * (2 * 256 * 64)) = pack8(x0 * gs[bj][0], x1 * gs[bj][1]); }
;     __device__ __forceinline__ void operator()(f32x4 (&acc)[2][2][4][2], const pg8::Unit& u, int ui, int wr, int wc, int fr, int fq) const {
;         const int b = u.pm >> 4, row0 = u.pm * 256 + wr * 64 + fr, col = u.pn * 256 + wc * 32 + fq * 8;
.LBB0_1131:
	s_mul_i32 s100, s30, 0x1e00
	s_mul_i32 s101, s81, 62
	s_add_u32 s100, s100, s101
	s_mov_b32 s101, 0
	v_mbcnt_lo_u32_b32 v247, -1, 0
	v_mbcnt_hi_u32_b32 v247, -1, v247
	s_lshl_b32 s31, s28, 8
	v_ashrrev_i32_e32 v130, 4, v247
	v_and_b32_e32 v0, 15, v247
	s_add_i32 s31, s31, s80
	v_lshl_add_u32 v131, v130, 3, s81
	v_or_b32_e32 v200, s31, v0
	v_lshl_add_u32 v198, s30, 8, v131
	s_ashr_i32 s36, s28, 4
	v_ashrrev_i32_e32 v199, 31, v198
	v_or_b32_e32 v206, 16, v200
	v_or_b32_e32 v204, 32, v200
	v_or_b32_e32 v202, 48, v200
	v_lshlrev_b32_e32 v132, 6, v200
	v_and_b32_e32 v131, 56, v131
	v_lshlrev_b32_e32 v130, 6, v130
	v_lshlrev_b32_e32 v0, 2, v0
	s_movk_i32 s12, 0x33c0
	s_and_b64 vcc, exec, s[94:95]
	v_ashrrev_i32_e32 v201, 31, v200
	s_mul_hi_i32 s65, s36, 0xc000
	s_mul_i32 s66, s36, 0xc000
	v_lshlrev_b64 v[146:147], 2, v[198:199]
	v_cmp_gt_u32_e64 s[28:29], 16, v247
	v_ashrrev_i32_e32 v207, 31, v206
	v_ashrrev_i32_e32 v205, 31, v204
	v_ashrrev_i32_e32 v203, 31, v202
	v_ashrrev_i32_e32 v208, 6, v198
	v_and_or_b32 v246, v132, s12, v131
	v_and_b32_e32 v248, 0x3c0, v246
	v_lshrrev_b32_e32 v248, 1, v248
	v_and_b32_e32 v249, 32, v246
	v_lshlrev_b32_e32 v249, 4, v249
	v_and_b32_e32 v246, 0x1018, v246
	v_or3_b32 v246, v246, v248, v249
	v_bitop3_b32 v245, v130, 64, v0 bitop3:0x36
	v_bitop3_b32 v244, v130, s84, v0 bitop3:0x36
	s_cbranch_vccz .LBB0_1149
	v_lshlrev_b64 v[212:213], 1, v[198:199]
	v_lshl_add_u64 v[212:213], v[212:213], 0, s[100:101]
	v_lshl_add_u64 v[220:221], s[10:11], 0, v[212:213]
	v_lshlrev_b64 v[214:215], 12, v[200:201]
	v_bfe_u32 v215, v214, 12, 4
	v_lshl_add_u32 v214, v215, 6, v214
	v_lshlrev_b32_e32 v215, 12, v215
	v_sub_u32_e32 v214, v214, v215
	v_mov_b32_e32 v215, 0
	v_lshl_add_u64 v[134:135], v[220:221], 0, v[214:215]
	global_load_dwordx4 v[130:133], v[134:135], off
	s_nop 0
	global_load_dwordx4 v[134:137], v[134:135], off offset:1024
	s_ashr_i32 s37, s36, 31
	s_add_u32 s34, s63, s66
	v_lshlrev_b64 v[228:229], 12, v[206:207]
	v_bfe_u32 v229, v228, 12, 4
	v_lshl_add_u32 v228, v229, 6, v228
	v_lshlrev_b32_e32 v229, 12, v229
	v_sub_u32_e32 v228, v228, v229
	v_mov_b32_e32 v229, 0
	s_addc_u32 s35, s67, s65
	v_lshl_add_u64 v[138:139], v[220:221], 0, v[228:229]
	v_lshlrev_b64 v[226:227], 12, v[204:205]
	v_bfe_u32 v227, v226, 12, 4
	v_lshl_add_u32 v226, v227, 6, v226
	v_lshlrev_b32_e32 v227, 12, v227
	v_sub_u32_e32 v226, v226, v227
	v_mov_b32_e32 v227, 0
	v_lshl_add_u64 v[222:223], s[34:35], 0, v[146:147]
	s_lshl_b64 s[34:35], s[36:37], 13
	global_load_dwordx4 v[182:185], v[138:139], off
	global_load_dwordx4 v[178:181], v[138:139], off offset:1024
	v_lshl_add_u64 v[138:139], v[220:221], 0, v[226:227]
	v_lshlrev_b64 v[218:219], 12, v[202:203]
	v_bfe_u32 v219, v218, 12, 4
	v_lshl_add_u32 v218, v219, 6, v218
	v_lshlrev_b32_e32 v219, 12, v219
	v_sub_u32_e32 v218, v218, v219
	v_mov_b32_e32 v219, 0
	s_add_u32 s34, s68, s34
	global_load_dwordx4 v[174:177], v[138:139], off
	global_load_dwordx4 v[170:173], v[138:139], off offset:1024
	v_lshl_add_u64 v[138:139], v[220:221], 0, v[218:219]
	s_addc_u32 s35, s70, s35
	global_load_dwordx4 v[142:145], v[138:139], off
	s_nop 0
	global_load_dwordx4 v[138:141], v[138:139], off offset:1024
	v_lshl_add_u64 v[224:225], s[34:35], 0, v[146:147]
	s_waitcnt vmcnt(0)
	v_cvt_f32_f16_e32 v216, v132
	v_cvt_f32_f16_sdwa v217, v132 dst_sel:DWORD dst_unused:UNUSED_PAD src0_sel:WORD_1
	v_cvt_f32_f16_e32 v234, v133
	v_cvt_f32_f16_sdwa v235, v133 dst_sel:DWORD dst_unused:UNUSED_PAD src0_sel:WORD_1
	v_cvt_f32_f16_e32 v236, v130
	v_cvt_f32_f16_sdwa v237, v130 dst_sel:DWORD dst_unused:UNUSED_PAD src0_sel:WORD_1
	v_cvt_f32_f16_e32 v248, v131
	v_cvt_f32_f16_sdwa v249, v131 dst_sel:DWORD dst_unused:UNUSED_PAD src0_sel:WORD_1
	v_cvt_f32_f16_e32 v230, v136
	v_cvt_f32_f16_sdwa v231, v136 dst_sel:DWORD dst_unused:UNUSED_PAD src0_sel:WORD_1
	v_cvt_f32_f16_e32 v232, v137
	v_cvt_f32_f16_sdwa v233, v137 dst_sel:DWORD dst_unused:UNUSED_PAD src0_sel:WORD_1
	v_cvt_f32_f16_e32 v250, v134
	v_cvt_f32_f16_sdwa v251, v134 dst_sel:DWORD dst_unused:UNUSED_PAD src0_sel:WORD_1
	v_cvt_f32_f16_e32 v252, v135
	v_cvt_f32_f16_sdwa v253, v135 dst_sel:DWORD dst_unused:UNUSED_PAD src0_sel:WORD_1
	global_load_dwordx4 v[162:165], v[222:223], off offset:16
	global_load_dwordx4 v[166:169], v[222:223], off
	global_load_dwordx4 v[154:157], v[224:225], off offset:16
	global_load_dwordx4 v[158:161], v[224:225], off
	global_load_dwordx4 v[146:149], v[222:223], off offset:528
	global_load_dwordx4 v[150:153], v[222:223], off offset:512
	global_load_dwordx4 v[130:133], v[224:225], off offset:528
	global_load_dwordx4 v[134:137], v[224:225], off offset:512
	v_ashrrev_i32_e32 v209, 31, v208
	s_waitcnt vmcnt(6)
	v_pk_fma_f32 v[248:249], v[128:129], v[168:169], v[248:249]
	v_pk_fma_f32 v[240:241], v[126:127], v[166:167], v[236:237]
	v_lshlrev_b64 v[238:239], 15, v[208:209]
	v_mul_f32_e32 v0, v241, v241
	v_mul_f32_e32 v209, v249, v249
	v_pk_fma_f32 v[210:211], v[124:125], v[164:165], v[234:235]
	v_pk_fma_f32 v[216:217], v[122:123], v[162:163], v[216:217]
	v_lshl_add_u64 v[214:215], s[10:11], 0, v[214:215]
	v_fmac_f32_e32 v0, v240, v240
	v_fmac_f32_e32 v209, v248, v248
	s_ashr_i32 s34, s31, 8
	v_cvt_pk_f16_f32 v237, v210, v211
	v_cvt_pk_f16_f32 v235, v248, v249
	v_cvt_pk_f16_f32 v236, v216, v217
	v_cvt_pk_f16_f32 v234, v240, v241
	v_lshl_add_u64 v[212:213], v[214:215], 0, v[212:213]
	v_add_f32_e32 v0, v0, v209
	v_mul_f32_e32 v209, v217, v217
	v_mul_f32_e32 v214, v211, v211
	s_ashr_i32 s35, s34, 31
	global_store_dwordx4 v[212:213], v[234:237], off
	v_fmac_f32_e32 v209, v216, v216
	v_fmac_f32_e32 v214, v210, v210
	s_waitcnt vmcnt(5)
; __device__ __forceinline__ float bperm(float v, int src_lane) { return __int_as_float(__builtin_amdgcn_ds_bpermute(src_lane << 2, __float_as_int(v))); }
; __device__ __forceinline__ u32x4 pack8(const f32x4 a, const f32x4 b) { u32x4 w; w.x = cvt_pk_bf16(a.x, a.y); w.y = cvt_pk_bf16(a.z, a.w); w.z = cvt_pk_bf16(b.x, b.y); w.w = cvt_pk_bf16(b.z, b.w); return w; }
; __host__ __device__ __forceinline__ size_t xs_off(int row, int col) { return (size_t)(row >> 8) * (256 * D) + (size_t)(col >> 6) * (256 * 64) + (size_t)((row & 255) * 64 + (col & 63)); }
;     template <bool INF32, int M0, int M1> __device__ __forceinline__ void half(f32x4 (&acc)[2][2][4][2], int ai, int b, int row0, int col, int pn, int wc, int fr, int fq) const {
;     ...
;         for (int m = M0; m < M1; ++m) { const int row = row0 + ai * 128 + m * 16; float ss = 0.f;
; #pragma unroll
;             for (int bj = 0; bj < 2; ++bj) { const size_t o = (size_t)row * D + col + bj * 128;
;                 const f32x4 x0 = xv[m][bj][0] + gt[bj][0] * acc[ai][bj][m][0], x1 = xv[m][bj][1] + gt[bj][1] * acc[ai][bj][m][1];
;                 if (out_f32) { *(f32x4*)((float*)xout + o) = x0; *(f32x4*)((float*)xout + o + 4) = x1; }
;                 else { const f32x8_t ff = {x0.x, x0.y, x0.z, x0.w, x1.x, x1.y, x1.z, x1.w}; *(f16x8_t*)((bf16_t*)xout + o) = __builtin_convertvector(ff, f16x8_t); }
;                 ss += ((x0.x * x0.x + x0.y * x0.y) + (x0.z * x0.z + x0.w * x0.w)) + ((x1.x * x1.x + x1.y * x1.y) + (x1.z * x1.z + x1.w * x1.w));
;                 if (XS) *(u32x4*)(XS + xs_off(row0, col) + (ai * 128 + m * 16) * 64 + bj * (2 * 256 * 64)) = pack8(x0 * gs[bj][0], x1 * gs[bj][1]); }
;             { const int ln = fr + 16 * fq; ss += bperm(ss, ln ^ 16); ss += bperm(ss, ln ^ 32); }
;             if (fq == 0) RSS[(size_t)row * 32 + pn * 4 + wc] = ss; }
	v_pk_mul_f32 v[234:235], v[158:159], v[240:241]
	v_pk_mul_f32 v[210:211], v[156:157], v[210:211]
	s_lshl_b64 s[46:47], s[34:35], 20
	v_add_f32_e32 v209, v209, v214
	v_pk_mul_f32 v[214:215], v[160:161], v[248:249]
	v_pk_mul_f32 v[216:217], v[154:155], v[216:217]
	v_cvt_pk_bf16_f32 v234, v234, v235
	v_cvt_pk_bf16_f32 v235, v214, v215
	v_add_f32_e32 v209, v0, v209
	v_cvt_pk_bf16_f32 v236, v216, v217
	v_cvt_pk_bf16_f32 v237, v210, v211
	v_lshl_add_u64 v[210:211], s[74:75], 0, v[238:239]
	v_lshl_add_u64 v[210:211], v[210:211], 0, s[46:47]
	v_lshlrev_b32_e32 v0, 1, v246
	v_lshl_add_u64 v[216:217], v[210:211], 0, v[0:1]
	global_store_dwordx4 v[216:217], v[234:237], off
	s_waitcnt vmcnt(4)
	v_pk_fma_f32 v[210:211], v[120:121], v[152:153], v[252:253]
	v_pk_fma_f32 v[214:215], v[118:119], v[150:151], v[250:251]
	v_pk_fma_f32 v[234:235], v[116:117], v[148:149], v[232:233]
	v_pk_fma_f32 v[236:237], v[114:115], v[146:147], v[230:231]
	v_cvt_pk_f16_f32 v233, v234, v235
	v_cvt_pk_f16_f32 v231, v210, v211
	v_cvt_pk_f16_f32 v232, v236, v237
	v_cvt_pk_f16_f32 v230, v214, v215
	global_store_dwordx4 v[212:213], v[230:233], off offset:1024
	v_mul_f32_e32 v0, v215, v215
	v_mul_f32_e32 v212, v211, v211
	v_fmac_f32_e32 v0, v214, v214
	v_fmac_f32_e32 v212, v210, v210
	v_add_f32_e32 v0, v0, v212
	v_mul_f32_e32 v212, v237, v237
	v_mul_f32_e32 v213, v235, v235
	v_fmac_f32_e32 v212, v236, v236
	v_fmac_f32_e32 v213, v234, v234
	v_add_f32_e32 v212, v212, v213
	v_add_f32_e32 v0, v0, v212
	v_add_f32_e32 v0, v209, v0
	ds_bpermute_b32 v209, v245, v0
	s_waitcnt vmcnt(3)
	v_pk_mul_f32 v[210:211], v[136:137], v[210:211]
	s_lshl_b32 s34, s30, 2
	v_pk_mul_f32 v[212:213], v[134:135], v[214:215]
	s_ashr_i32 s35, s34, 31
	s_waitcnt lgkmcnt(0)
	v_add_f32_e32 v0, v0, v209
	ds_bpermute_b32 v209, v244, v0
	v_cvt_pk_bf16_f32 v230, v212, v213
	v_cvt_pk_bf16_f32 v231, v210, v211
	v_add_co_u32_e32 v210, vcc, 0x10000, v216
	v_pk_mul_f32 v[232:233], v[130:131], v[236:237]
	s_nop 0
	v_addc_co_u32_e32 v211, vcc, 0, v217, vcc
	v_pk_mul_f32 v[214:215], v[132:133], v[234:235]
	v_cvt_pk_bf16_f32 v232, v232, v233
	s_nop 0
	v_cvt_pk_bf16_f32 v233, v214, v215
	global_store_dwordx4 v[210:211], v[230:233], off
	s_and_saveexec_b64 s[46:47], s[28:29]
	s_cbranch_execz .LBB0_1134
	v_lshlrev_b64 v[210:211], 7, v[200:201]
	v_bfe_u32 v211, v210, 7, 4
	v_lshl_add_u32 v210, v211, 2, v210
	v_lshlrev_b32_e32 v211, 7, v211
	v_sub_u32_e32 v210, v210, v211
	v_mov_b32_e32 v211, 0
	v_lshl_add_u64 v[210:211], s[42:43], 0, v[210:211]
	v_lshl_add_u64 v[210:211], s[34:35], 2, v[210:211]
	s_mul_i32 s44, s34, 15
	s_lshl4_add_u32 s44, s71, s44
	s_lshl_b32 s44, s44, 2
	v_lshl_add_u64 v[210:211], v[210:211], 0, s[44:45]
	s_waitcnt lgkmcnt(0)
	v_add_f32_e32 v0, v0, v209
	global_store_dword v[210:211], v0, off
.LBB0_1134:
	s_or_b64 exec, exec, s[46:47]
	v_cvt_f32_f16_sdwa v211, v184 dst_sel:DWORD dst_unused:UNUSED_PAD src0_sel:WORD_1
	v_cvt_f32_f16_sdwa v213, v185 dst_sel:DWORD dst_unused:UNUSED_PAD src0_sel:WORD_1
	v_cvt_f32_f16_sdwa v215, v182 dst_sel:DWORD dst_unused:UNUSED_PAD src0_sel:WORD_1
	v_cvt_f32_f16_sdwa v231, v183 dst_sel:DWORD dst_unused:UNUSED_PAD src0_sel:WORD_1
	v_cvt_f32_f16_e32 v210, v184
	v_cvt_f32_f16_e32 v212, v185
	v_cvt_f32_f16_e32 v214, v182
	v_cvt_f32_f16_e32 v230, v183
	v_pk_fma_f32 v[210:211], v[106:107], v[162:163], v[210:211]
	v_pk_fma_f32 v[212:213], v[108:109], v[164:165], v[212:213]
	v_pk_fma_f32 v[214:215], v[110:111], v[166:167], v[214:215]
	v_pk_fma_f32 v[230:231], v[112:113], v[168:169], v[230:231]
	v_lshl_add_u64 v[228:229], s[10:11], 0, v[228:229]
	v_cvt_f32_f16_sdwa v183, v180 dst_sel:DWORD dst_unused:UNUSED_PAD src0_sel:WORD_1
	v_cvt_f32_f16_sdwa v185, v181 dst_sel:DWORD dst_unused:UNUSED_PAD src0_sel:WORD_1
	v_cvt_f32_f16_sdwa v233, v178 dst_sel:DWORD dst_unused:UNUSED_PAD src0_sel:WORD_1
	v_cvt_f32_f16_sdwa v235, v179 dst_sel:DWORD dst_unused:UNUSED_PAD src0_sel:WORD_1
	v_cvt_f32_f16_e32 v182, v180
	v_cvt_f32_f16_e32 v184, v181
	v_cvt_f32_f16_e32 v232, v178
	v_cvt_f32_f16_e32 v234, v179
	v_cvt_pk_f16_f32 v181, v212, v213
	v_cvt_pk_f16_f32 v179, v230, v231
	v_cvt_pk_f16_f32 v180, v210, v211
	v_cvt_pk_f16_f32 v178, v214, v215
	v_lshl_add_u64 v[228:229], v[198:199], 1, v[228:229]
	v_lshl_add_u64 v[228:229], v[228:229], 0, s[100:101]
	global_store_dwordx4 v[228:229], v[178:181], off
	v_mul_f32_e32 v0, v215, v215
	v_fmac_f32_e32 v0, v214, v214
	v_mul_f32_e32 v178, v231, v231
	v_fmac_f32_e32 v178, v230, v230
	v_add_f32_e32 v0, v0, v178
	v_mul_f32_e32 v178, v211, v211
	v_mul_f32_e32 v179, v213, v213
	v_fmac_f32_e32 v178, v210, v210
	v_fmac_f32_e32 v179, v212, v212
	v_add_f32_e32 v178, v178, v179
	v_add_f32_e32 v0, v0, v178
	v_pk_mul_f32 v[180:181], v[160:161], v[230:231]
	v_pk_mul_f32 v[178:179], v[158:159], v[214:215]
	v_pk_mul_f32 v[212:213], v[156:157], v[212:213]
	v_pk_mul_f32 v[210:211], v[154:155], v[210:211]
	v_cvt_pk_bf16_f32 v178, v178, v179
	v_cvt_pk_bf16_f32 v179, v180, v181
	v_pk_fma_f32 v[184:185], v[100:101], v[148:149], v[184:185]
	v_cvt_pk_bf16_f32 v180, v210, v211
	v_cvt_pk_bf16_f32 v181, v212, v213
	v_pk_fma_f32 v[210:211], v[104:105], v[152:153], v[234:235]
	v_pk_fma_f32 v[212:213], v[102:103], v[150:151], v[232:233]
	v_pk_fma_f32 v[182:183], v[98:99], v[146:147], v[182:183]
	global_store_dwordx4 v[216:217], v[178:181], off offset:2048
	s_nop 1
	v_cvt_pk_f16_f32 v181, v184, v185
	v_cvt_pk_f16_f32 v179, v210, v211
	v_cvt_pk_f16_f32 v180, v182, v183
	v_cvt_pk_f16_f32 v178, v212, v213
	global_store_dwordx4 v[228:229], v[178:181], off offset:1024
	s_nop 1
	v_mul_f32_e32 v178, v213, v213
	v_mul_f32_e32 v179, v211, v211
	v_fmac_f32_e32 v178, v212, v212
	v_fmac_f32_e32 v179, v210, v210
	v_add_f32_e32 v178, v178, v179
	v_mul_f32_e32 v179, v183, v183
	v_mul_f32_e32 v180, v185, v185
	v_fmac_f32_e32 v179, v182, v182
	v_fmac_f32_e32 v180, v184, v184
	v_add_f32_e32 v179, v179, v180
	v_add_f32_e32 v178, v178, v179
	v_add_f32_e32 v0, v0, v178
	v_pk_mul_f32 v[178:179], v[136:137], v[210:211]
	v_pk_mul_f32 v[180:181], v[134:135], v[212:213]
	v_pk_mul_f32 v[184:185], v[132:133], v[184:185]
	v_cvt_pk_bf16_f32 v180, v180, v181
	v_cvt_pk_bf16_f32 v181, v178, v179
	ds_bpermute_b32 v178, v245, v0
	v_pk_mul_f32 v[182:183], v[130:131], v[182:183]
	s_waitcnt lgkmcnt(0)
	v_add_f32_e32 v0, v0, v178
	ds_bpermute_b32 v178, v244, v0
	v_cvt_pk_bf16_f32 v182, v182, v183
	v_cvt_pk_bf16_f32 v183, v184, v185
	v_add_co_u32_e32 v184, vcc, 0x10000, v216
	s_nop 1
	v_addc_co_u32_e32 v185, vcc, 0, v217, vcc
	global_store_dwordx4 v[184:185], v[180:183], off offset:2048
	s_and_saveexec_b64 s[46:47], s[28:29]
	s_cbranch_execz .LBB0_1136
; __device__ __forceinline__ float bperm(float v, int src_lane) { return __int_as_float(__builtin_amdgcn_ds_bpermute(src_lane << 2, __float_as_int(v))); }
; __device__ __forceinline__ u32x4 pack8(const f32x4 a, const f32x4 b) { u32x4 w; w.x = cvt_pk_bf16(a.x, a.y); w.y = cvt_pk_bf16(a.z, a.w); w.z = cvt_pk_bf16(b.x, b.y); w.w = cvt_pk_bf16(b.z, b.w); return w; }
; __host__ __device__ __forceinline__ size_t xs_off(int row, int col) { return (size_t)(row >> 8) * (256 * D) + (size_t)(col >> 6) * (256 * 64) + (size_t)((row & 255) * 64 + (col & 63)); }
;     template <bool INF32, int M0, int M1> __device__ __forceinline__ void half(f32x4 (&acc)[2][2][4][2], int ai, int b, int row0, int col, int pn, int wc, int fr, int fq) const {
;     ...
;         for (int m = M0; m < M1; ++m) { const int row = row0 + ai * 128 + m * 16; float ss = 0.f;
; #pragma unroll
;             for (int bj = 0; bj < 2; ++bj) { const size_t o = (size_t)row * D + col + bj * 128;
;                 const f32x4 x0 = xv[m][bj][0] + gt[bj][0] * acc[ai][bj][m][0], x1 = xv[m][bj][1] + gt[bj][1] * acc[ai][bj][m][1];
;                 if (out_f32) { *(f32x4*)((float*)xout + o) = x0; *(f32x4*)((float*)xout + o + 4) = x1; }
;                 else { const f32x8_t ff = {x0.x, x0.y, x0.z, x0.w, x1.x, x1.y, x1.z, x1.w}; *(f16x8_t*)((bf16_t*)xout + o) = __builtin_convertvector(ff, f16x8_t); }
;                 ss += ((x0.x * x0.x + x0.y * x0.y) + (x0.z * x0.z + x0.w * x0.w)) + ((x1.x * x1.x + x1.y * x1.y) + (x1.z * x1.z + x1.w * x1.w));
;                 if (XS) *(u32x4*)(XS + xs_off(row0, col) + (ai * 128 + m * 16) * 64 + bj * (2 * 256 * 64)) = pack8(x0 * gs[bj][0], x1 * gs[bj][1]); }
;             { const int ln = fr + 16 * fq; ss += bperm(ss, ln ^ 16); ss += bperm(ss, ln ^ 32); }
;             if (fq == 0) RSS[(size_t)row * 32 + pn * 4 + wc] = ss; }
	v_lshlrev_b64 v[180:181], 7, v[206:207]
	v_bfe_u32 v181, v180, 7, 4
	v_lshl_add_u32 v180, v181, 2, v180
	v_lshlrev_b32_e32 v181, 7, v181
	v_sub_u32_e32 v180, v180, v181
	v_mov_b32_e32 v181, 0
	v_lshl_add_u64 v[180:181], s[42:43], 0, v[180:181]
	v_lshl_add_u64 v[180:181], s[34:35], 2, v[180:181]
	s_mul_i32 s44, s34, 15
	s_lshl4_add_u32 s44, s71, s44
	s_lshl_b32 s44, s44, 2
	v_lshl_add_u64 v[180:181], v[180:181], 0, s[44:45]
	s_waitcnt lgkmcnt(0)
	v_add_f32_e32 v0, v0, v178
	global_store_dword v[180:181], v0, off
.LBB0_1136:
	s_or_b64 exec, exec, s[46:47]
	v_cvt_f32_f16_sdwa v179, v176 dst_sel:DWORD dst_unused:UNUSED_PAD src0_sel:WORD_1
	v_cvt_f32_f16_sdwa v181, v177 dst_sel:DWORD dst_unused:UNUSED_PAD src0_sel:WORD_1
	v_cvt_f32_f16_sdwa v183, v174 dst_sel:DWORD dst_unused:UNUSED_PAD src0_sel:WORD_1
	v_cvt_f32_f16_sdwa v185, v175 dst_sel:DWORD dst_unused:UNUSED_PAD src0_sel:WORD_1
	s_waitcnt lgkmcnt(0)
	v_cvt_f32_f16_e32 v178, v176
	v_cvt_f32_f16_e32 v180, v177
	v_cvt_f32_f16_e32 v182, v174
	v_cvt_f32_f16_e32 v184, v175
	v_pk_fma_f32 v[178:179], v[90:91], v[162:163], v[178:179]
	v_pk_fma_f32 v[180:181], v[92:93], v[164:165], v[180:181]
	v_pk_fma_f32 v[182:183], v[94:95], v[166:167], v[182:183]
	v_pk_fma_f32 v[174:175], v[96:97], v[168:169], v[184:185]
	v_lshl_add_u64 v[184:185], s[10:11], 0, v[226:227]
	v_cvt_f32_f16_sdwa v177, v172 dst_sel:DWORD dst_unused:UNUSED_PAD src0_sel:WORD_1
	v_cvt_f32_f16_sdwa v211, v173 dst_sel:DWORD dst_unused:UNUSED_PAD src0_sel:WORD_1
	v_cvt_f32_f16_sdwa v213, v170 dst_sel:DWORD dst_unused:UNUSED_PAD src0_sel:WORD_1
	v_cvt_f32_f16_sdwa v215, v171 dst_sel:DWORD dst_unused:UNUSED_PAD src0_sel:WORD_1
	v_cvt_f32_f16_e32 v176, v172
	v_cvt_f32_f16_e32 v210, v173
	v_cvt_f32_f16_e32 v212, v170
	v_cvt_f32_f16_e32 v214, v171
	v_cvt_pk_f16_f32 v173, v180, v181
	v_cvt_pk_f16_f32 v171, v174, v175
	v_cvt_pk_f16_f32 v172, v178, v179
	v_cvt_pk_f16_f32 v170, v182, v183
	v_lshl_add_u64 v[184:185], v[198:199], 1, v[184:185]
	v_lshl_add_u64 v[184:185], v[184:185], 0, s[100:101]
	global_store_dwordx4 v[184:185], v[170:173], off
	v_mul_f32_e32 v0, v183, v183
	v_fmac_f32_e32 v0, v182, v182
	v_mul_f32_e32 v170, v175, v175
	v_fmac_f32_e32 v170, v174, v174
	v_add_f32_e32 v0, v0, v170
	v_mul_f32_e32 v170, v179, v179
	v_mul_f32_e32 v171, v181, v181
	v_fmac_f32_e32 v170, v178, v178
	v_fmac_f32_e32 v171, v180, v180
	v_add_f32_e32 v170, v170, v171
	v_add_f32_e32 v0, v0, v170
	v_pk_mul_f32 v[170:171], v[160:161], v[174:175]
	v_pk_mul_f32 v[172:173], v[158:159], v[182:183]
	s_movk_i32 s12, 0x1000
	v_pk_mul_f32 v[180:181], v[156:157], v[180:181]
	v_pk_mul_f32 v[174:175], v[154:155], v[178:179]
	v_cvt_pk_bf16_f32 v172, v172, v173
	v_cvt_pk_bf16_f32 v173, v170, v171
	v_add_co_u32_e32 v170, vcc, s12, v216
	v_cvt_pk_bf16_f32 v174, v174, v175
	v_cvt_pk_bf16_f32 v175, v180, v181
	v_pk_fma_f32 v[178:179], v[88:89], v[152:153], v[214:215]
	s_nop 0
	v_addc_co_u32_e32 v171, vcc, 0, v217, vcc
	v_pk_fma_f32 v[180:181], v[86:87], v[150:151], v[212:213]
	v_pk_fma_f32 v[182:183], v[84:85], v[148:149], v[210:211]
	v_pk_fma_f32 v[176:177], v[82:83], v[146:147], v[176:177]
	global_store_dwordx4 v[170:171], v[172:175], off
	s_nop 1
	v_cvt_pk_f16_f32 v175, v182, v183
	v_cvt_pk_f16_f32 v173, v178, v179
	v_cvt_pk_f16_f32 v174, v176, v177
	v_cvt_pk_f16_f32 v172, v180, v181
	global_store_dwordx4 v[184:185], v[172:175], off offset:1024
	s_nop 1
	v_mul_f32_e32 v172, v181, v181
	v_mul_f32_e32 v173, v179, v179
	v_fmac_f32_e32 v172, v180, v180
	v_fmac_f32_e32 v173, v178, v178
	v_add_f32_e32 v172, v172, v173
	v_mul_f32_e32 v173, v177, v177
	v_mul_f32_e32 v174, v183, v183
	v_fmac_f32_e32 v173, v176, v176
	v_fmac_f32_e32 v174, v182, v182
	v_add_f32_e32 v173, v173, v174
	v_add_f32_e32 v172, v172, v173
	v_add_f32_e32 v0, v0, v172
	v_pk_mul_f32 v[172:173], v[136:137], v[178:179]
	v_pk_mul_f32 v[174:175], v[134:135], v[180:181]
	v_pk_mul_f32 v[178:179], v[132:133], v[182:183]
	v_cvt_pk_bf16_f32 v174, v174, v175
	v_cvt_pk_bf16_f32 v175, v172, v173
	ds_bpermute_b32 v172, v245, v0
	v_pk_mul_f32 v[176:177], v[130:131], v[176:177]
	s_waitcnt lgkmcnt(0)
	v_add_f32_e32 v0, v0, v172
	ds_bpermute_b32 v172, v244, v0
	v_cvt_pk_bf16_f32 v176, v176, v177
	v_cvt_pk_bf16_f32 v177, v178, v179
	v_add_co_u32_e32 v178, vcc, 0x11000, v216
	s_nop 1
	v_addc_co_u32_e32 v179, vcc, 0, v217, vcc
	global_store_dwordx4 v[178:179], v[174:177], off
	s_and_saveexec_b64 s[46:47], s[28:29]
	s_cbranch_execz .LBB0_1138
	v_lshlrev_b64 v[174:175], 7, v[204:205]
	v_bfe_u32 v175, v174, 7, 4
	v_lshl_add_u32 v174, v175, 2, v174
	v_lshlrev_b32_e32 v175, 7, v175
	v_sub_u32_e32 v174, v174, v175
	v_mov_b32_e32 v175, 0
	v_lshl_add_u64 v[174:175], s[42:43], 0, v[174:175]
	v_lshl_add_u64 v[174:175], s[34:35], 2, v[174:175]
	s_mul_i32 s44, s34, 15
	s_lshl4_add_u32 s44, s71, s44
	s_lshl_b32 s44, s44, 2
	v_lshl_add_u64 v[174:175], v[174:175], 0, s[44:45]
	s_waitcnt lgkmcnt(0)
	v_add_f32_e32 v0, v0, v172
	global_store_dword v[174:175], v0, off
; __device__ __forceinline__ float bperm(float v, int src_lane) { return __int_as_float(__builtin_amdgcn_ds_bpermute(src_lane << 2, __float_as_int(v))); }
; __device__ __forceinline__ u32x4 pack8(const f32x4 a, const f32x4 b) { u32x4 w; w.x = cvt_pk_bf16(a.x, a.y); w.y = cvt_pk_bf16(a.z, a.w); w.z = cvt_pk_bf16(b.x, b.y); w.w = cvt_pk_bf16(b.z, b.w); return w; }
; __host__ __device__ __forceinline__ size_t xs_off(int row, int col) { return (size_t)(row >> 8) * (256 * D) + (size_t)(col >> 6) * (256 * 64) + (size_t)((row & 255) * 64 + (col & 63)); }
;     template <bool INF32, int M0, int M1> __device__ __forceinline__ void half(f32x4 (&acc)[2][2][4][2], int ai, int b, int row0, int col, int pn, int wc, int fr, int fq) const {
;     ...
;         for (int m = M0; m < M1; ++m) { const int row = row0 + ai * 128 + m * 16; float ss = 0.f;
; #pragma unroll
;             for (int bj = 0; bj < 2; ++bj) { const size_t o = (size_t)row * D + col + bj * 128;
;                 const f32x4 x0 = xv[m][bj][0] + gt[bj][0] * acc[ai][bj][m][0], x1 = xv[m][bj][1] + gt[bj][1] * acc[ai][bj][m][1];
;                 if (out_f32) { *(f32x4*)((float*)xout + o) = x0; *(f32x4*)((float*)xout + o + 4) = x1; }
;                 else { const f32x8_t ff = {x0.x, x0.y, x0.z, x0.w, x1.x, x1.y, x1.z, x1.w}; *(f16x8_t*)((bf16_t*)xout + o) = __builtin_convertvector(ff, f16x8_t); }
;                 ss += ((x0.x * x0.x + x0.y * x0.y) + (x0.z * x0.z + x0.w * x0.w)) + ((x1.x * x1.x + x1.y * x1.y) + (x1.z * x1.z + x1.w * x1.w));
;                 if (XS) *(u32x4*)(XS + xs_off(row0, col) + (ai * 128 + m * 16) * 64 + bj * (2 * 256 * 64)) = pack8(x0 * gs[bj][0], x1 * gs[bj][1]); }
;             { const int ln = fr + 16 * fq; ss += bperm(ss, ln ^ 16); ss += bperm(ss, ln ^ 32); }
;             if (fq == 0) RSS[(size_t)row * 32 + pn * 4 + wc] = ss; }
.LBB0_1138:
	s_or_b64 exec, exec, s[46:47]
	v_cvt_f32_f16_sdwa v173, v144 dst_sel:DWORD dst_unused:UNUSED_PAD src0_sel:WORD_1
	v_cvt_f32_f16_sdwa v175, v145 dst_sel:DWORD dst_unused:UNUSED_PAD src0_sel:WORD_1
	v_cvt_f32_f16_sdwa v177, v142 dst_sel:DWORD dst_unused:UNUSED_PAD src0_sel:WORD_1
	v_cvt_f32_f16_sdwa v179, v143 dst_sel:DWORD dst_unused:UNUSED_PAD src0_sel:WORD_1
	s_waitcnt lgkmcnt(0)
	v_cvt_f32_f16_e32 v172, v144
	v_cvt_f32_f16_e32 v174, v145
	v_cvt_f32_f16_e32 v176, v142
	v_cvt_f32_f16_e32 v178, v143
	v_pk_fma_f32 v[162:163], v[74:75], v[162:163], v[172:173]
	v_pk_fma_f32 v[164:165], v[76:77], v[164:165], v[174:175]
	v_pk_fma_f32 v[166:167], v[78:79], v[166:167], v[176:177]
	v_pk_fma_f32 v[168:169], v[80:81], v[168:169], v[178:179]
	v_lshl_add_u64 v[172:173], s[10:11], 0, v[218:219]
	v_cvt_f32_f16_sdwa v143, v140 dst_sel:DWORD dst_unused:UNUSED_PAD src0_sel:WORD_1
	v_cvt_f32_f16_sdwa v145, v141 dst_sel:DWORD dst_unused:UNUSED_PAD src0_sel:WORD_1
	v_cvt_f32_f16_sdwa v181, v138 dst_sel:DWORD dst_unused:UNUSED_PAD src0_sel:WORD_1
	v_cvt_f32_f16_sdwa v183, v139 dst_sel:DWORD dst_unused:UNUSED_PAD src0_sel:WORD_1
	v_cvt_f32_f16_e32 v142, v140
	v_cvt_f32_f16_e32 v144, v141
	v_cvt_f32_f16_e32 v180, v138
	v_cvt_f32_f16_e32 v182, v139
	v_cvt_pk_f16_f32 v141, v164, v165
	v_cvt_pk_f16_f32 v139, v168, v169
	v_cvt_pk_f16_f32 v140, v162, v163
	v_cvt_pk_f16_f32 v138, v166, v167
	v_lshl_add_u64 v[172:173], v[198:199], 1, v[172:173]
	v_lshl_add_u64 v[172:173], v[172:173], 0, s[100:101]
	global_store_dwordx4 v[172:173], v[138:141], off
	v_mul_f32_e32 v0, v167, v167
	v_fmac_f32_e32 v0, v166, v166
	v_mul_f32_e32 v138, v169, v169
	v_fmac_f32_e32 v138, v168, v168
	v_add_f32_e32 v0, v0, v138
	v_mul_f32_e32 v138, v163, v163
	v_mul_f32_e32 v139, v165, v165
	v_fmac_f32_e32 v138, v162, v162
	v_fmac_f32_e32 v139, v164, v164
	v_add_f32_e32 v138, v138, v139
	v_add_f32_e32 v0, v0, v138
	v_pk_mul_f32 v[140:141], v[160:161], v[168:169]
	v_pk_mul_f32 v[138:139], v[158:159], v[166:167]
	v_pk_mul_f32 v[156:157], v[156:157], v[164:165]
	v_pk_mul_f32 v[154:155], v[154:155], v[162:163]
	v_cvt_pk_bf16_f32 v138, v138, v139
	v_cvt_pk_bf16_f32 v139, v140, v141
	v_pk_fma_f32 v[152:153], v[72:73], v[152:153], v[182:183]
	v_cvt_pk_bf16_f32 v140, v154, v155
	v_cvt_pk_bf16_f32 v141, v156, v157
	v_pk_fma_f32 v[150:151], v[70:71], v[150:151], v[180:181]
	v_pk_fma_f32 v[144:145], v[68:69], v[148:149], v[144:145]
	v_pk_fma_f32 v[142:143], v[66:67], v[146:147], v[142:143]
	global_store_dwordx4 v[170:171], v[138:141], off offset:2048
	v_pk_mul_f32 v[136:137], v[136:137], v[152:153]
	v_pk_mul_f32 v[134:135], v[134:135], v[150:151]
	v_cvt_pk_f16_f32 v141, v144, v145
	v_cvt_pk_f16_f32 v139, v152, v153
	v_cvt_pk_f16_f32 v140, v142, v143
	v_cvt_pk_f16_f32 v138, v150, v151
	global_store_dwordx4 v[172:173], v[138:141], off offset:1024
	v_pk_mul_f32 v[130:131], v[130:131], v[142:143]
	s_nop 0
	v_mul_f32_e32 v138, v151, v151
	v_mul_f32_e32 v139, v153, v153
	v_fmac_f32_e32 v138, v150, v150
	v_fmac_f32_e32 v139, v152, v152
	v_add_f32_e32 v138, v138, v139
	v_mul_f32_e32 v139, v143, v143
	v_mul_f32_e32 v140, v145, v145
	v_fmac_f32_e32 v139, v142, v142
	v_fmac_f32_e32 v140, v144, v144
	v_add_f32_e32 v139, v139, v140
	v_add_f32_e32 v138, v138, v139
	v_add_f32_e32 v0, v0, v138
	v_pk_mul_f32 v[138:139], v[132:133], v[144:145]
	v_cvt_pk_bf16_f32 v132, v134, v135
	v_cvt_pk_bf16_f32 v133, v136, v137
	ds_bpermute_b32 v137, v245, v0
	v_cvt_pk_bf16_f32 v134, v130, v131
	v_add_co_u32_e32 v136, vcc, 0x11000, v216
	v_cvt_pk_bf16_f32 v135, v138, v139
	s_waitcnt lgkmcnt(0)
	v_add_f32_e32 v0, v0, v137
	ds_bpermute_b32 v130, v244, v0
	v_addc_co_u32_e32 v137, vcc, 0, v217, vcc
	global_store_dwordx4 v[136:137], v[132:135], off offset:2048
	s_and_saveexec_b64 s[46:47], s[28:29]
	s_cbranch_execz .LBB0_1140
	v_lshlrev_b64 v[132:133], 7, v[202:203]
	v_bfe_u32 v133, v132, 7, 4
	v_lshl_add_u32 v132, v133, 2, v132
	v_lshlrev_b32_e32 v133, 7, v133
	v_sub_u32_e32 v132, v132, v133
	v_mov_b32_e32 v133, 0
	v_lshl_add_u64 v[132:133], s[42:43], 0, v[132:133]
	v_lshl_add_u64 v[132:133], s[34:35], 2, v[132:133]
	s_mul_i32 s44, s34, 15
	s_lshl4_add_u32 s44, s71, s44
	s_lshl_b32 s44, s44, 2
	v_lshl_add_u64 v[132:133], v[132:133], 0, s[44:45]
	s_waitcnt lgkmcnt(0)
	v_add_f32_e32 v0, v0, v130
	global_store_dword v[132:133], v0, off
; __device__ __forceinline__ float bperm(float v, int src_lane) { return __int_as_float(__builtin_amdgcn_ds_bpermute(src_lane << 2, __float_as_int(v))); }
;     template <bool INF32, int M0, int M1> __device__ __forceinline__ void half(f32x4 (&acc)[2][2][4][2], int ai, int b, int row0, int col, int pn, int wc, int fr, int fq) const {
;     ...
;             for (int m = M0; m < M1; ++m)
; #pragma unroll
;                 for (int bj = 0; bj < 2; ++bj) hh[m][bj] = *(const f16x8_t*)((const bf16_t*)xin + (size_t)(row0 + ai * 128 + m * 16) * D + col + bj * 128);
; #pragma unroll
;             for (int m = M0; m < M1; ++m)
; #pragma unroll
;                 for (int bj = 0; bj < 2; ++bj) { const f32x8_t ff = __builtin_convertvector(hh[m][bj], f32x8_t); xv[m][bj][0] = (f32x4){ff[0], ff[1], ff[2], ff[3]}; xv[m][bj][1] = (f32x4){ff[4], ff[5], ff[6], ff[7]}; }
;         }
;         f32x4 gt[2][2], gs[2][2];
; #pragma unroll
;         for (int bj = 0; bj < 2; ++bj)
; #pragma unroll
;             for (int n = 0; n < 2; ++n) { gt[bj][n] = *(const f32x4*)(gate + (size_t)b * 6 * D + col + bj * 128 + n * 4); gs[bj][n] = XS ? *(const f32x4*)(GS + (size_t)b * D + col + bj * 128 + n * 4) : (f32x4){0.f, 0.f, 0.f, 0.f}; }
;         __builtin_amdgcn_sched_barrier(0);
; #pragma unroll
;         for (int m = M0; m < M1; ++m) { const int row = row0 + ai * 128 + m * 16; float ss = 0.f;
; #pragma unroll
;             for (int bj = 0; bj < 2; ++bj) { const size_t o = (size_t)row * D + col + bj * 128;
;                 const f32x4 x0 = xv[m][bj][0] + gt[bj][0] * acc[ai][bj][m][0], x1 = xv[m][bj][1] + gt[bj][1] * acc[ai][bj][m][1];
;                 if (out_f32) { *(f32x4*)((float*)xout + o) = x0; *(f32x4*)((float*)xout + o + 4) = x1; }
;                 else { const f32x8_t ff = {x0.x, x0.y, x0.z, x0.w, x1.x, x1.y, x1.z, x1.w}; *(f16x8_t*)((bf16_t*)xout + o) = __builtin_convertvector(ff, f16x8_t); }
;                 ss += ((x0.x * x0.x + x0.y * x0.y) + (x0.z * x0.z + x0.w * x0.w)) + ((x1.x * x1.x + x1.y * x1.y) + (x1.z * x1.z + x1.w * x1.w));
;                 if (XS) *(u32x4*)(XS + xs_off(row0, col) + (ai * 128 + m * 16) * 64 + bj * (2 * 256 * 64)) = pack8(x0 * gs[bj][0], x1 * gs[bj][1]); }
;             { const int ln = fr + 16 * fq; ss += bperm(ss, ln ^ 16); ss += bperm(ss, ln ^ 32); }
;             if (fq == 0) RSS[(size_t)row * 32 + pn * 4 + wc] = ss; }
.LBB0_1140:
	s_or_b64 exec, exec, s[46:47]
	v_add_u32_e32 v236, 0x80, v200
	v_ashrrev_i32_e32 v237, 31, v236
	v_add_u32_e32 v232, 0x90, v200
	v_lshlrev_b64 v[210:211], 12, v[236:237]
	v_bfe_u32 v211, v210, 12, 4
	v_lshl_add_u32 v210, v211, 6, v210
	v_lshlrev_b32_e32 v211, 12, v211
	v_sub_u32_e32 v210, v210, v211
	v_mov_b32_e32 v211, 0
	v_ashrrev_i32_e32 v233, 31, v232
	v_add_u32_e32 v228, 0xa0, v200
	v_add_u32_e32 v218, 0xb0, v200
	s_waitcnt lgkmcnt(0)
	v_lshl_add_u64 v[130:131], v[220:221], 0, v[210:211]
	v_lshlrev_b64 v[234:235], 12, v[232:233]
	v_bfe_u32 v235, v234, 12, 4
	v_lshl_add_u32 v234, v235, 6, v234
	v_lshlrev_b32_e32 v235, 12, v235
	v_sub_u32_e32 v234, v234, v235
	v_mov_b32_e32 v235, 0
	v_ashrrev_i32_e32 v229, 31, v228
	v_ashrrev_i32_e32 v219, 31, v218
	global_load_dwordx4 v[248:251], v[130:131], off
	global_load_dwordx4 v[212:215], v[130:131], off offset:1024
	v_lshl_add_u64 v[130:131], v[220:221], 0, v[234:235]
	v_lshlrev_b64 v[230:231], 12, v[228:229]
	v_bfe_u32 v231, v230, 12, 4
	v_lshl_add_u32 v230, v231, 6, v230
	v_lshlrev_b32_e32 v231, 12, v231
	v_sub_u32_e32 v230, v230, v231
	v_mov_b32_e32 v231, 0
	v_lshlrev_b64 v[226:227], 12, v[218:219]
	v_bfe_u32 v227, v226, 12, 4
	v_lshl_add_u32 v226, v227, 6, v226
	v_lshlrev_b32_e32 v227, 12, v227
	v_sub_u32_e32 v226, v226, v227
	v_mov_b32_e32 v227, 0
	global_load_dwordx4 v[182:185], v[130:131], off
	global_load_dwordx4 v[178:181], v[130:131], off offset:1024
	v_lshl_add_u64 v[130:131], v[220:221], 0, v[230:231]
	v_lshl_add_u64 v[162:163], v[220:221], 0, v[226:227]
	global_load_dwordx4 v[174:177], v[130:131], off
	global_load_dwordx4 v[170:173], v[130:131], off offset:1024
	global_load_dwordx4 v[154:157], v[222:223], off offset:16
	global_load_dwordx4 v[158:161], v[222:223], off
	global_load_dwordx4 v[146:149], v[224:225], off offset:16
	global_load_dwordx4 v[150:153], v[224:225], off
	global_load_dwordx4 v[138:141], v[222:223], off offset:528
	global_load_dwordx4 v[142:145], v[222:223], off offset:512
	global_load_dwordx4 v[130:133], v[224:225], off offset:528
	global_load_dwordx4 v[134:137], v[224:225], off offset:512
	global_load_dwordx4 v[166:169], v[162:163], off
	s_nop 0
	global_load_dwordx4 v[162:165], v[162:163], off offset:1024
	s_waitcnt vmcnt(15)
	v_cvt_f32_f16_e32 v220, v251
	v_cvt_f32_f16_sdwa v221, v251 dst_sel:DWORD dst_unused:UNUSED_PAD src0_sel:WORD_1
	v_cvt_f32_f16_e32 v222, v250
	v_cvt_f32_f16_sdwa v223, v250 dst_sel:DWORD dst_unused:UNUSED_PAD src0_sel:WORD_1
	v_cvt_f32_f16_e32 v224, v249
	v_cvt_f32_f16_sdwa v225, v249 dst_sel:DWORD dst_unused:UNUSED_PAD src0_sel:WORD_1
	v_cvt_f32_f16_e32 v238, v248
	v_cvt_f32_f16_sdwa v239, v248 dst_sel:DWORD dst_unused:UNUSED_PAD src0_sel:WORD_1
	s_waitcnt vmcnt(14)
	v_cvt_f32_f16_e32 v240, v215
	v_cvt_f32_f16_sdwa v241, v215 dst_sel:DWORD dst_unused:UNUSED_PAD src0_sel:WORD_1
	v_cvt_f32_f16_e32 v248, v214
	v_cvt_f32_f16_sdwa v249, v214 dst_sel:DWORD dst_unused:UNUSED_PAD src0_sel:WORD_1
	v_cvt_f32_f16_e32 v250, v213
	v_cvt_f32_f16_sdwa v251, v213 dst_sel:DWORD dst_unused:UNUSED_PAD src0_sel:WORD_1
	v_cvt_f32_f16_e32 v252, v212
	v_cvt_f32_f16_sdwa v253, v212 dst_sel:DWORD dst_unused:UNUSED_PAD src0_sel:WORD_1
	s_waitcnt vmcnt(8)
	v_pk_fma_f32 v[238:239], v[62:63], v[158:159], v[238:239]
	v_pk_fma_f32 v[224:225], v[64:65], v[160:161], v[224:225]
	v_pk_fma_f32 v[222:223], v[58:59], v[154:155], v[222:223]
	v_pk_fma_f32 v[220:221], v[60:61], v[156:157], v[220:221]
	v_lshl_add_u64 v[210:211], s[10:11], 0, v[210:211]
	v_mul_f32_e32 v0, v239, v239
	v_mul_f32_e32 v209, v225, v225
	v_cvt_pk_f16_f32 v215, v220, v221
	v_cvt_pk_f16_f32 v214, v222, v223
	v_cvt_pk_f16_f32 v213, v224, v225
	v_cvt_pk_f16_f32 v212, v238, v239
	v_lshl_add_u64 v[210:211], v[198:199], 1, v[210:211]
	v_lshl_add_u64 v[210:211], v[210:211], 0, s[100:101]
	v_fmac_f32_e32 v0, v238, v238
	v_fmac_f32_e32 v209, v224, v224
	global_store_dwordx4 v[210:211], v[212:215], off
	v_add_f32_e32 v0, v0, v209
	v_mul_f32_e32 v209, v223, v223
	v_mul_f32_e32 v212, v221, v221
	v_fmac_f32_e32 v209, v222, v222
	v_fmac_f32_e32 v212, v220, v220
	v_add_f32_e32 v209, v209, v212
	s_waitcnt vmcnt(7)
	v_pk_mul_f32 v[214:215], v[152:153], v[224:225]
	v_pk_mul_f32 v[212:213], v[150:151], v[238:239]
	v_pk_mul_f32 v[220:221], v[148:149], v[220:221]
	v_pk_mul_f32 v[222:223], v[146:147], v[222:223]
	v_cvt_pk_bf16_f32 v212, v212, v213
	v_cvt_pk_bf16_f32 v213, v214, v215
	s_waitcnt vmcnt(5)
	v_pk_fma_f32 v[224:225], v[56:57], v[144:145], v[250:251]
	v_cvt_pk_bf16_f32 v214, v222, v223
	v_cvt_pk_bf16_f32 v215, v220, v221
	v_add_co_u32_e32 v220, vcc, s60, v216
	v_pk_fma_f32 v[222:223], v[54:55], v[142:143], v[252:253]
	s_nop 0
	v_addc_co_u32_e32 v221, vcc, 0, v217, vcc
	v_pk_fma_f32 v[238:239], v[50:51], v[138:139], v[248:249]
	v_pk_fma_f32 v[240:241], v[52:53], v[140:141], v[240:241]
	global_store_dwordx4 v[220:221], v[212:215], off
	v_add_f32_e32 v0, v0, v209
	v_mul_f32_e32 v209, v223, v223
	v_cvt_pk_f16_f32 v215, v240, v241
	v_cvt_pk_f16_f32 v214, v238, v239
	v_cvt_pk_f16_f32 v213, v224, v225
	v_cvt_pk_f16_f32 v212, v222, v223
	global_store_dwordx4 v[210:211], v[212:215], off offset:1024
	v_mul_f32_e32 v210, v225, v225
	v_fmac_f32_e32 v209, v222, v222
	v_fmac_f32_e32 v210, v224, v224
	v_add_f32_e32 v209, v209, v210
	v_mul_f32_e32 v210, v239, v239
	v_mul_f32_e32 v211, v241, v241
	v_fmac_f32_e32 v210, v238, v238
	v_fmac_f32_e32 v211, v240, v240
	v_add_f32_e32 v210, v210, v211
	v_add_f32_e32 v209, v209, v210
	v_add_f32_e32 v0, v0, v209
	ds_bpermute_b32 v209, v245, v0
	s_waitcnt vmcnt(5)
	v_pk_mul_f32 v[210:211], v[136:137], v[224:225]
	v_pk_mul_f32 v[212:213], v[134:135], v[222:223]
	v_pk_mul_f32 v[214:215], v[130:131], v[238:239]
	v_cvt_pk_bf16_f32 v212, v212, v213
	s_waitcnt lgkmcnt(0)
	v_add_f32_e32 v0, v0, v209
	ds_bpermute_b32 v209, v244, v0
	v_cvt_pk_bf16_f32 v213, v210, v211
	v_add_co_u32_e32 v210, vcc, 0x14000, v216
	v_pk_mul_f32 v[222:223], v[132:133], v[240:241]
	s_nop 0
	v_addc_co_u32_e32 v211, vcc, 0, v217, vcc
	v_cvt_pk_bf16_f32 v214, v214, v215
	v_cvt_pk_bf16_f32 v215, v222, v223
	global_store_dwordx4 v[210:211], v[212:215], off
	s_and_saveexec_b64 s[46:47], s[28:29]
	s_cbranch_execz .LBB0_1142
	v_lshlrev_b64 v[210:211], 7, v[236:237]
	v_bfe_u32 v211, v210, 7, 4
	v_lshl_add_u32 v210, v211, 2, v210
	v_lshlrev_b32_e32 v211, 7, v211
	v_sub_u32_e32 v210, v210, v211
	v_mov_b32_e32 v211, 0
	v_lshl_add_u64 v[210:211], s[42:43], 0, v[210:211]
	v_lshl_add_u64 v[210:211], s[34:35], 2, v[210:211]
	s_mul_i32 s44, s34, 15
	s_lshl4_add_u32 s44, s71, s44
	s_lshl_b32 s44, s44, 2
	v_lshl_add_u64 v[210:211], v[210:211], 0, s[44:45]
	s_waitcnt lgkmcnt(0)
	v_add_f32_e32 v0, v0, v209
	global_store_dword v[210:211], v0, off
; __device__ __forceinline__ float bperm(float v, int src_lane) { return __int_as_float(__builtin_amdgcn_ds_bpermute(src_lane << 2, __float_as_int(v))); }
; __device__ __forceinline__ u32x4 pack8(const f32x4 a, const f32x4 b) { u32x4 w; w.x = cvt_pk_bf16(a.x, a.y); w.y = cvt_pk_bf16(a.z, a.w); w.z = cvt_pk_bf16(b.x, b.y); w.w = cvt_pk_bf16(b.z, b.w); return w; }
; __host__ __device__ __forceinline__ size_t xs_off(int row, int col) { return (size_t)(row >> 8) * (256 * D) + (size_t)(col >> 6) * (256 * 64) + (size_t)((row & 255) * 64 + (col & 63)); }
;     template <bool INF32, int M0, int M1> __device__ __forceinline__ void half(f32x4 (&acc)[2][2][4][2], int ai, int b, int row0, int col, int pn, int wc, int fr, int fq) const {
;     ...
;         for (int m = M0; m < M1; ++m) { const int row = row0 + ai * 128 + m * 16; float ss = 0.f;
; #pragma unroll
;             for (int bj = 0; bj < 2; ++bj) { const size_t o = (size_t)row * D + col + bj * 128;
;                 const f32x4 x0 = xv[m][bj][0] + gt[bj][0] * acc[ai][bj][m][0], x1 = xv[m][bj][1] + gt[bj][1] * acc[ai][bj][m][1];
;                 if (out_f32) { *(f32x4*)((float*)xout + o) = x0; *(f32x4*)((float*)xout + o + 4) = x1; }
;                 else { const f32x8_t ff = {x0.x, x0.y, x0.z, x0.w, x1.x, x1.y, x1.z, x1.w}; *(f16x8_t*)((bf16_t*)xout + o) = __builtin_convertvector(ff, f16x8_t); }
;                 ss += ((x0.x * x0.x + x0.y * x0.y) + (x0.z * x0.z + x0.w * x0.w)) + ((x1.x * x1.x + x1.y * x1.y) + (x1.z * x1.z + x1.w * x1.w));
;                 if (XS) *(u32x4*)(XS + xs_off(row0, col) + (ai * 128 + m * 16) * 64 + bj * (2 * 256 * 64)) = pack8(x0 * gs[bj][0], x1 * gs[bj][1]); }
;             { const int ln = fr + 16 * fq; ss += bperm(ss, ln ^ 16); ss += bperm(ss, ln ^ 32); }
;             if (fq == 0) RSS[(size_t)row * 32 + pn * 4 + wc] = ss; }
.LBB0_1142:
	s_or_b64 exec, exec, s[46:47]
	v_cvt_f32_f16_sdwa v211, v184 dst_sel:DWORD dst_unused:UNUSED_PAD src0_sel:WORD_1
	v_cvt_f32_f16_sdwa v213, v185 dst_sel:DWORD dst_unused:UNUSED_PAD src0_sel:WORD_1
	v_cvt_f32_f16_sdwa v215, v182 dst_sel:DWORD dst_unused:UNUSED_PAD src0_sel:WORD_1
	v_cvt_f32_f16_sdwa v223, v183 dst_sel:DWORD dst_unused:UNUSED_PAD src0_sel:WORD_1
	v_cvt_f32_f16_e32 v210, v184
	v_cvt_f32_f16_e32 v212, v185
	v_cvt_f32_f16_e32 v214, v182
	v_cvt_f32_f16_e32 v222, v183
	v_pk_fma_f32 v[210:211], v[42:43], v[154:155], v[210:211]
	v_pk_fma_f32 v[212:213], v[44:45], v[156:157], v[212:213]
	v_pk_fma_f32 v[214:215], v[46:47], v[158:159], v[214:215]
	v_pk_fma_f32 v[222:223], v[48:49], v[160:161], v[222:223]
	v_lshl_add_u64 v[234:235], s[10:11], 0, v[234:235]
	v_cvt_f32_f16_sdwa v183, v180 dst_sel:DWORD dst_unused:UNUSED_PAD src0_sel:WORD_1
	v_cvt_f32_f16_sdwa v185, v181 dst_sel:DWORD dst_unused:UNUSED_PAD src0_sel:WORD_1
	v_cvt_f32_f16_sdwa v225, v178 dst_sel:DWORD dst_unused:UNUSED_PAD src0_sel:WORD_1
	v_cvt_f32_f16_sdwa v237, v179 dst_sel:DWORD dst_unused:UNUSED_PAD src0_sel:WORD_1
	v_cvt_f32_f16_e32 v182, v180
	v_cvt_f32_f16_e32 v184, v181
	v_cvt_f32_f16_e32 v224, v178
	v_cvt_f32_f16_e32 v236, v179
	v_cvt_pk_f16_f32 v181, v212, v213
	v_cvt_pk_f16_f32 v179, v222, v223
	v_cvt_pk_f16_f32 v180, v210, v211
	v_cvt_pk_f16_f32 v178, v214, v215
	v_lshl_add_u64 v[234:235], v[198:199], 1, v[234:235]
	v_lshl_add_u64 v[234:235], v[234:235], 0, s[100:101]
	global_store_dwordx4 v[234:235], v[178:181], off
	v_mul_f32_e32 v0, v215, v215
	v_fmac_f32_e32 v0, v214, v214
	v_mul_f32_e32 v178, v223, v223
	v_fmac_f32_e32 v178, v222, v222
	v_add_f32_e32 v0, v0, v178
	v_mul_f32_e32 v178, v211, v211
	v_mul_f32_e32 v179, v213, v213
	v_fmac_f32_e32 v178, v210, v210
	v_fmac_f32_e32 v179, v212, v212
	v_add_f32_e32 v178, v178, v179
	v_add_f32_e32 v0, v0, v178
	v_pk_mul_f32 v[180:181], v[152:153], v[222:223]
	v_pk_mul_f32 v[178:179], v[150:151], v[214:215]
	v_pk_mul_f32 v[212:213], v[148:149], v[212:213]
	v_pk_mul_f32 v[210:211], v[146:147], v[210:211]
	v_cvt_pk_bf16_f32 v178, v178, v179
	v_cvt_pk_bf16_f32 v179, v180, v181
	v_pk_fma_f32 v[184:185], v[36:37], v[140:141], v[184:185]
	v_cvt_pk_bf16_f32 v180, v210, v211
	v_cvt_pk_bf16_f32 v181, v212, v213
	v_pk_fma_f32 v[210:211], v[40:41], v[144:145], v[236:237]
	v_pk_fma_f32 v[212:213], v[38:39], v[142:143], v[224:225]
	v_pk_fma_f32 v[182:183], v[34:35], v[138:139], v[182:183]
	global_store_dwordx4 v[220:221], v[178:181], off offset:2048
	s_nop 1
	v_cvt_pk_f16_f32 v181, v184, v185
	v_cvt_pk_f16_f32 v179, v210, v211
	v_cvt_pk_f16_f32 v180, v182, v183
	v_cvt_pk_f16_f32 v178, v212, v213
	global_store_dwordx4 v[234:235], v[178:181], off offset:1024
	s_nop 1
	v_mul_f32_e32 v178, v213, v213
	v_mul_f32_e32 v179, v211, v211
	v_fmac_f32_e32 v178, v212, v212
	v_fmac_f32_e32 v179, v210, v210
	v_add_f32_e32 v178, v178, v179
	v_mul_f32_e32 v179, v183, v183
	v_mul_f32_e32 v180, v185, v185
	v_fmac_f32_e32 v179, v182, v182
	v_fmac_f32_e32 v180, v184, v184
	v_add_f32_e32 v179, v179, v180
	v_add_f32_e32 v178, v178, v179
	v_add_f32_e32 v0, v0, v178
	v_pk_mul_f32 v[178:179], v[136:137], v[210:211]
	v_pk_mul_f32 v[180:181], v[134:135], v[212:213]
	v_pk_mul_f32 v[184:185], v[132:133], v[184:185]
	v_cvt_pk_bf16_f32 v180, v180, v181
	v_cvt_pk_bf16_f32 v181, v178, v179
	ds_bpermute_b32 v178, v245, v0
	v_pk_mul_f32 v[182:183], v[130:131], v[182:183]
	s_waitcnt lgkmcnt(0)
	v_add_f32_e32 v0, v0, v178
	ds_bpermute_b32 v178, v244, v0
	v_cvt_pk_bf16_f32 v182, v182, v183
	v_cvt_pk_bf16_f32 v183, v184, v185
	v_add_co_u32_e32 v184, vcc, 0x14000, v216
	s_nop 1
	v_addc_co_u32_e32 v185, vcc, 0, v217, vcc
	global_store_dwordx4 v[184:185], v[180:183], off offset:2048
	s_and_saveexec_b64 s[46:47], s[28:29]
	s_cbranch_execz .LBB0_1144
	v_lshlrev_b64 v[180:181], 7, v[232:233]
	v_bfe_u32 v181, v180, 7, 4
	v_lshl_add_u32 v180, v181, 2, v180
	v_lshlrev_b32_e32 v181, 7, v181
	v_sub_u32_e32 v180, v180, v181
	v_mov_b32_e32 v181, 0
	v_lshl_add_u64 v[180:181], s[42:43], 0, v[180:181]
	v_lshl_add_u64 v[180:181], s[34:35], 2, v[180:181]
	s_mul_i32 s44, s34, 15
	s_lshl4_add_u32 s44, s71, s44
	s_lshl_b32 s44, s44, 2
	v_lshl_add_u64 v[180:181], v[180:181], 0, s[44:45]
	s_waitcnt lgkmcnt(0)
	v_add_f32_e32 v0, v0, v178
	global_store_dword v[180:181], v0, off
; __device__ __forceinline__ float bperm(float v, int src_lane) { return __int_as_float(__builtin_amdgcn_ds_bpermute(src_lane << 2, __float_as_int(v))); }
; __device__ __forceinline__ u32x4 pack8(const f32x4 a, const f32x4 b) { u32x4 w; w.x = cvt_pk_bf16(a.x, a.y); w.y = cvt_pk_bf16(a.z, a.w); w.z = cvt_pk_bf16(b.x, b.y); w.w = cvt_pk_bf16(b.z, b.w); return w; }
; __host__ __device__ __forceinline__ size_t xs_off(int row, int col) { return (size_t)(row >> 8) * (256 * D) + (size_t)(col >> 6) * (256 * 64) + (size_t)((row & 255) * 64 + (col & 63)); }
;     template <bool INF32, int M0, int M1> __device__ __forceinline__ void half(f32x4 (&acc)[2][2][4][2], int ai, int b, int row0, int col, int pn, int wc, int fr, int fq) const {
;     ...
;         for (int m = M0; m < M1; ++m) { const int row = row0 + ai * 128 + m * 16; float ss = 0.f;
; #pragma unroll
;             for (int bj = 0; bj < 2; ++bj) { const size_t o = (size_t)row * D + col + bj * 128;
;                 const f32x4 x0 = xv[m][bj][0] + gt[bj][0] * acc[ai][bj][m][0], x1 = xv[m][bj][1] + gt[bj][1] * acc[ai][bj][m][1];
;                 if (out_f32) { *(f32x4*)((float*)xout + o) = x0; *(f32x4*)((float*)xout + o + 4) = x1; }
;                 else { const f32x8_t ff = {x0.x, x0.y, x0.z, x0.w, x1.x, x1.y, x1.z, x1.w}; *(f16x8_t*)((bf16_t*)xout + o) = __builtin_convertvector(ff, f16x8_t); }
;                 ss += ((x0.x * x0.x + x0.y * x0.y) + (x0.z * x0.z + x0.w * x0.w)) + ((x1.x * x1.x + x1.y * x1.y) + (x1.z * x1.z + x1.w * x1.w));
;                 if (XS) *(u32x4*)(XS + xs_off(row0, col) + (ai * 128 + m * 16) * 64 + bj * (2 * 256 * 64)) = pack8(x0 * gs[bj][0], x1 * gs[bj][1]); }
;             { const int ln = fr + 16 * fq; ss += bperm(ss, ln ^ 16); ss += bperm(ss, ln ^ 32); }
;             if (fq == 0) RSS[(size_t)row * 32 + pn * 4 + wc] = ss; }
.LBB0_1144:
	s_or_b64 exec, exec, s[46:47]
	v_cvt_f32_f16_sdwa v179, v176 dst_sel:DWORD dst_unused:UNUSED_PAD src0_sel:WORD_1
	v_cvt_f32_f16_sdwa v181, v177 dst_sel:DWORD dst_unused:UNUSED_PAD src0_sel:WORD_1
	v_cvt_f32_f16_sdwa v183, v174 dst_sel:DWORD dst_unused:UNUSED_PAD src0_sel:WORD_1
	v_cvt_f32_f16_sdwa v185, v175 dst_sel:DWORD dst_unused:UNUSED_PAD src0_sel:WORD_1
	s_waitcnt lgkmcnt(0)
	v_cvt_f32_f16_e32 v178, v176
	v_cvt_f32_f16_e32 v180, v177
	v_cvt_f32_f16_e32 v182, v174
	v_cvt_f32_f16_e32 v184, v175
	v_pk_fma_f32 v[178:179], v[26:27], v[154:155], v[178:179]
	v_pk_fma_f32 v[180:181], v[28:29], v[156:157], v[180:181]
	v_pk_fma_f32 v[182:183], v[30:31], v[158:159], v[182:183]
	v_pk_fma_f32 v[174:175], v[32:33], v[160:161], v[184:185]
	v_lshl_add_u64 v[184:185], s[10:11], 0, v[230:231]
	v_cvt_f32_f16_sdwa v177, v172 dst_sel:DWORD dst_unused:UNUSED_PAD src0_sel:WORD_1
	v_cvt_f32_f16_sdwa v211, v173 dst_sel:DWORD dst_unused:UNUSED_PAD src0_sel:WORD_1
	v_cvt_f32_f16_sdwa v213, v170 dst_sel:DWORD dst_unused:UNUSED_PAD src0_sel:WORD_1
	v_cvt_f32_f16_sdwa v215, v171 dst_sel:DWORD dst_unused:UNUSED_PAD src0_sel:WORD_1
	v_cvt_f32_f16_e32 v176, v172
	v_cvt_f32_f16_e32 v210, v173
	v_cvt_f32_f16_e32 v212, v170
	v_cvt_f32_f16_e32 v214, v171
	v_cvt_pk_f16_f32 v173, v180, v181
	v_cvt_pk_f16_f32 v171, v174, v175
	v_cvt_pk_f16_f32 v172, v178, v179
	v_cvt_pk_f16_f32 v170, v182, v183
	v_lshl_add_u64 v[184:185], v[198:199], 1, v[184:185]
	v_lshl_add_u64 v[184:185], v[184:185], 0, s[100:101]
	global_store_dwordx4 v[184:185], v[170:173], off
	v_mul_f32_e32 v0, v183, v183
	v_fmac_f32_e32 v0, v182, v182
	v_mul_f32_e32 v170, v175, v175
	v_fmac_f32_e32 v170, v174, v174
	v_add_f32_e32 v0, v0, v170
	v_mul_f32_e32 v170, v179, v179
	v_mul_f32_e32 v171, v181, v181
	v_fmac_f32_e32 v170, v178, v178
	v_fmac_f32_e32 v171, v180, v180
	v_add_f32_e32 v170, v170, v171
	v_add_f32_e32 v0, v0, v170
	v_pk_mul_f32 v[170:171], v[152:153], v[174:175]
	v_pk_mul_f32 v[172:173], v[150:151], v[182:183]
	v_pk_mul_f32 v[180:181], v[148:149], v[180:181]
	v_pk_mul_f32 v[174:175], v[146:147], v[178:179]
	v_cvt_pk_bf16_f32 v172, v172, v173
	v_cvt_pk_bf16_f32 v173, v170, v171
	v_add_co_u32_e32 v170, vcc, s82, v216
	v_cvt_pk_bf16_f32 v174, v174, v175
	v_cvt_pk_bf16_f32 v175, v180, v181
	v_pk_fma_f32 v[178:179], v[24:25], v[144:145], v[214:215]
	s_nop 0
	v_addc_co_u32_e32 v171, vcc, 0, v217, vcc
	v_pk_fma_f32 v[180:181], v[22:23], v[142:143], v[212:213]
	v_pk_fma_f32 v[182:183], v[20:21], v[140:141], v[210:211]
	v_pk_fma_f32 v[176:177], v[18:19], v[138:139], v[176:177]
	global_store_dwordx4 v[170:171], v[172:175], off
	s_nop 1
	v_cvt_pk_f16_f32 v175, v182, v183
	v_cvt_pk_f16_f32 v173, v178, v179
	v_cvt_pk_f16_f32 v174, v176, v177
	v_cvt_pk_f16_f32 v172, v180, v181
	global_store_dwordx4 v[184:185], v[172:175], off offset:1024
	s_nop 1
	v_mul_f32_e32 v172, v181, v181
	v_mul_f32_e32 v173, v179, v179
	v_fmac_f32_e32 v172, v180, v180
	v_fmac_f32_e32 v173, v178, v178
	v_add_f32_e32 v172, v172, v173
	v_mul_f32_e32 v173, v177, v177
	v_mul_f32_e32 v174, v183, v183
	v_fmac_f32_e32 v173, v176, v176
	v_fmac_f32_e32 v174, v182, v182
	v_add_f32_e32 v173, v173, v174
	v_add_f32_e32 v172, v172, v173
	v_add_f32_e32 v0, v0, v172
	v_pk_mul_f32 v[172:173], v[136:137], v[178:179]
	v_pk_mul_f32 v[174:175], v[134:135], v[180:181]
	v_pk_mul_f32 v[178:179], v[132:133], v[182:183]
	v_cvt_pk_bf16_f32 v174, v174, v175
	v_cvt_pk_bf16_f32 v175, v172, v173
	ds_bpermute_b32 v172, v245, v0
	v_pk_mul_f32 v[176:177], v[130:131], v[176:177]
	s_waitcnt lgkmcnt(0)
	v_add_f32_e32 v0, v0, v172
	ds_bpermute_b32 v172, v244, v0
	v_cvt_pk_bf16_f32 v176, v176, v177
	v_cvt_pk_bf16_f32 v177, v178, v179
	v_add_co_u32_e32 v178, vcc, 0x15000, v216
	s_nop 1
	v_addc_co_u32_e32 v179, vcc, 0, v217, vcc
	global_store_dwordx4 v[178:179], v[174:177], off
	s_and_saveexec_b64 s[46:47], s[28:29]
	s_cbranch_execz .LBB0_1146
	v_lshlrev_b64 v[174:175], 7, v[228:229]
	v_bfe_u32 v175, v174, 7, 4
	v_lshl_add_u32 v174, v175, 2, v174
	v_lshlrev_b32_e32 v175, 7, v175
	v_sub_u32_e32 v174, v174, v175
	v_mov_b32_e32 v175, 0
	v_lshl_add_u64 v[174:175], s[42:43], 0, v[174:175]
	v_lshl_add_u64 v[174:175], s[34:35], 2, v[174:175]
	s_mul_i32 s44, s34, 15
	s_lshl4_add_u32 s44, s71, s44
	s_lshl_b32 s44, s44, 2
	v_lshl_add_u64 v[174:175], v[174:175], 0, s[44:45]
	s_waitcnt lgkmcnt(0)
	v_add_f32_e32 v0, v0, v172
	global_store_dword v[174:175], v0, off

;     template <bool INF32, int M0, int M1> __device__ __forceinline__ void half(f32x4 (&acc)[2][2][4][2], int ai, int b, int row0, int col, int pn, int wc, int fr, int fq) const {
;     ...
;         if (INF32) {
; #pragma unroll
;             for (int m = M0; m < M1; ++m)
; #pragma unroll
;                 for (int bj = 0; bj < 2; ++bj) { const float* p = (const float*)xin + (size_t)(row0 + ai * 128 + m * 16) * D + col + bj * 128; xv[m][bj][0] = *(const f32x4*)p; xv[m][bj][1] = *(const f32x4*)(p + 4); }
;         } else {
;             f16x8_t hh[4][2];
; #pragma unroll
;             for (int m = M0; m < M1; ++m)
; #pragma unroll
;                 for (int bj = 0; bj < 2; ++bj) hh[m][bj] = *(const f16x8_t*)((const bf16_t*)xin + (size_t)(row0 + ai * 128 + m * 16) * D + col + bj * 128);
; #pragma unroll
;             for (int m = M0; m < M1; ++m)
; #pragma unroll
;                 for (int bj = 0; bj < 2; ++bj) { const f32x8_t ff = __builtin_convertvector(hh[m][bj], f32x8_t); xv[m][bj][0] = (f32x4){ff[0], ff[1], ff[2], ff[3]}; xv[m][bj][1] = (f32x4){ff[4], ff[5], ff[6], ff[7]}; }
;         }
;         f32x4 gt[2][2], gs[2][2];
; #pragma unroll
;         for (int bj = 0; bj < 2; ++bj)
; #pragma unroll
;             for (int n = 0; n < 2; ++n) { gt[bj][n] = *(const f32x4*)(gate + (size_t)b * 6 * D + col + bj * 128 + n * 4); gs[bj][n] = XS ? *(const f32x4*)(GS + (size_t)b * D + col + bj * 128 + n * 4) : (f32x4){0.f, 0.f, 0.f, 0.f}; }
;         __builtin_amdgcn_sched_barrier(0);
; #pragma unroll
;         for (int m = M0; m < M1; ++m) { const int row = row0 + ai * 128 + m * 16; float ss = 0.f;
; #pragma unroll
;             for (int bj = 0; bj < 2; ++bj) { const size_t o = (size_t)row * D + col + bj * 128;
;                 const f32x4 x0 = xv[m][bj][0] + gt[bj][0] * acc[ai][bj][m][0], x1 = xv[m][bj][1] + gt[bj][1] * acc[ai][bj][m][1];
;                 if (out_f32) { *(f32x4*)((float*)xout + o) = x0; *(f32x4*)((float*)xout + o + 4) = x1; }
;                 else { const f32x8_t ff = {x0.x, x0.y, x0.z, x0.w, x1.x, x1.y, x1.z, x1.w}; *(f16x8_t*)((bf16_t*)xout + o) = __builtin_convertvector(ff, f16x8_t); }
;                 ss += ((x0.x * x0.x + x0.y * x0.y) + (x0.z * x0.z + x0.w * x0.w)) + ((x1.x * x1.x + x1.y * x1.y) + (x1.z * x1.z + x1.w * x1.w));
.LBB0_1149:
	s_mov_b64 s[28:29], 0
	s_cbranch_execz .LBB0_1147
	s_ashr_i32 s34, s31, 8
	s_ashr_i32 s37, s36, 31
	s_ashr_i32 s35, s34, 31
	v_readlane_b32 s12, v254, 30
	s_lshl_b64 s[28:29], s[36:37], 13
	s_lshl_b64 s[36:37], s[34:35], 20
	v_readlane_b32 s13, v254, 31
	v_lshlrev_b64 v[132:133], 2, v[198:199]
	s_waitcnt lgkmcnt(0)
	v_lshlrev_b64 v[130:131], 13, v[200:201]
	v_lshl_add_u64 v[180:181], s[12:13], 0, v[132:133]
	s_add_u32 s34, s63, s66
	v_lshl_add_u64 v[130:131], v[180:181], 0, v[130:131]
	s_addc_u32 s35, s67, s65
	global_load_dwordx4 v[216:219], v[130:131], off offset:16
	global_load_dwordx4 v[220:223], v[130:131], off
	global_load_dwordx4 v[224:227], v[130:131], off offset:528
	global_load_dwordx4 v[228:231], v[130:131], off offset:512
	v_lshlrev_b64 v[130:131], 13, v[206:207]
	s_add_u32 s28, s68, s28
	v_lshl_add_u64 v[130:131], v[180:181], 0, v[130:131]
	v_lshl_add_u64 v[182:183], s[34:35], 0, v[132:133]
	s_addc_u32 s29, s70, s29
	global_load_dwordx4 v[162:165], v[130:131], off offset:16
	global_load_dwordx4 v[166:169], v[130:131], off
	global_load_dwordx4 v[138:141], v[130:131], off offset:528
	global_load_dwordx4 v[142:145], v[130:131], off offset:512
	v_lshl_add_u64 v[184:185], s[28:29], 0, v[132:133]
	global_load_dwordx4 v[170:173], v[182:183], off offset:16
	global_load_dwordx4 v[174:177], v[182:183], off
	global_load_dwordx4 v[154:157], v[184:185], off offset:16
	global_load_dwordx4 v[158:161], v[184:185], off
	global_load_dwordx4 v[146:149], v[182:183], off offset:528
	global_load_dwordx4 v[150:153], v[182:183], off offset:512
	global_load_dwordx4 v[130:133], v[184:185], off offset:528
	global_load_dwordx4 v[134:137], v[184:185], off offset:512
	v_ashrrev_i32_e32 v209, 31, v208
	v_lshlrev_b64 v[178:179], 15, v[208:209]
	v_cmp_gt_u32_e64 s[28:29], 16, v247
	v_readlane_b32 s14, v254, 32
	v_readlane_b32 s15, v254, 33
	v_readlane_b32 s16, v254, 34
	v_readlane_b32 s17, v254, 35
	v_readlane_b32 s18, v254, 36
	v_readlane_b32 s19, v254, 37
	v_readlane_b32 s20, v254, 38
	v_readlane_b32 s21, v254, 39
	v_readlane_b32 s22, v254, 40
	v_readlane_b32 s23, v254, 41
	v_readlane_b32 s24, v254, 42
	v_readlane_b32 s25, v254, 43
	v_readlane_b32 s26, v254, 44
	v_readlane_b32 s27, v254, 45
	v_lshlrev_b64 v[212:213], 12, v[200:201]
	v_bfe_u32 v213, v212, 12, 4
	v_lshl_add_u32 v212, v213, 6, v212
	v_lshlrev_b32_e32 v213, 12, v213
	v_sub_u32_e32 v212, v212, v213
	v_mov_b32_e32 v213, 0
	s_waitcnt vmcnt(0)
	v_pk_fma_f32 v[128:129], v[128:129], v[176:177], v[222:223]
	v_pk_fma_f32 v[126:127], v[126:127], v[174:175], v[220:221]
	v_pk_fma_f32 v[208:209], v[124:125], v[172:173], v[218:219]
	v_pk_fma_f32 v[210:211], v[122:123], v[170:171], v[216:217]
	v_lshl_add_u64 v[212:213], s[10:11], 0, v[212:213]
	v_cvt_pk_f16_f32 v125, v208, v209
	v_cvt_pk_f16_f32 v123, v128, v129
	v_cvt_pk_f16_f32 v124, v210, v211
	v_cvt_pk_f16_f32 v122, v126, v127
	v_lshl_add_u64 v[212:213], v[198:199], 1, v[212:213]
	v_lshl_add_u64 v[212:213], v[212:213], 0, s[100:101]
	global_store_dwordx4 v[212:213], v[122:125], off
	v_mul_f32_e32 v0, v127, v127
	v_fmac_f32_e32 v0, v126, v126
	v_mul_f32_e32 v122, v129, v129
	v_fmac_f32_e32 v122, v128, v128
	v_add_f32_e32 v0, v0, v122
	v_mul_f32_e32 v122, v211, v211
	v_mul_f32_e32 v123, v209, v209
	v_fmac_f32_e32 v122, v210, v210
	v_fmac_f32_e32 v123, v208, v208
	v_add_f32_e32 v122, v122, v123
	v_add_f32_e32 v214, v0, v122
	v_pk_mul_f32 v[124:125], v[160:161], v[128:129]
	v_pk_mul_f32 v[122:123], v[158:159], v[126:127]
	v_pk_mul_f32 v[126:127], v[156:157], v[208:209]
	v_pk_mul_f32 v[128:129], v[154:155], v[210:211]
	v_cvt_pk_bf16_f32 v122, v122, v123
	v_cvt_pk_bf16_f32 v123, v124, v125
	v_lshlrev_b32_e32 v0, 1, v246
	v_cvt_pk_bf16_f32 v124, v128, v129
	v_cvt_pk_bf16_f32 v125, v126, v127
	v_lshl_add_u64 v[126:127], s[74:75], 0, v[178:179]
	v_lshl_add_u64 v[126:127], v[126:127], 0, s[36:37]
	v_lshl_add_u64 v[178:179], v[126:127], 0, v[0:1]
	global_store_dwordx4 v[178:179], v[122:125], off
	v_pk_fma_f32 v[120:121], v[120:121], v[152:153], v[230:231]
	v_pk_fma_f32 v[118:119], v[118:119], v[150:151], v[228:229]
	v_pk_fma_f32 v[122:123], v[116:117], v[148:149], v[226:227]
	v_pk_fma_f32 v[124:125], v[114:115], v[146:147], v[224:225]
	v_cvt_pk_f16_f32 v117, v122, v123
	v_cvt_pk_f16_f32 v115, v120, v121
	v_cvt_pk_f16_f32 v116, v124, v125
	v_cvt_pk_f16_f32 v114, v118, v119
	global_store_dwordx4 v[212:213], v[114:117], off offset:1024
	v_mul_f32_e32 v0, v119, v119
	v_fmac_f32_e32 v0, v118, v118
	v_mul_f32_e32 v114, v121, v121
	v_fmac_f32_e32 v114, v120, v120
	v_add_f32_e32 v0, v0, v114
	v_mul_f32_e32 v114, v125, v125
	v_mul_f32_e32 v115, v123, v123
	v_fmac_f32_e32 v114, v124, v124
	v_fmac_f32_e32 v115, v122, v122
	v_add_f32_e32 v114, v114, v115
	v_add_f32_e32 v0, v0, v114
	v_add_f32_e32 v0, v214, v0
	v_pk_mul_f32 v[114:115], v[136:137], v[120:121]
	v_pk_mul_f32 v[116:117], v[134:135], v[118:119]
	v_pk_mul_f32 v[120:121], v[132:133], v[122:123]
	v_cvt_pk_bf16_f32 v116, v116, v117
	v_cvt_pk_bf16_f32 v117, v114, v115
	ds_bpermute_b32 v114, v245, v0
	v_pk_mul_f32 v[118:119], v[130:131], v[124:125]
	s_lshl_b32 s34, s30, 2
	v_cvt_pk_bf16_f32 v118, v118, v119
	v_cvt_pk_bf16_f32 v119, v120, v121
	s_waitcnt lgkmcnt(0)
	v_add_f32_e32 v0, v0, v114
	ds_bpermute_b32 v114, v244, v0
	v_add_co_u32_e32 v120, vcc, 0x10000, v178
	s_ashr_i32 s35, s34, 31
	s_nop 0
	v_addc_co_u32_e32 v121, vcc, 0, v179, vcc
	global_store_dwordx4 v[120:121], v[116:119], off
	s_and_saveexec_b64 s[30:31], s[28:29]
	s_cbranch_execz .LBB0_1152
	v_lshlrev_b64 v[116:117], 7, v[200:201]
	v_bfe_u32 v117, v116, 7, 4
	v_lshl_add_u32 v116, v117, 2, v116
	v_lshlrev_b32_e32 v117, 7, v117
	v_sub_u32_e32 v116, v116, v117
	v_mov_b32_e32 v117, 0
	v_lshl_add_u64 v[116:117], s[42:43], 0, v[116:117]
	v_lshl_add_u64 v[116:117], s[34:35], 2, v[116:117]
	s_mul_i32 s44, s34, 15
	s_lshl4_add_u32 s44, s71, s44
	s_lshl_b32 s44, s44, 2
	v_lshl_add_u64 v[116:117], v[116:117], 0, s[44:45]
	s_waitcnt lgkmcnt(0)
	v_add_f32_e32 v0, v0, v114
	global_store_dword v[116:117], v0, off
;     template <bool INF32, int M0, int M1> __device__ __forceinline__ void half(f32x4 (&acc)[2][2][4][2], int ai, int b, int row0, int col, int pn, int wc, int fr, int fq) const {
;     ...
;         if (INF32) {
; #pragma unroll
;             for (int m = M0; m < M1; ++m)
; #pragma unroll
;                 for (int bj = 0; bj < 2; ++bj) { const float* p = (const float*)xin + (size_t)(row0 + ai * 128 + m * 16) * D + col + bj * 128; xv[m][bj][0] = *(const f32x4*)p; xv[m][bj][1] = *(const f32x4*)(p + 4); }
;         } else {
;             f16x8_t hh[4][2];
; #pragma unroll
;             for (int m = M0; m < M1; ++m)
; #pragma unroll
;                 for (int bj = 0; bj < 2; ++bj) hh[m][bj] = *(const f16x8_t*)((const bf16_t*)xin + (size_t)(row0 + ai * 128 + m * 16) * D + col + bj * 128);
; #pragma unroll
;             for (int m = M0; m < M1; ++m)
; #pragma unroll
;                 for (int bj = 0; bj < 2; ++bj) { const f32x8_t ff = __builtin_convertvector(hh[m][bj], f32x8_t); xv[m][bj][0] = (f32x4){ff[0], ff[1], ff[2], ff[3]}; xv[m][bj][1] = (f32x4){ff[4], ff[5], ff[6], ff[7]}; }
;         }
;         f32x4 gt[2][2], gs[2][2];
; #pragma unroll
;         for (int bj = 0; bj < 2; ++bj)
; #pragma unroll
;             for (int n = 0; n < 2; ++n) { gt[bj][n] = *(const f32x4*)(gate + (size_t)b * 6 * D + col + bj * 128 + n * 4); gs[bj][n] = XS ? *(const f32x4*)(GS + (size_t)b * D + col + bj * 128 + n * 4) : (f32x4){0.f, 0.f, 0.f, 0.f}; }
;         __builtin_amdgcn_sched_barrier(0);
; #pragma unroll
;         for (int m = M0; m < M1; ++m) { const int row = row0 + ai * 128 + m * 16; float ss = 0.f;
; #pragma unroll
;             for (int bj = 0; bj < 2; ++bj) { const size_t o = (size_t)row * D + col + bj * 128;
;                 const f32x4 x0 = xv[m][bj][0] + gt[bj][0] * acc[ai][bj][m][0], x1 = xv[m][bj][1] + gt[bj][1] * acc[ai][bj][m][1];
;                 if (out_f32) { *(f32x4*)((float*)xout + o) = x0; *(f32x4*)((float*)xout + o + 4) = x1; }
;                 else { const f32x8_t ff = {x0.x, x0.y, x0.z, x0.w, x1.x, x1.y, x1.z, x1.w}; *(f16x8_t*)((bf16_t*)xout + o) = __builtin_convertvector(ff, f16x8_t); }
;                 ss += ((x0.x * x0.x + x0.y * x0.y) + (x0.z * x0.z + x0.w * x0.w)) + ((x1.x * x1.x + x1.y * x1.y) + (x1.z * x1.z + x1.w * x1.w));
.LBB0_1152:
	s_or_b64 exec, exec, s[30:31]
	v_lshlrev_b64 v[118:119], 12, v[206:207]
	v_bfe_u32 v119, v118, 12, 4
	v_lshl_add_u32 v118, v119, 6, v118
	v_lshlrev_b32_e32 v119, 12, v119
	v_sub_u32_e32 v118, v118, v119
	v_mov_b32_e32 v119, 0
	v_pk_fma_f32 v[112:113], v[112:113], v[176:177], v[168:169]
	v_pk_fma_f32 v[110:111], v[110:111], v[174:175], v[166:167]
	s_waitcnt lgkmcnt(0)
	v_pk_fma_f32 v[114:115], v[108:109], v[172:173], v[164:165]
	v_pk_fma_f32 v[116:117], v[106:107], v[170:171], v[162:163]
	v_lshl_add_u64 v[118:119], s[10:11], 0, v[118:119]
	v_cvt_pk_f16_f32 v109, v114, v115
	v_cvt_pk_f16_f32 v107, v112, v113
	v_cvt_pk_f16_f32 v106, v110, v111
	v_cvt_pk_f16_f32 v108, v116, v117
	v_lshl_add_u64 v[118:119], v[198:199], 1, v[118:119]
	v_lshl_add_u64 v[118:119], v[118:119], 0, s[100:101]
	global_store_dwordx4 v[118:119], v[106:109], off
	v_mul_f32_e32 v0, v111, v111
	v_fmac_f32_e32 v0, v110, v110
	v_mul_f32_e32 v106, v113, v113
	v_fmac_f32_e32 v106, v112, v112
	v_add_f32_e32 v0, v0, v106
	v_mul_f32_e32 v106, v117, v117
	v_mul_f32_e32 v107, v115, v115
	v_fmac_f32_e32 v106, v116, v116
	v_fmac_f32_e32 v107, v114, v114
	v_add_f32_e32 v106, v106, v107
	v_add_f32_e32 v0, v0, v106
	v_pk_mul_f32 v[108:109], v[160:161], v[112:113]
	v_pk_mul_f32 v[106:107], v[158:159], v[110:111]
	v_pk_mul_f32 v[110:111], v[156:157], v[114:115]
	v_pk_mul_f32 v[112:113], v[154:155], v[116:117]
	v_cvt_pk_bf16_f32 v106, v106, v107
	v_cvt_pk_bf16_f32 v107, v108, v109
	v_pk_fma_f32 v[104:105], v[104:105], v[152:153], v[144:145]
	v_cvt_pk_bf16_f32 v108, v112, v113
	v_cvt_pk_bf16_f32 v109, v110, v111
	global_store_dwordx4 v[178:179], v[106:109], off offset:2048
	v_pk_fma_f32 v[102:103], v[102:103], v[150:151], v[142:143]
	s_nop 0
	v_pk_fma_f32 v[106:107], v[100:101], v[148:149], v[140:141]
	v_pk_fma_f32 v[108:109], v[98:99], v[146:147], v[138:139]
	v_cvt_pk_f16_f32 v101, v106, v107
	v_cvt_pk_f16_f32 v99, v104, v105
	v_cvt_pk_f16_f32 v98, v102, v103
	v_cvt_pk_f16_f32 v100, v108, v109
	global_store_dwordx4 v[118:119], v[98:101], off offset:1024
	s_nop 1
	v_mul_f32_e32 v98, v103, v103
	v_mul_f32_e32 v99, v105, v105
	v_fmac_f32_e32 v98, v102, v102
	v_fmac_f32_e32 v99, v104, v104
	v_add_f32_e32 v98, v98, v99
	v_mul_f32_e32 v99, v109, v109
	v_mul_f32_e32 v100, v107, v107
	v_fmac_f32_e32 v99, v108, v108
	v_fmac_f32_e32 v100, v106, v106
	v_add_f32_e32 v99, v99, v100
	v_add_f32_e32 v98, v98, v99
	v_add_f32_e32 v0, v0, v98
	v_pk_mul_f32 v[98:99], v[136:137], v[104:105]
	v_pk_mul_f32 v[100:101], v[134:135], v[102:103]
	v_pk_mul_f32 v[104:105], v[132:133], v[106:107]
	v_cvt_pk_bf16_f32 v100, v100, v101
	v_cvt_pk_bf16_f32 v101, v98, v99
	ds_bpermute_b32 v98, v245, v0
	v_pk_mul_f32 v[102:103], v[130:131], v[108:109]
	s_waitcnt lgkmcnt(0)
	v_add_f32_e32 v0, v0, v98
	ds_bpermute_b32 v98, v244, v0
	v_cvt_pk_bf16_f32 v102, v102, v103
	v_cvt_pk_bf16_f32 v103, v104, v105
	v_add_co_u32_e32 v104, vcc, 0x10000, v178
	s_nop 1
	v_addc_co_u32_e32 v105, vcc, 0, v179, vcc
	global_store_dwordx4 v[104:105], v[100:103], off offset:2048
	s_and_saveexec_b64 s[30:31], s[28:29]
	s_cbranch_execz .LBB0_1154
	v_lshlrev_b64 v[100:101], 7, v[206:207]
	v_bfe_u32 v101, v100, 7, 4
	v_lshl_add_u32 v100, v101, 2, v100
	v_lshlrev_b32_e32 v101, 7, v101
	v_sub_u32_e32 v100, v100, v101
	v_mov_b32_e32 v101, 0
	v_lshl_add_u64 v[100:101], s[42:43], 0, v[100:101]
	v_lshl_add_u64 v[100:101], s[34:35], 2, v[100:101]
	s_mul_i32 s44, s34, 15
	s_lshl4_add_u32 s44, s71, s44
	s_lshl_b32 s44, s44, 2
	v_lshl_add_u64 v[100:101], v[100:101], 0, s[44:45]
	s_waitcnt lgkmcnt(0)
	v_add_f32_e32 v0, v0, v98
	global_store_dword v[100:101], v0, off
.LBB0_1154:
	s_or_b64 exec, exec, s[30:31]
	s_waitcnt lgkmcnt(0)
	v_lshlrev_b64 v[98:99], 13, v[204:205]
	v_lshl_add_u64 v[98:99], v[180:181], 0, v[98:99]
	global_load_dwordx4 v[146:149], v[98:99], off offset:16
	global_load_dwordx4 v[150:153], v[98:99], off
	global_load_dwordx4 v[154:157], v[98:99], off offset:528
	global_load_dwordx4 v[158:161], v[98:99], off offset:512
	v_lshlrev_b64 v[98:99], 13, v[202:203]
	v_lshl_add_u64 v[98:99], v[180:181], 0, v[98:99]
	global_load_dwordx4 v[130:133], v[98:99], off offset:16
	global_load_dwordx4 v[138:141], v[98:99], off
	global_load_dwordx4 v[106:109], v[98:99], off offset:528
	global_load_dwordx4 v[114:117], v[98:99], off offset:512
	global_load_dwordx4 v[134:137], v[182:183], off offset:16
	global_load_dwordx4 v[142:145], v[182:183], off
	global_load_dwordx4 v[122:125], v[184:185], off offset:16
	global_load_dwordx4 v[126:129], v[184:185], off
	global_load_dwordx4 v[110:113], v[182:183], off offset:528
	global_load_dwordx4 v[118:121], v[182:183], off offset:512
	global_load_dwordx4 v[98:101], v[184:185], off offset:528
	global_load_dwordx4 v[102:105], v[184:185], off offset:512
	s_waitcnt vmcnt(6)
	v_pk_fma_f32 v[94:95], v[94:95], v[142:143], v[150:151]
	v_lshlrev_b64 v[150:151], 12, v[204:205]
	v_bfe_u32 v151, v150, 12, 4
	v_lshl_add_u32 v150, v151, 6, v150
	v_lshlrev_b32_e32 v151, 12, v151
	v_sub_u32_e32 v150, v150, v151
	v_mov_b32_e32 v151, 0
	v_pk_fma_f32 v[96:97], v[96:97], v[144:145], v[152:153]
	v_pk_fma_f32 v[148:149], v[92:93], v[136:137], v[148:149]
	v_pk_fma_f32 v[146:147], v[90:91], v[134:135], v[146:147]
	v_lshl_add_u64 v[150:151], s[10:11], 0, v[150:151]
	v_cvt_pk_f16_f32 v93, v148, v149
	v_cvt_pk_f16_f32 v91, v96, v97
	v_cvt_pk_f16_f32 v92, v146, v147
	v_cvt_pk_f16_f32 v90, v94, v95
	v_lshl_add_u64 v[150:151], v[198:199], 1, v[150:151]
	v_lshl_add_u64 v[150:151], v[150:151], 0, s[100:101]
	global_store_dwordx4 v[150:151], v[90:93], off
	v_mul_f32_e32 v0, v95, v95
	v_fmac_f32_e32 v0, v94, v94
	v_mul_f32_e32 v90, v97, v97
	v_fmac_f32_e32 v90, v96, v96
	v_add_f32_e32 v0, v0, v90
	v_mul_f32_e32 v90, v147, v147
	v_mul_f32_e32 v91, v149, v149
	v_fmac_f32_e32 v90, v146, v146
	v_fmac_f32_e32 v91, v148, v148
	v_add_f32_e32 v90, v90, v91
	v_add_f32_e32 v0, v0, v90
	s_waitcnt vmcnt(5)
; __device__ __forceinline__ float bperm(float v, int src_lane) { return __int_as_float(__builtin_amdgcn_ds_bpermute(src_lane << 2, __float_as_int(v))); }
; __device__ __forceinline__ u32x4 pack8(const f32x4 a, const f32x4 b) { u32x4 w; w.x = cvt_pk_bf16(a.x, a.y); w.y = cvt_pk_bf16(a.z, a.w); w.z = cvt_pk_bf16(b.x, b.y); w.w = cvt_pk_bf16(b.z, b.w); return w; }
; __host__ __device__ __forceinline__ size_t xs_off(int row, int col) { return (size_t)(row >> 8) * (256 * D) + (size_t)(col >> 6) * (256 * 64) + (size_t)((row & 255) * 64 + (col & 63)); }
;     template <bool INF32, int M0, int M1> __device__ __forceinline__ void half(f32x4 (&acc)[2][2][4][2], int ai, int b, int row0, int col, int pn, int wc, int fr, int fq) const {
;     ...
;         for (int m = M0; m < M1; ++m) { const int row = row0 + ai * 128 + m * 16; float ss = 0.f;
; #pragma unroll
;             for (int bj = 0; bj < 2; ++bj) { const size_t o = (size_t)row * D + col + bj * 128;
;                 const f32x4 x0 = xv[m][bj][0] + gt[bj][0] * acc[ai][bj][m][0], x1 = xv[m][bj][1] + gt[bj][1] * acc[ai][bj][m][1];
;                 if (out_f32) { *(f32x4*)((float*)xout + o) = x0; *(f32x4*)((float*)xout + o + 4) = x1; }
;                 else { const f32x8_t ff = {x0.x, x0.y, x0.z, x0.w, x1.x, x1.y, x1.z, x1.w}; *(f16x8_t*)((bf16_t*)xout + o) = __builtin_convertvector(ff, f16x8_t); }
;                 ss += ((x0.x * x0.x + x0.y * x0.y) + (x0.z * x0.z + x0.w * x0.w)) + ((x1.x * x1.x + x1.y * x1.y) + (x1.z * x1.z + x1.w * x1.w));
;                 if (XS) *(u32x4*)(XS + xs_off(row0, col) + (ai * 128 + m * 16) * 64 + bj * (2 * 256 * 64)) = pack8(x0 * gs[bj][0], x1 * gs[bj][1]); }
;             { const int ln = fr + 16 * fq; ss += bperm(ss, ln ^ 16); ss += bperm(ss, ln ^ 32); }
;             if (fq == 0) RSS[(size_t)row * 32 + pn * 4 + wc] = ss; }
	v_pk_mul_f32 v[90:91], v[128:129], v[96:97]
	v_pk_mul_f32 v[92:93], v[126:127], v[94:95]
	s_movk_i32 s12, 0x1000
	v_pk_mul_f32 v[94:95], v[122:123], v[146:147]
	v_cvt_pk_bf16_f32 v92, v92, v93
	v_cvt_pk_bf16_f32 v93, v90, v91
	v_add_co_u32_e32 v90, vcc, s12, v178
	v_pk_mul_f32 v[96:97], v[124:125], v[148:149]
	v_cvt_pk_bf16_f32 v94, v94, v95
	s_nop 0
	v_addc_co_u32_e32 v91, vcc, 0, v179, vcc
	v_cvt_pk_bf16_f32 v95, v96, v97
	global_store_dwordx4 v[90:91], v[92:95], off
	s_waitcnt vmcnt(4)
	v_pk_fma_f32 v[88:89], v[88:89], v[120:121], v[160:161]
	v_pk_fma_f32 v[86:87], v[86:87], v[118:119], v[158:159]
	v_pk_fma_f32 v[92:93], v[84:85], v[112:113], v[156:157]
	v_pk_fma_f32 v[94:95], v[82:83], v[110:111], v[154:155]
	v_cvt_pk_f16_f32 v85, v92, v93
	v_cvt_pk_f16_f32 v83, v88, v89
	v_cvt_pk_f16_f32 v84, v94, v95
	v_cvt_pk_f16_f32 v82, v86, v87
	global_store_dwordx4 v[150:151], v[82:85], off offset:1024
	s_nop 1
	v_mul_f32_e32 v82, v87, v87
	v_mul_f32_e32 v83, v89, v89
	v_fmac_f32_e32 v82, v86, v86
	v_fmac_f32_e32 v83, v88, v88
	v_add_f32_e32 v82, v82, v83
	v_mul_f32_e32 v83, v95, v95
	v_mul_f32_e32 v84, v93, v93
	v_fmac_f32_e32 v83, v94, v94
	v_fmac_f32_e32 v84, v92, v92
	v_add_f32_e32 v83, v83, v84
	v_add_f32_e32 v82, v82, v83
	v_add_f32_e32 v0, v0, v82
	s_waitcnt vmcnt(3)
	v_pk_mul_f32 v[82:83], v[104:105], v[88:89]
	v_pk_mul_f32 v[84:85], v[102:103], v[86:87]
	v_pk_mul_f32 v[88:89], v[100:101], v[92:93]
	v_cvt_pk_bf16_f32 v84, v84, v85
	v_cvt_pk_bf16_f32 v85, v82, v83
	ds_bpermute_b32 v82, v245, v0
	v_pk_mul_f32 v[86:87], v[98:99], v[94:95]
	s_waitcnt lgkmcnt(0)
	v_add_f32_e32 v0, v0, v82
	ds_bpermute_b32 v82, v244, v0
	v_cvt_pk_bf16_f32 v86, v86, v87
	v_cvt_pk_bf16_f32 v87, v88, v89
	v_add_co_u32_e32 v88, vcc, 0x11000, v178
	s_nop 1
	v_addc_co_u32_e32 v89, vcc, 0, v179, vcc
	global_store_dwordx4 v[88:89], v[84:87], off
	s_and_saveexec_b64 s[30:31], s[28:29]
	s_cbranch_execz .LBB0_1156
	v_lshlrev_b64 v[84:85], 7, v[204:205]
	v_bfe_u32 v85, v84, 7, 4
	v_lshl_add_u32 v84, v85, 2, v84
	v_lshlrev_b32_e32 v85, 7, v85
	v_sub_u32_e32 v84, v84, v85
	v_mov_b32_e32 v85, 0
	v_lshl_add_u64 v[84:85], s[42:43], 0, v[84:85]
	v_lshl_add_u64 v[84:85], s[34:35], 2, v[84:85]
	s_mul_i32 s44, s34, 15
	s_lshl4_add_u32 s44, s71, s44
	s_lshl_b32 s44, s44, 2
	v_lshl_add_u64 v[84:85], v[84:85], 0, s[44:45]
	s_waitcnt lgkmcnt(0)
	v_add_f32_e32 v0, v0, v82
	global_store_dword v[84:85], v0, off
.LBB0_1156:
	s_or_b64 exec, exec, s[30:31]
	v_lshlrev_b64 v[86:87], 12, v[202:203]
	v_bfe_u32 v87, v86, 12, 4
	v_lshl_add_u32 v86, v87, 6, v86
	v_lshlrev_b32_e32 v87, 12, v87
	v_sub_u32_e32 v86, v86, v87
	v_mov_b32_e32 v87, 0
	v_pk_fma_f32 v[80:81], v[80:81], v[144:145], v[140:141]
	v_pk_fma_f32 v[78:79], v[78:79], v[142:143], v[138:139]
	s_waitcnt lgkmcnt(0)
	v_pk_fma_f32 v[82:83], v[76:77], v[136:137], v[132:133]
	v_pk_fma_f32 v[84:85], v[74:75], v[134:135], v[130:131]
	v_lshl_add_u64 v[86:87], s[10:11], 0, v[86:87]
	v_cvt_pk_f16_f32 v77, v82, v83
	v_cvt_pk_f16_f32 v75, v80, v81
	v_cvt_pk_f16_f32 v74, v78, v79
	v_cvt_pk_f16_f32 v76, v84, v85
	v_lshl_add_u64 v[86:87], v[198:199], 1, v[86:87]
	v_lshl_add_u64 v[86:87], v[86:87], 0, s[100:101]
	global_store_dwordx4 v[86:87], v[74:77], off
	v_mul_f32_e32 v0, v79, v79
	v_fmac_f32_e32 v0, v78, v78
	v_mul_f32_e32 v74, v81, v81
	v_fmac_f32_e32 v74, v80, v80
	v_add_f32_e32 v0, v0, v74
	v_mul_f32_e32 v74, v85, v85
	v_mul_f32_e32 v75, v83, v83
	v_fmac_f32_e32 v74, v84, v84
	v_fmac_f32_e32 v75, v82, v82
	v_add_f32_e32 v74, v74, v75
	v_add_f32_e32 v0, v0, v74
	v_pk_mul_f32 v[76:77], v[128:129], v[80:81]
	v_pk_mul_f32 v[74:75], v[126:127], v[78:79]
	v_pk_mul_f32 v[78:79], v[124:125], v[82:83]
	v_pk_mul_f32 v[80:81], v[122:123], v[84:85]
	v_cvt_pk_bf16_f32 v74, v74, v75
	v_cvt_pk_bf16_f32 v75, v76, v77
	v_pk_fma_f32 v[72:73], v[72:73], v[120:121], v[116:117]
	v_cvt_pk_bf16_f32 v76, v80, v81
	v_cvt_pk_bf16_f32 v77, v78, v79
	global_store_dwordx4 v[90:91], v[74:77], off offset:2048
	v_pk_fma_f32 v[70:71], v[70:71], v[118:119], v[114:115]
	s_nop 0
	v_pk_fma_f32 v[74:75], v[68:69], v[112:113], v[108:109]
	v_pk_fma_f32 v[76:77], v[66:67], v[110:111], v[106:107]
	v_cvt_pk_f16_f32 v69, v74, v75
	v_cvt_pk_f16_f32 v67, v72, v73
	v_cvt_pk_f16_f32 v66, v70, v71
	v_cvt_pk_f16_f32 v68, v76, v77
	global_store_dwordx4 v[86:87], v[66:69], off offset:1024
	s_nop 1
	v_mul_f32_e32 v66, v71, v71
	v_mul_f32_e32 v67, v73, v73
	v_fmac_f32_e32 v66, v70, v70
	v_fmac_f32_e32 v67, v72, v72
	v_add_f32_e32 v66, v66, v67
	v_mul_f32_e32 v67, v77, v77
	v_mul_f32_e32 v68, v75, v75
	v_fmac_f32_e32 v67, v76, v76
	v_fmac_f32_e32 v68, v74, v74
	v_add_f32_e32 v67, v67, v68
	v_add_f32_e32 v66, v66, v67
	v_add_f32_e32 v0, v0, v66
	v_pk_mul_f32 v[66:67], v[104:105], v[72:73]
	v_pk_mul_f32 v[68:69], v[102:103], v[70:71]
	v_pk_mul_f32 v[72:73], v[100:101], v[74:75]
	v_cvt_pk_bf16_f32 v68, v68, v69
	v_cvt_pk_bf16_f32 v69, v66, v67
	ds_bpermute_b32 v66, v245, v0
	v_pk_mul_f32 v[70:71], v[98:99], v[76:77]
	s_waitcnt lgkmcnt(0)
	v_add_f32_e32 v0, v0, v66
	ds_bpermute_b32 v66, v244, v0
	v_cvt_pk_bf16_f32 v70, v70, v71
	v_cvt_pk_bf16_f32 v71, v72, v73
	v_add_co_u32_e32 v72, vcc, 0x11000, v178
	s_nop 1
	v_addc_co_u32_e32 v73, vcc, 0, v179, vcc
	global_store_dwordx4 v[72:73], v[68:71], off offset:2048
	s_and_saveexec_b64 s[30:31], s[28:29]
	s_cbranch_execz .LBB0_1158
	v_lshlrev_b64 v[68:69], 7, v[202:203]
	v_bfe_u32 v69, v68, 7, 4
	v_lshl_add_u32 v68, v69, 2, v68
	v_lshlrev_b32_e32 v69, 7, v69
	v_sub_u32_e32 v68, v68, v69
	v_mov_b32_e32 v69, 0
	v_lshl_add_u64 v[68:69], s[42:43], 0, v[68:69]
	v_lshl_add_u64 v[68:69], s[34:35], 2, v[68:69]
	s_mul_i32 s44, s34, 15
	s_lshl4_add_u32 s44, s71, s44
	s_lshl_b32 s44, s44, 2
	v_lshl_add_u64 v[68:69], v[68:69], 0, s[44:45]
	s_waitcnt lgkmcnt(0)
	v_add_f32_e32 v0, v0, v66
	global_store_dword v[68:69], v0, off
;     template <bool INF32, int M0, int M1> __device__ __forceinline__ void half(f32x4 (&acc)[2][2][4][2], int ai, int b, int row0, int col, int pn, int wc, int fr, int fq) const {
;     ...
;         if (INF32) {
; #pragma unroll
;             for (int m = M0; m < M1; ++m)
; #pragma unroll
;                 for (int bj = 0; bj < 2; ++bj) { const float* p = (const float*)xin + (size_t)(row0 + ai * 128 + m * 16) * D + col + bj * 128; xv[m][bj][0] = *(const f32x4*)p; xv[m][bj][1] = *(const f32x4*)(p + 4); }
;         } else {
;             f16x8_t hh[4][2];
; #pragma unroll
;             for (int m = M0; m < M1; ++m)
; #pragma unroll
;                 for (int bj = 0; bj < 2; ++bj) hh[m][bj] = *(const f16x8_t*)((const bf16_t*)xin + (size_t)(row0 + ai * 128 + m * 16) * D + col + bj * 128);
; #pragma unroll
;             for (int m = M0; m < M1; ++m)
; #pragma unroll
;                 for (int bj = 0; bj < 2; ++bj) { const f32x8_t ff = __builtin_convertvector(hh[m][bj], f32x8_t); xv[m][bj][0] = (f32x4){ff[0], ff[1], ff[2], ff[3]}; xv[m][bj][1] = (f32x4){ff[4], ff[5], ff[6], ff[7]}; }
;         }
;         f32x4 gt[2][2], gs[2][2];
; #pragma unroll
;         for (int bj = 0; bj < 2; ++bj)
; #pragma unroll
;             for (int n = 0; n < 2; ++n) { gt[bj][n] = *(const f32x4*)(gate + (size_t)b * 6 * D + col + bj * 128 + n * 4); gs[bj][n] = XS ? *(const f32x4*)(GS + (size_t)b * D + col + bj * 128 + n * 4) : (f32x4){0.f, 0.f, 0.f, 0.f}; }
;         __builtin_amdgcn_sched_barrier(0);
; #pragma unroll
;         for (int m = M0; m < M1; ++m) { const int row = row0 + ai * 128 + m * 16; float ss = 0.f;
; #pragma unroll
;             for (int bj = 0; bj < 2; ++bj) { const size_t o = (size_t)row * D + col + bj * 128;
;                 const f32x4 x0 = xv[m][bj][0] + gt[bj][0] * acc[ai][bj][m][0], x1 = xv[m][bj][1] + gt[bj][1] * acc[ai][bj][m][1];
;                 if (out_f32) { *(f32x4*)((float*)xout + o) = x0; *(f32x4*)((float*)xout + o + 4) = x1; }
;                 else { const f32x8_t ff = {x0.x, x0.y, x0.z, x0.w, x1.x, x1.y, x1.z, x1.w}; *(f16x8_t*)((bf16_t*)xout + o) = __builtin_convertvector(ff, f16x8_t); }
;                 ss += ((x0.x * x0.x + x0.y * x0.y) + (x0.z * x0.z + x0.w * x0.w)) + ((x1.x * x1.x + x1.y * x1.y) + (x1.z * x1.z + x1.w * x1.w));
.LBB0_1158:
	s_or_b64 exec, exec, s[30:31]
	v_add_u32_e32 v114, 0x80, v200
	v_ashrrev_i32_e32 v115, 31, v114
	s_waitcnt lgkmcnt(0)
	v_lshlrev_b64 v[66:67], 13, v[114:115]
	v_add_u32_e32 v116, 0x90, v200
	v_lshl_add_u64 v[66:67], v[180:181], 0, v[66:67]
	v_ashrrev_i32_e32 v117, 31, v116
	global_load_dwordx4 v[118:121], v[66:67], off offset:16
	global_load_dwordx4 v[122:125], v[66:67], off
	global_load_dwordx4 v[126:129], v[66:67], off offset:528
	global_load_dwordx4 v[130:133], v[66:67], off offset:512
	v_lshlrev_b64 v[66:67], 13, v[116:117]
	v_lshl_add_u64 v[66:67], v[180:181], 0, v[66:67]
	global_load_dwordx4 v[98:101], v[66:67], off offset:16
	global_load_dwordx4 v[106:109], v[66:67], off
	global_load_dwordx4 v[74:77], v[66:67], off offset:528
	global_load_dwordx4 v[82:85], v[66:67], off offset:512
	global_load_dwordx4 v[102:105], v[182:183], off offset:16
	global_load_dwordx4 v[110:113], v[182:183], off
	global_load_dwordx4 v[90:93], v[184:185], off offset:16
	global_load_dwordx4 v[94:97], v[184:185], off
	global_load_dwordx4 v[78:81], v[182:183], off offset:528
	global_load_dwordx4 v[86:89], v[182:183], off offset:512
	global_load_dwordx4 v[66:69], v[184:185], off offset:528
	global_load_dwordx4 v[70:73], v[184:185], off offset:512
	s_waitcnt vmcnt(6)
	v_pk_fma_f32 v[62:63], v[62:63], v[110:111], v[122:123]
	v_lshlrev_b64 v[122:123], 12, v[114:115]
	v_bfe_u32 v123, v122, 12, 4
	v_lshl_add_u32 v122, v123, 6, v122
	v_lshlrev_b32_e32 v123, 12, v123
	v_sub_u32_e32 v122, v122, v123
	v_mov_b32_e32 v123, 0
	v_pk_fma_f32 v[64:65], v[64:65], v[112:113], v[124:125]
	v_pk_fma_f32 v[120:121], v[60:61], v[104:105], v[120:121]
	v_pk_fma_f32 v[118:119], v[58:59], v[102:103], v[118:119]
	v_lshl_add_u64 v[122:123], s[10:11], 0, v[122:123]
	v_cvt_pk_f16_f32 v61, v120, v121
	v_cvt_pk_f16_f32 v59, v64, v65
	v_cvt_pk_f16_f32 v60, v118, v119
	v_cvt_pk_f16_f32 v58, v62, v63
	v_lshl_add_u64 v[122:123], v[198:199], 1, v[122:123]
	v_lshl_add_u64 v[122:123], v[122:123], 0, s[100:101]
	global_store_dwordx4 v[122:123], v[58:61], off
	v_mul_f32_e32 v0, v63, v63
	v_fmac_f32_e32 v0, v62, v62
	v_mul_f32_e32 v58, v65, v65
	v_fmac_f32_e32 v58, v64, v64
	v_add_f32_e32 v0, v0, v58
	v_mul_f32_e32 v58, v119, v119
	v_mul_f32_e32 v59, v121, v121
	v_fmac_f32_e32 v58, v118, v118
	v_fmac_f32_e32 v59, v120, v120
	v_add_f32_e32 v58, v58, v59
	v_add_f32_e32 v0, v0, v58
	s_waitcnt vmcnt(5)
	v_pk_mul_f32 v[58:59], v[96:97], v[64:65]
	v_pk_mul_f32 v[60:61], v[94:95], v[62:63]
	v_pk_mul_f32 v[62:63], v[90:91], v[118:119]
	v_cvt_pk_bf16_f32 v60, v60, v61
	v_cvt_pk_bf16_f32 v61, v58, v59
	v_add_co_u32_e32 v58, vcc, s60, v178
	v_pk_mul_f32 v[64:65], v[92:93], v[120:121]
	v_cvt_pk_bf16_f32 v62, v62, v63
	s_nop 0
	v_addc_co_u32_e32 v59, vcc, 0, v179, vcc
	v_cvt_pk_bf16_f32 v63, v64, v65
	global_store_dwordx4 v[58:59], v[60:63], off
	s_waitcnt vmcnt(4)
	v_pk_fma_f32 v[56:57], v[56:57], v[88:89], v[132:133]
	v_pk_fma_f32 v[54:55], v[54:55], v[86:87], v[130:131]
	v_pk_fma_f32 v[60:61], v[52:53], v[80:81], v[128:129]
	v_pk_fma_f32 v[62:63], v[50:51], v[78:79], v[126:127]
	v_cvt_pk_f16_f32 v53, v60, v61
	v_cvt_pk_f16_f32 v51, v56, v57
	v_cvt_pk_f16_f32 v52, v62, v63
	v_cvt_pk_f16_f32 v50, v54, v55
	global_store_dwordx4 v[122:123], v[50:53], off offset:1024
	s_nop 1
	v_mul_f32_e32 v50, v55, v55
	v_mul_f32_e32 v51, v57, v57
	v_fmac_f32_e32 v50, v54, v54
	v_fmac_f32_e32 v51, v56, v56
	v_add_f32_e32 v50, v50, v51
	v_mul_f32_e32 v51, v63, v63
	v_mul_f32_e32 v52, v61, v61
	v_fmac_f32_e32 v51, v62, v62
	v_fmac_f32_e32 v52, v60, v60
	v_add_f32_e32 v51, v51, v52
	v_add_f32_e32 v50, v50, v51
	v_add_f32_e32 v0, v0, v50
	s_waitcnt vmcnt(3)
	v_pk_mul_f32 v[50:51], v[72:73], v[56:57]
	v_pk_mul_f32 v[52:53], v[70:71], v[54:55]
	v_pk_mul_f32 v[56:57], v[68:69], v[60:61]
	v_cvt_pk_bf16_f32 v52, v52, v53
	v_cvt_pk_bf16_f32 v53, v50, v51
	ds_bpermute_b32 v50, v245, v0
	v_pk_mul_f32 v[54:55], v[66:67], v[62:63]
	s_waitcnt lgkmcnt(0)
	v_add_f32_e32 v0, v0, v50
	ds_bpermute_b32 v50, v244, v0
	v_cvt_pk_bf16_f32 v54, v54, v55
	v_cvt_pk_bf16_f32 v55, v56, v57
	v_add_co_u32_e32 v56, vcc, 0x14000, v178
	s_nop 1
	v_addc_co_u32_e32 v57, vcc, 0, v179, vcc
	global_store_dwordx4 v[56:57], v[52:55], off
	s_and_saveexec_b64 s[30:31], s[28:29]
	s_cbranch_execz .LBB0_1160
	v_lshlrev_b64 v[52:53], 7, v[114:115]
	v_bfe_u32 v53, v52, 7, 4
	v_lshl_add_u32 v52, v53, 2, v52
	v_lshlrev_b32_e32 v53, 7, v53
	v_sub_u32_e32 v52, v52, v53
	v_mov_b32_e32 v53, 0
	v_lshl_add_u64 v[52:53], s[42:43], 0, v[52:53]
	v_lshl_add_u64 v[52:53], s[34:35], 2, v[52:53]
	s_mul_i32 s44, s34, 15
	s_lshl4_add_u32 s44, s71, s44
	s_lshl_b32 s44, s44, 2
	v_lshl_add_u64 v[52:53], v[52:53], 0, s[44:45]
	s_waitcnt lgkmcnt(0)
	v_add_f32_e32 v0, v0, v50
	global_store_dword v[52:53], v0, off
; __device__ __forceinline__ float bperm(float v, int src_lane) { return __int_as_float(__builtin_amdgcn_ds_bpermute(src_lane << 2, __float_as_int(v))); }
; __device__ __forceinline__ u32x4 pack8(const f32x4 a, const f32x4 b) { u32x4 w; w.x = cvt_pk_bf16(a.x, a.y); w.y = cvt_pk_bf16(a.z, a.w); w.z = cvt_pk_bf16(b.x, b.y); w.w = cvt_pk_bf16(b.z, b.w); return w; }
; __host__ __device__ __forceinline__ size_t xs_off(int row, int col) { return (size_t)(row >> 8) * (256 * D) + (size_t)(col >> 6) * (256 * 64) + (size_t)((row & 255) * 64 + (col & 63)); }
;     template <bool INF32, int M0, int M1> __device__ __forceinline__ void half(f32x4 (&acc)[2][2][4][2], int ai, int b, int row0, int col, int pn, int wc, int fr, int fq) const {
;     ...
;         for (int m = M0; m < M1; ++m) { const int row = row0 + ai * 128 + m * 16; float ss = 0.f;
; #pragma unroll
;             for (int bj = 0; bj < 2; ++bj) { const size_t o = (size_t)row * D + col + bj * 128;
;                 const f32x4 x0 = xv[m][bj][0] + gt[bj][0] * acc[ai][bj][m][0], x1 = xv[m][bj][1] + gt[bj][1] * acc[ai][bj][m][1];
;                 if (out_f32) { *(f32x4*)((float*)xout + o) = x0; *(f32x4*)((float*)xout + o + 4) = x1; }
;                 else { const f32x8_t ff = {x0.x, x0.y, x0.z, x0.w, x1.x, x1.y, x1.z, x1.w}; *(f16x8_t*)((bf16_t*)xout + o) = __builtin_convertvector(ff, f16x8_t); }
;                 ss += ((x0.x * x0.x + x0.y * x0.y) + (x0.z * x0.z + x0.w * x0.w)) + ((x1.x * x1.x + x1.y * x1.y) + (x1.z * x1.z + x1.w * x1.w));
;                 if (XS) *(u32x4*)(XS + xs_off(row0, col) + (ai * 128 + m * 16) * 64 + bj * (2 * 256 * 64)) = pack8(x0 * gs[bj][0], x1 * gs[bj][1]); }
;             { const int ln = fr + 16 * fq; ss += bperm(ss, ln ^ 16); ss += bperm(ss, ln ^ 32); }
;             if (fq == 0) RSS[(size_t)row * 32 + pn * 4 + wc] = ss; }
.LBB0_1160:
	s_or_b64 exec, exec, s[30:31]
	v_lshlrev_b64 v[54:55], 12, v[116:117]
	v_bfe_u32 v55, v54, 12, 4
	v_lshl_add_u32 v54, v55, 6, v54
	v_lshlrev_b32_e32 v55, 12, v55
	v_sub_u32_e32 v54, v54, v55
	v_mov_b32_e32 v55, 0
	v_pk_fma_f32 v[48:49], v[48:49], v[112:113], v[108:109]
	v_pk_fma_f32 v[46:47], v[46:47], v[110:111], v[106:107]
	s_waitcnt lgkmcnt(0)
	v_pk_fma_f32 v[50:51], v[44:45], v[104:105], v[100:101]
	v_pk_fma_f32 v[52:53], v[42:43], v[102:103], v[98:99]
	v_lshl_add_u64 v[54:55], s[10:11], 0, v[54:55]
	v_cvt_pk_f16_f32 v45, v50, v51
	v_cvt_pk_f16_f32 v43, v48, v49
	v_cvt_pk_f16_f32 v42, v46, v47
	v_cvt_pk_f16_f32 v44, v52, v53
	v_lshl_add_u64 v[54:55], v[198:199], 1, v[54:55]
	v_lshl_add_u64 v[54:55], v[54:55], 0, s[100:101]
	global_store_dwordx4 v[54:55], v[42:45], off
	v_mul_f32_e32 v0, v47, v47
	v_fmac_f32_e32 v0, v46, v46
	v_mul_f32_e32 v42, v49, v49
	v_fmac_f32_e32 v42, v48, v48
	v_add_f32_e32 v0, v0, v42
	v_mul_f32_e32 v42, v53, v53
	v_mul_f32_e32 v43, v51, v51
	v_fmac_f32_e32 v42, v52, v52
	v_fmac_f32_e32 v43, v50, v50
	v_add_f32_e32 v42, v42, v43
	v_add_f32_e32 v0, v0, v42
	v_pk_mul_f32 v[44:45], v[96:97], v[48:49]
	v_pk_mul_f32 v[42:43], v[94:95], v[46:47]
	v_pk_mul_f32 v[46:47], v[92:93], v[50:51]
	v_pk_mul_f32 v[48:49], v[90:91], v[52:53]
	v_cvt_pk_bf16_f32 v42, v42, v43
	v_cvt_pk_bf16_f32 v43, v44, v45
	v_pk_fma_f32 v[40:41], v[40:41], v[88:89], v[84:85]
	v_cvt_pk_bf16_f32 v44, v48, v49
	v_cvt_pk_bf16_f32 v45, v46, v47
	global_store_dwordx4 v[58:59], v[42:45], off offset:2048
	v_pk_fma_f32 v[38:39], v[38:39], v[86:87], v[82:83]
	s_nop 0
	v_pk_fma_f32 v[42:43], v[36:37], v[80:81], v[76:77]
	v_pk_fma_f32 v[44:45], v[34:35], v[78:79], v[74:75]
	v_cvt_pk_f16_f32 v37, v42, v43
	v_cvt_pk_f16_f32 v35, v40, v41
	v_cvt_pk_f16_f32 v34, v38, v39
	v_cvt_pk_f16_f32 v36, v44, v45
	global_store_dwordx4 v[54:55], v[34:37], off offset:1024
	s_nop 1
	v_mul_f32_e32 v34, v39, v39
	v_mul_f32_e32 v35, v41, v41
	v_fmac_f32_e32 v34, v38, v38
	v_fmac_f32_e32 v35, v40, v40
	v_add_f32_e32 v34, v34, v35
	v_mul_f32_e32 v35, v45, v45
	v_mul_f32_e32 v36, v43, v43
	v_fmac_f32_e32 v35, v44, v44
	v_fmac_f32_e32 v36, v42, v42
	v_add_f32_e32 v35, v35, v36
	v_add_f32_e32 v34, v34, v35
	v_add_f32_e32 v0, v0, v34
	v_pk_mul_f32 v[34:35], v[72:73], v[40:41]
	v_pk_mul_f32 v[36:37], v[70:71], v[38:39]
	v_pk_mul_f32 v[40:41], v[68:69], v[42:43]
	v_cvt_pk_bf16_f32 v36, v36, v37
	v_cvt_pk_bf16_f32 v37, v34, v35
	ds_bpermute_b32 v34, v245, v0
	v_pk_mul_f32 v[38:39], v[66:67], v[44:45]
	s_waitcnt lgkmcnt(0)
	v_add_f32_e32 v0, v0, v34
	ds_bpermute_b32 v34, v244, v0
	v_cvt_pk_bf16_f32 v38, v38, v39
	v_cvt_pk_bf16_f32 v39, v40, v41
	v_add_co_u32_e32 v40, vcc, 0x14000, v178
	s_nop 1
	v_addc_co_u32_e32 v41, vcc, 0, v179, vcc
	global_store_dwordx4 v[40:41], v[36:39], off offset:2048
	s_and_saveexec_b64 s[30:31], s[28:29]
	s_cbranch_execz .LBB0_1162
	v_lshlrev_b64 v[36:37], 7, v[116:117]
	v_bfe_u32 v37, v36, 7, 4
	v_lshl_add_u32 v36, v37, 2, v36
	v_lshlrev_b32_e32 v37, 7, v37
	v_sub_u32_e32 v36, v36, v37
	v_mov_b32_e32 v37, 0
	v_lshl_add_u64 v[36:37], s[42:43], 0, v[36:37]
	v_lshl_add_u64 v[36:37], s[34:35], 2, v[36:37]
	s_mul_i32 s44, s34, 15
	s_lshl4_add_u32 s44, s71, s44
	s_lshl_b32 s44, s44, 2
	v_lshl_add_u64 v[36:37], v[36:37], 0, s[44:45]
	s_waitcnt lgkmcnt(0)
	v_add_f32_e32 v0, v0, v34
	global_store_dword v[36:37], v0, off
;     template <bool INF32, int M0, int M1> __device__ __forceinline__ void half(f32x4 (&acc)[2][2][4][2], int ai, int b, int row0, int col, int pn, int wc, int fr, int fq) const {
;     ...
;         if (INF32) {
; #pragma unroll
;             for (int m = M0; m < M1; ++m)
; #pragma unroll
;                 for (int bj = 0; bj < 2; ++bj) { const float* p = (const float*)xin + (size_t)(row0 + ai * 128 + m * 16) * D + col + bj * 128; xv[m][bj][0] = *(const f32x4*)p; xv[m][bj][1] = *(const f32x4*)(p + 4); }
;         } else {
;             f16x8_t hh[4][2];
; #pragma unroll
;             for (int m = M0; m < M1; ++m)
; #pragma unroll
;                 for (int bj = 0; bj < 2; ++bj) hh[m][bj] = *(const f16x8_t*)((const bf16_t*)xin + (size_t)(row0 + ai * 128 + m * 16) * D + col + bj * 128);
; #pragma unroll
;             for (int m = M0; m < M1; ++m)
; #pragma unroll
;                 for (int bj = 0; bj < 2; ++bj) { const f32x8_t ff = __builtin_convertvector(hh[m][bj], f32x8_t); xv[m][bj][0] = (f32x4){ff[0], ff[1], ff[2], ff[3]}; xv[m][bj][1] = (f32x4){ff[4], ff[5], ff[6], ff[7]}; }
;         }
;         f32x4 gt[2][2], gs[2][2];
; #pragma unroll
;         for (int bj = 0; bj < 2; ++bj)
; #pragma unroll
;             for (int n = 0; n < 2; ++n) { gt[bj][n] = *(const f32x4*)(gate + (size_t)b * 6 * D + col + bj * 128 + n * 4); gs[bj][n] = XS ? *(const f32x4*)(GS + (size_t)b * D + col + bj * 128 + n * 4) : (f32x4){0.f, 0.f, 0.f, 0.f}; }
;         __builtin_amdgcn_sched_barrier(0);
; #pragma unroll
;         for (int m = M0; m < M1; ++m) { const int row = row0 + ai * 128 + m * 16; float ss = 0.f;
; #pragma unroll
;             for (int bj = 0; bj < 2; ++bj) { const size_t o = (size_t)row * D + col + bj * 128;
;                 const f32x4 x0 = xv[m][bj][0] + gt[bj][0] * acc[ai][bj][m][0], x1 = xv[m][bj][1] + gt[bj][1] * acc[ai][bj][m][1];
;                 if (out_f32) { *(f32x4*)((float*)xout + o) = x0; *(f32x4*)((float*)xout + o + 4) = x1; }
;                 else { const f32x8_t ff = {x0.x, x0.y, x0.z, x0.w, x1.x, x1.y, x1.z, x1.w}; *(f16x8_t*)((bf16_t*)xout + o) = __builtin_convertvector(ff, f16x8_t); }
;                 ss += ((x0.x * x0.x + x0.y * x0.y) + (x0.z * x0.z + x0.w * x0.w)) + ((x1.x * x1.x + x1.y * x1.y) + (x1.z * x1.z + x1.w * x1.w));
.LBB0_1162:
	s_or_b64 exec, exec, s[30:31]
	v_or_b32_e32 v82, 32, v114
	v_ashrrev_i32_e32 v83, 31, v82
	s_waitcnt lgkmcnt(0)
	v_lshlrev_b64 v[34:35], 13, v[82:83]
	v_or_b32_e32 v218, 48, v114
	v_lshl_add_u64 v[34:35], v[180:181], 0, v[34:35]
	v_ashrrev_i32_e32 v219, 31, v218
	global_load_dwordx4 v[84:87], v[34:35], off offset:16
	global_load_dwordx4 v[88:91], v[34:35], off
	global_load_dwordx4 v[92:95], v[34:35], off offset:528
	global_load_dwordx4 v[96:99], v[34:35], off offset:512
	v_lshlrev_b64 v[34:35], 13, v[218:219]
	v_lshl_add_u64 v[34:35], v[180:181], 0, v[34:35]
	global_load_dwordx4 v[66:69], v[34:35], off offset:16
	global_load_dwordx4 v[74:77], v[34:35], off
	global_load_dwordx4 v[42:45], v[34:35], off offset:528
	global_load_dwordx4 v[50:53], v[34:35], off offset:512
	global_load_dwordx4 v[70:73], v[182:183], off offset:16
	global_load_dwordx4 v[78:81], v[182:183], off
	global_load_dwordx4 v[58:61], v[184:185], off offset:16
	global_load_dwordx4 v[62:65], v[184:185], off
	global_load_dwordx4 v[46:49], v[182:183], off offset:528
	global_load_dwordx4 v[54:57], v[182:183], off offset:512
	global_load_dwordx4 v[34:37], v[184:185], off offset:528
	global_load_dwordx4 v[38:41], v[184:185], off offset:512
	s_waitcnt vmcnt(6)
	v_pk_fma_f32 v[30:31], v[30:31], v[78:79], v[88:89]
	v_lshlrev_b64 v[88:89], 12, v[82:83]
	v_bfe_u32 v89, v88, 12, 4
	v_lshl_add_u32 v88, v89, 6, v88
	v_lshlrev_b32_e32 v89, 12, v89
	v_sub_u32_e32 v88, v88, v89
	v_mov_b32_e32 v89, 0
	v_pk_fma_f32 v[32:33], v[32:33], v[80:81], v[90:91]
	v_pk_fma_f32 v[86:87], v[28:29], v[72:73], v[86:87]
	v_pk_fma_f32 v[84:85], v[26:27], v[70:71], v[84:85]
	v_lshl_add_u64 v[88:89], s[10:11], 0, v[88:89]
	v_cvt_pk_f16_f32 v29, v86, v87
	v_cvt_pk_f16_f32 v27, v32, v33
	v_cvt_pk_f16_f32 v28, v84, v85
	v_cvt_pk_f16_f32 v26, v30, v31
	v_lshl_add_u64 v[88:89], v[198:199], 1, v[88:89]
	v_lshl_add_u64 v[88:89], v[88:89], 0, s[100:101]
	global_store_dwordx4 v[88:89], v[26:29], off
	v_mul_f32_e32 v0, v31, v31
	v_fmac_f32_e32 v0, v30, v30
	v_mul_f32_e32 v26, v33, v33
	v_fmac_f32_e32 v26, v32, v32
	v_add_f32_e32 v0, v0, v26
	v_mul_f32_e32 v26, v85, v85
	v_mul_f32_e32 v27, v87, v87
	v_fmac_f32_e32 v26, v84, v84
	v_fmac_f32_e32 v27, v86, v86
	v_add_f32_e32 v26, v26, v27
	v_add_f32_e32 v0, v0, v26
	s_waitcnt vmcnt(5)
	v_pk_mul_f32 v[26:27], v[64:65], v[32:33]
	v_pk_mul_f32 v[28:29], v[62:63], v[30:31]
	v_pk_mul_f32 v[30:31], v[58:59], v[84:85]
	v_cvt_pk_bf16_f32 v28, v28, v29
	v_cvt_pk_bf16_f32 v29, v26, v27
	v_add_co_u32_e32 v26, vcc, s82, v178
	v_pk_mul_f32 v[32:33], v[60:61], v[86:87]
	v_cvt_pk_bf16_f32 v30, v30, v31
	s_nop 0
	v_addc_co_u32_e32 v27, vcc, 0, v179, vcc
	v_cvt_pk_bf16_f32 v31, v32, v33
	global_store_dwordx4 v[26:27], v[28:31], off
	s_waitcnt vmcnt(4)
	v_pk_fma_f32 v[24:25], v[24:25], v[56:57], v[98:99]
	v_pk_fma_f32 v[22:23], v[22:23], v[54:55], v[96:97]
	v_pk_fma_f32 v[28:29], v[20:21], v[48:49], v[94:95]
	v_pk_fma_f32 v[30:31], v[18:19], v[46:47], v[92:93]
	v_cvt_pk_f16_f32 v21, v28, v29
	v_cvt_pk_f16_f32 v19, v24, v25
	v_cvt_pk_f16_f32 v20, v30, v31
	v_cvt_pk_f16_f32 v18, v22, v23
	global_store_dwordx4 v[88:89], v[18:21], off offset:1024
	s_nop 1
	v_mul_f32_e32 v18, v23, v23
	v_mul_f32_e32 v19, v25, v25
	v_fmac_f32_e32 v18, v22, v22
	v_fmac_f32_e32 v19, v24, v24
	v_add_f32_e32 v18, v18, v19
	v_mul_f32_e32 v19, v31, v31
	v_mul_f32_e32 v20, v29, v29
	v_fmac_f32_e32 v19, v30, v30
	v_fmac_f32_e32 v20, v28, v28
	v_add_f32_e32 v19, v19, v20
	v_add_f32_e32 v18, v18, v19
	v_add_f32_e32 v0, v0, v18
	s_waitcnt vmcnt(3)
	v_pk_mul_f32 v[18:19], v[40:41], v[24:25]
	v_pk_mul_f32 v[20:21], v[38:39], v[22:23]
	v_pk_mul_f32 v[24:25], v[36:37], v[28:29]
	v_cvt_pk_bf16_f32 v20, v20, v21
	v_cvt_pk_bf16_f32 v21, v18, v19
	ds_bpermute_b32 v18, v245, v0
	v_pk_mul_f32 v[22:23], v[34:35], v[30:31]
	s_waitcnt lgkmcnt(0)
	v_add_f32_e32 v0, v0, v18
	ds_bpermute_b32 v18, v244, v0
	v_cvt_pk_bf16_f32 v22, v22, v23
	v_cvt_pk_bf16_f32 v23, v24, v25
	v_add_co_u32_e32 v24, vcc, 0x15000, v178
	s_nop 1
	v_addc_co_u32_e32 v25, vcc, 0, v179, vcc
	global_store_dwordx4 v[24:25], v[20:23], off
	s_and_saveexec_b64 s[30:31], s[28:29]
	s_cbranch_execz .LBB0_1164
	v_lshlrev_b64 v[20:21], 7, v[82:83]
	v_bfe_u32 v21, v20, 7, 4
	v_lshl_add_u32 v20, v21, 2, v20
	v_lshlrev_b32_e32 v21, 7, v21
	v_sub_u32_e32 v20, v20, v21
	v_mov_b32_e32 v21, 0
	v_lshl_add_u64 v[20:21], s[42:43], 0, v[20:21]
	v_lshl_add_u64 v[20:21], s[34:35], 2, v[20:21]
	s_mul_i32 s44, s34, 15
	s_lshl4_add_u32 s44, s71, s44
	s_lshl_b32 s44, s44, 2
	v_lshl_add_u64 v[20:21], v[20:21], 0, s[44:45]
	s_waitcnt lgkmcnt(0)
	v_add_f32_e32 v0, v0, v18
	global_store_dword v[20:21], v0, off

; __device__ __forceinline__ float bperm(float v, int src_lane) { return __int_as_float(__builtin_amdgcn_ds_bpermute(src_lane << 2, __float_as_int(v))); }
; __device__ __forceinline__ u32x4 pack8(const f32x4 a, const f32x4 b) { u32x4 w; w.x = cvt_pk_bf16(a.x, a.y); w.y = cvt_pk_bf16(a.z, a.w); w.z = cvt_pk_bf16(b.x, b.y); w.w = cvt_pk_bf16(b.z, b.w); return w; }
; __host__ __device__ __forceinline__ size_t xs_off(int row, int col) { return (size_t)(row >> 8) * (256 * D) + (size_t)(col >> 6) * (256 * 64) + (size_t)((row & 255) * 64 + (col & 63)); }
;     template <bool INF32, int M0, int M1> __device__ __forceinline__ void half(f32x4 (&acc)[2][2][4][2], int ai, int b, int row0, int col, int pn, int wc, int fr, int fq) const {
;     ...
;         for (int m = M0; m < M1; ++m) { const int row = row0 + ai * 128 + m * 16; float ss = 0.f;
; #pragma unroll
;             for (int bj = 0; bj < 2; ++bj) { const size_t o = (size_t)row * D + col + bj * 128;
;                 const f32x4 x0 = xv[m][bj][0] + gt[bj][0] * acc[ai][bj][m][0], x1 = xv[m][bj][1] + gt[bj][1] * acc[ai][bj][m][1];
;                 if (out_f32) { *(f32x4*)((float*)xout + o) = x0; *(f32x4*)((float*)xout + o + 4) = x1; }
;                 else { const f32x8_t ff = {x0.x, x0.y, x0.z, x0.w, x1.x, x1.y, x1.z, x1.w}; *(f16x8_t*)((bf16_t*)xout + o) = __builtin_convertvector(ff, f16x8_t); }
;                 ss += ((x0.x * x0.x + x0.y * x0.y) + (x0.z * x0.z + x0.w * x0.w)) + ((x1.x * x1.x + x1.y * x1.y) + (x1.z * x1.z + x1.w * x1.w));
;                 if (XS) *(u32x4*)(XS + xs_off(row0, col) + (ai * 128 + m * 16) * 64 + bj * (2 * 256 * 64)) = pack8(x0 * gs[bj][0], x1 * gs[bj][1]); }
;             { const int ln = fr + 16 * fq; ss += bperm(ss, ln ^ 16); ss += bperm(ss, ln ^ 32); }
;             if (fq == 0) RSS[(size_t)row * 32 + pn * 4 + wc] = ss; }
.LBB0_1165:
	v_lshlrev_b64 v[2:3], 7, v[218:219]
	v_bfe_u32 v3, v2, 7, 4
	v_lshl_add_u32 v2, v3, 2, v2
	v_lshlrev_b32_e32 v3, 7, v3
	v_sub_u32_e32 v2, v2, v3
	v_mov_b32_e32 v3, 0
	v_lshl_add_u64 v[2:3], s[42:43], 0, v[2:3]
	v_lshl_add_u64 v[2:3], s[34:35], 2, v[2:3]
	s_mul_i32 s44, s34, 15
	s_lshl4_add_u32 s44, s71, s44
	s_lshl_b32 s44, s44, 2
	s_waitcnt lgkmcnt(0)
	v_add_f32_e32 v0, v0, v130
	v_lshl_add_u64 v[2:3], v[2:3], 0, s[44:45]
	global_store_dword v[2:3], v0, off
	s_or_b64 exec, exec, s[30:31]
	s_andn2_b64 vcc, exec, s[6:7]
	s_mov_b64 s[6:7], -1
	s_cbranch_vccnz .LBB0_1120

;     __host__ __device__ __forceinline__ bool next(int i, Unit& u) const { const int vv = vid + (i / 5) * G; if (vv >= 256) return false; u.pm = vv >> 2; u.pn = (vv & 3) + 4 * (i % 5); return true; }
; #define LAS __attribute__((address_space(3)))
;     __host__ __device__ __forceinline__ bool next(int i, pg8::Unit& u) const { const long Lx = (long)i * G + c; if (Lx >= 128) return false; const int Lq = (int)Lx; u.pm = 8 * (Lq >> 5) + (Lq & 7); u.pn = (Lq >> 3) & 3; return true; }
; template <class Sched> __device__ __forceinline__ void fill_rstd(LAS unsigned char* lds, const float* RSS, const Sched& S, int tid) {
;     LAS float* T = (LAS float*)(lds + RSTD_OFF); const int row = tid & 255; pg8::Unit u;
;     int prev_pm = -1; float prev = 0.f;
;     for (int i = tid >> 8; S.next(i, u); i += 2) {
;         if (u.pm != prev_pm) { const float* p = RSS + (size_t)(u.pm * 256 + row) * 32; float s_ = 0.f;
; #pragma unroll
;             for (int j = 0; j < 8; ++j) { const f32x4 a = *(const f32x4*)(p + 4 * j); s_ += (a.x + a.y) + (a.z + a.w); }
;             prev = rsqrtf(s_ * (1.f / D) + EPS); prev_pm = u.pm; }
;         T[i * 256 + row] = prev; }
.LBB0_1245:
	s_mov_b64 s[16:17], 0xb00
	v_cmp_gt_i64_e32 vcc, s[16:17], v[2:3]
	s_or_b64 s[14:15], s[14:15], exec
	s_and_saveexec_b64 s[16:17], vcc
	s_cbranch_execz .LBB0_1244
	v_ashrrev_i32_e32 v16, 31, v2
	v_lshrrev_b32_e32 v16, 29, v16
	v_add_u32_e32 v16, v2, v16
	v_ashrrev_i32_e32 v19, 3, v16
	v_and_b32_e32 v16, -8, v16
	v_sub_u32_e32 v16, v2, v16
	v_cmp_gt_i32_e32 vcc, 0, v16
	v_mov_b32_e32 v20, 0x160
	v_mov_b32_e32 v21, 0x161
	v_cndmask_b32_e32 v20, v20, v21, vcc
	v_mul_lo_u32 v16, v16, v20
	v_add_u32_e32 v16, v16, v19
	v_mul_hi_i32 v19, v16, s55
	v_lshrrev_b32_e32 v20, 31, v19
	v_ashrrev_i32_e32 v19, 6, v19
	v_add_u32_e32 v19, v19, v20
	v_lshlrev_b32_e32 v20, 3, v19
	v_sub_u32_e32 v21, 64, v20
	v_min_i32_e32 v21, 8, v21
	v_sub_u32_e32 v22, 0, v21
	v_max_i32_e32 v21, v21, v22
	v_cvt_f32_u32_e32 v22, v21
	v_mul_i32_i24_e32 v19, 0x160, v19
	v_sub_u32_e32 v16, v16, v19
	v_sub_u32_e32 v23, 0, v16
	v_rcp_iflag_f32_e32 v22, v22
	v_ashrrev_i32_e32 v19, 31, v16
	v_max_i32_e32 v16, v16, v23
	v_sub_u32_e32 v23, 0, v21
	v_mul_f32_e32 v22, 0x4f7ffffe, v22
	v_cvt_u32_f32_e32 v22, v22
	v_mul_lo_u32 v23, v23, v22
	v_mul_hi_u32 v23, v22, v23
	v_add_u32_e32 v22, v22, v23
	v_mul_hi_u32 v22, v16, v22
	v_mul_lo_u32 v22, v22, v21
	v_sub_u32_e32 v16, v16, v22
	v_sub_u32_e32 v22, v16, v21
	v_cmp_ge_u32_e32 vcc, v16, v21
	s_nop 1
	v_cndmask_b32_e32 v16, v16, v22, vcc
	v_sub_u32_e32 v22, v16, v21
	v_cmp_ge_u32_e32 vcc, v16, v21
	s_nop 1
	v_cndmask_b32_e32 v16, v16, v22, vcc
	v_xor_b32_e32 v16, v16, v19
	v_sub_u32_e32 v16, v16, v19
	v_add_u32_e32 v16, v20, v16
	v_cmp_ne_u32_e32 vcc, v16, v18
	s_and_saveexec_b64 s[20:21], vcc
	s_cbranch_execz .LBB0_1243
	v_lshl_or_b32 v18, v16, 8, v14
	v_ashrrev_i32_e32 v19, 31, v18
	v_lshlrev_b64 v[18:19], 7, v[18:19]
	v_bfe_u32 v19, v18, 7, 4
	v_lshl_add_u32 v18, v19, 2, v18
	v_lshlrev_b32_e32 v19, 7, v19
	v_sub_u32_e32 v18, v18, v19
	v_mov_b32_e32 v19, 0
	v_lshl_add_u64 v[34:35], s[6:7], 0, v[18:19]
	global_load_dword v44, v[34:35], off
	global_load_dword v45, v[34:35], off offset:64
	global_load_dword v46, v[34:35], off offset:128
	global_load_dword v47, v[34:35], off offset:192
	global_load_dword v48, v[34:35], off offset:256
	global_load_dword v49, v[34:35], off offset:320
	global_load_dword v50, v[34:35], off offset:384
	global_load_dword v51, v[34:35], off offset:448
	global_load_dword v52, v[34:35], off offset:512
	global_load_dword v53, v[34:35], off offset:576
	global_load_dword v54, v[34:35], off offset:640
	global_load_dword v55, v[34:35], off offset:704
	global_load_dword v56, v[34:35], off offset:768
	global_load_dword v57, v[34:35], off offset:832
	global_load_dword v58, v[34:35], off offset:896
	global_load_dword v59, v[34:35], off offset:960
	global_load_dword v60, v[34:35], off offset:1024
	global_load_dword v61, v[34:35], off offset:1088
	global_load_dword v62, v[34:35], off offset:1152
	global_load_dword v63, v[34:35], off offset:1216
	global_load_dword v64, v[34:35], off offset:1280
	global_load_dword v65, v[34:35], off offset:1344
	global_load_dword v66, v[34:35], off offset:1408
	global_load_dword v67, v[34:35], off offset:1472
	global_load_dword v68, v[34:35], off offset:1536
	global_load_dword v69, v[34:35], off offset:1600
	global_load_dword v70, v[34:35], off offset:1664
	global_load_dword v71, v[34:35], off offset:1728
	global_load_dword v72, v[34:35], off offset:1792
	global_load_dword v73, v[34:35], off offset:1856
	global_load_dword v74, v[34:35], off offset:1920
	global_load_dword v75, v[34:35], off offset:1984
	s_waitcnt vmcnt(0)
	v_add_f32_e32 v44, v44, v45
	v_add_f32_e32 v46, v46, v47
	v_add_f32_e32 v48, v48, v49
	v_add_f32_e32 v50, v50, v51
	v_add_f32_e32 v52, v52, v53
	v_add_f32_e32 v54, v54, v55
	v_add_f32_e32 v56, v56, v57
	v_add_f32_e32 v58, v58, v59
	v_add_f32_e32 v60, v60, v61
	v_add_f32_e32 v62, v62, v63
	v_add_f32_e32 v64, v64, v65
	v_add_f32_e32 v66, v66, v67
	v_add_f32_e32 v68, v68, v69
	v_add_f32_e32 v70, v70, v71
	v_add_f32_e32 v72, v72, v73
	v_add_f32_e32 v74, v74, v75
	v_add_f32_e32 v44, v44, v46
	v_add_f32_e32 v48, v48, v50
	v_add_f32_e32 v52, v52, v54
	v_add_f32_e32 v56, v56, v58
	v_add_f32_e32 v60, v60, v62
	v_add_f32_e32 v64, v64, v66
	v_add_f32_e32 v68, v68, v70
	v_add_f32_e32 v72, v72, v74
	v_add_f32_e32 v44, v44, v48
	v_add_f32_e32 v52, v52, v56
	v_add_f32_e32 v60, v60, v64
	v_add_f32_e32 v68, v68, v72
	v_add_f32_e32 v44, v44, v52
	v_add_f32_e32 v60, v60, v68
	v_add_f32_e32 v44, v44, v60
	v_mov_b32_e32 v17, v44
	v_fmamk_f32 v17, v17, 0x3a000000, v240
	v_cmp_gt_f32_e32 vcc, s3, v17
	v_mul_f32_e32 v18, 0x4b800000, v17
	s_nop 0
	v_cndmask_b32_e32 v17, v17, v18, vcc
	v_rsq_f32_e32 v17, v17
	s_nop 0
	v_mul_f32_e32 v18, 0x45800000, v17
	v_cndmask_b32_e32 v17, v17, v18, vcc
	v_mov_b32_e32 v18, v16
	s_branch .LBB0_1243

; __device__ __forceinline__ float bperm(float v, int src_lane) { return __int_as_float(__builtin_amdgcn_ds_bpermute(src_lane << 2, __float_as_int(v))); }
; __device__ __forceinline__ u32x4 pack8(const f32x4 a, const f32x4 b) { u32x4 w; w.x = cvt_pk_bf16(a.x, a.y); w.y = cvt_pk_bf16(a.z, a.w); w.z = cvt_pk_bf16(b.x, b.y); w.w = cvt_pk_bf16(b.z, b.w); return w; }
; __host__ __device__ __forceinline__ size_t xs_off(int row, int col) { return (size_t)(row >> 8) * (256 * D) + (size_t)(col >> 6) * (256 * 64) + (size_t)((row & 255) * 64 + (col & 63)); }
;     template <bool INF32, int M0, int M1> __device__ __forceinline__ void half(f32x4 (&acc)[2][2][4][2], int ai, int b, int row0, int col, int pn, int wc, int fr, int fq) const {
;     ...
;         for (int m = M0; m < M1; ++m) { const int row = row0 + ai * 128 + m * 16; float ss = 0.f;
; #pragma unroll
;             for (int bj = 0; bj < 2; ++bj) { const size_t o = (size_t)row * D + col + bj * 128;
;                 const f32x4 x0 = xv[m][bj][0] + gt[bj][0] * acc[ai][bj][m][0], x1 = xv[m][bj][1] + gt[bj][1] * acc[ai][bj][m][1];
;                 if (out_f32) { *(f32x4*)((float*)xout + o) = x0; *(f32x4*)((float*)xout + o + 4) = x1; }
;                 else { const f32x8_t ff = {x0.x, x0.y, x0.z, x0.w, x1.x, x1.y, x1.z, x1.w}; *(f16x8_t*)((bf16_t*)xout + o) = __builtin_convertvector(ff, f16x8_t); }
;                 ss += ((x0.x * x0.x + x0.y * x0.y) + (x0.z * x0.z + x0.w * x0.w)) + ((x1.x * x1.x + x1.y * x1.y) + (x1.z * x1.z + x1.w * x1.w));
;                 if (XS) *(u32x4*)(XS + xs_off(row0, col) + (ai * 128 + m * 16) * 64 + bj * (2 * 256 * 64)) = pack8(x0 * gs[bj][0], x1 * gs[bj][1]); }
;             { const int ln = fr + 16 * fq; ss += bperm(ss, ln ^ 16); ss += bperm(ss, ln ^ 32); }
;             if (fq == 0) RSS[(size_t)row * 32 + pn * 4 + wc] = ss; }
.LBB0_1463:
	v_mul_f32_e32 v127, v127, v127
	v_mul_f32_e32 v123, v123, v123
	v_mul_f32_e32 v119, v119, v119
	v_mul_f32_e32 v115, v115, v115
	v_fmac_f32_e32 v127, v126, v126
	v_mul_f32_e32 v126, v129, v129
	v_fmac_f32_e32 v123, v122, v122
	v_mul_f32_e32 v122, v125, v125
	v_fmac_f32_e32 v119, v118, v118
	v_mul_f32_e32 v118, v121, v121
	v_fmac_f32_e32 v115, v114, v114
	v_mul_f32_e32 v114, v117, v117
	v_fmac_f32_e32 v126, v128, v128
	v_fmac_f32_e32 v122, v124, v124
	v_fmac_f32_e32 v118, v120, v120
	v_fmac_f32_e32 v114, v116, v116
	v_add_f32_e32 v126, v127, v126
	v_add_f32_e32 v122, v123, v122
	v_add_f32_e32 v118, v119, v118
	v_add_f32_e32 v114, v115, v114
	v_add_f32_e32 v122, v126, v122
	v_add_f32_e32 v114, v118, v114
	v_lshlrev_b32_e32 v115, 6, v234
	v_lshlrev_b32_e32 v116, 2, v233
	v_add_f32_e32 v114, v122, v114
	v_bitop3_b32 v186, v115, 64, v116 bitop3:0x36
	ds_bpermute_b32 v117, v186, v114
	v_bitop3_b32 v187, v115, s84, v116 bitop3:0x36
	s_lshl_b32 s28, s86, 2
	v_cmp_gt_u32_e64 s[10:11], 16, v232
	s_ashr_i32 s29, s28, 31
	s_waitcnt lgkmcnt(0)
	v_add_f32_e32 v114, v114, v117
	ds_bpermute_b32 v115, v187, v114
	s_and_saveexec_b64 s[30:31], s[10:11]
	s_cbranch_execz .LBB0_1465
	v_lshlrev_b64 v[116:117], 7, v[208:209]
	v_bfe_u32 v117, v116, 7, 4
	v_lshl_add_u32 v116, v117, 2, v116
	v_lshlrev_b32_e32 v117, 7, v117
	v_sub_u32_e32 v116, v116, v117
	v_mov_b32_e32 v117, 0
	v_lshl_add_u64 v[116:117], s[20:21], 0, v[116:117]
	v_lshl_add_u64 v[116:117], s[28:29], 2, v[116:117]
	s_mul_i32 s44, s28, 15
	s_lshl4_add_u32 s44, s67, s44
	s_lshl_b32 s44, s44, 2
	v_lshl_add_u64 v[116:117], v[116:117], 0, s[44:45]
	s_waitcnt lgkmcnt(0)
	v_add_f32_e32 v114, v114, v115
	global_store_dword v[116:117], v114, off

; __device__ __forceinline__ float bperm(float v, int src_lane) { return __int_as_float(__builtin_amdgcn_ds_bpermute(src_lane << 2, __float_as_int(v))); }
; __device__ __forceinline__ u32x4 pack8(const f32x4 a, const f32x4 b) { u32x4 w; w.x = cvt_pk_bf16(a.x, a.y); w.y = cvt_pk_bf16(a.z, a.w); w.z = cvt_pk_bf16(b.x, b.y); w.w = cvt_pk_bf16(b.z, b.w); return w; }
; __host__ __device__ __forceinline__ size_t xs_off(int row, int col) { return (size_t)(row >> 8) * (256 * D) + (size_t)(col >> 6) * (256 * 64) + (size_t)((row & 255) * 64 + (col & 63)); }
;     template <bool INF32, int M0, int M1> __device__ __forceinline__ void half(f32x4 (&acc)[2][2][4][2], int ai, int b, int row0, int col, int pn, int wc, int fr, int fq) const {
;     ...
;         for (int m = M0; m < M1; ++m) { const int row = row0 + ai * 128 + m * 16; float ss = 0.f;
; #pragma unroll
;             for (int bj = 0; bj < 2; ++bj) { const size_t o = (size_t)row * D + col + bj * 128;
;                 const f32x4 x0 = xv[m][bj][0] + gt[bj][0] * acc[ai][bj][m][0], x1 = xv[m][bj][1] + gt[bj][1] * acc[ai][bj][m][1];
;                 if (out_f32) { *(f32x4*)((float*)xout + o) = x0; *(f32x4*)((float*)xout + o + 4) = x1; }
;                 else { const f32x8_t ff = {x0.x, x0.y, x0.z, x0.w, x1.x, x1.y, x1.z, x1.w}; *(f16x8_t*)((bf16_t*)xout + o) = __builtin_convertvector(ff, f16x8_t); }
;                 ss += ((x0.x * x0.x + x0.y * x0.y) + (x0.z * x0.z + x0.w * x0.w)) + ((x1.x * x1.x + x1.y * x1.y) + (x1.z * x1.z + x1.w * x1.w));
;                 if (XS) *(u32x4*)(XS + xs_off(row0, col) + (ai * 128 + m * 16) * 64 + bj * (2 * 256 * 64)) = pack8(x0 * gs[bj][0], x1 * gs[bj][1]); }
;             { const int ln = fr + 16 * fq; ss += bperm(ss, ln ^ 16); ss += bperm(ss, ln ^ 32); }
;             if (fq == 0) RSS[(size_t)row * 32 + pn * 4 + wc] = ss; }
.LBB0_1469:
	v_mul_f32_e32 v111, v111, v111
	v_mul_f32_e32 v107, v107, v107
	v_mul_f32_e32 v103, v103, v103
	v_mul_f32_e32 v99, v99, v99
	v_fmac_f32_e32 v111, v110, v110
	v_mul_f32_e32 v110, v113, v113
	v_fmac_f32_e32 v107, v106, v106
	v_mul_f32_e32 v106, v109, v109
	v_fmac_f32_e32 v103, v102, v102
	v_mul_f32_e32 v102, v105, v105
	v_fmac_f32_e32 v99, v98, v98
	v_mul_f32_e32 v98, v101, v101
	v_fmac_f32_e32 v110, v112, v112
	v_fmac_f32_e32 v106, v108, v108
	v_fmac_f32_e32 v102, v104, v104
	v_fmac_f32_e32 v98, v100, v100
	v_add_f32_e32 v110, v111, v110
	v_add_f32_e32 v106, v107, v106
	v_add_f32_e32 v102, v103, v102
	v_add_f32_e32 v98, v99, v98
	v_add_f32_e32 v106, v110, v106
	v_add_f32_e32 v98, v102, v98
	v_add_f32_e32 v98, v106, v98
	ds_bpermute_b32 v99, v186, v98
	s_waitcnt lgkmcnt(0)
	v_add_f32_e32 v98, v98, v99
	ds_bpermute_b32 v99, v187, v98
	s_and_saveexec_b64 s[30:31], s[10:11]
	s_cbranch_execz .LBB0_1471
	v_lshlrev_b64 v[100:101], 7, v[224:225]
	v_bfe_u32 v101, v100, 7, 4
	v_lshl_add_u32 v100, v101, 2, v100
	v_lshlrev_b32_e32 v101, 7, v101
	v_sub_u32_e32 v100, v100, v101
	v_mov_b32_e32 v101, 0
	v_lshl_add_u64 v[100:101], s[20:21], 0, v[100:101]
	v_lshl_add_u64 v[100:101], s[28:29], 2, v[100:101]
	s_mul_i32 s44, s28, 15
	s_lshl4_add_u32 s44, s67, s44
	s_lshl_b32 s44, s44, 2
	v_lshl_add_u64 v[100:101], v[100:101], 0, s[44:45]
	s_waitcnt lgkmcnt(0)
	v_add_f32_e32 v98, v98, v99
	global_store_dword v[100:101], v98, off

; __device__ __forceinline__ float bperm(float v, int src_lane) { return __int_as_float(__builtin_amdgcn_ds_bpermute(src_lane << 2, __float_as_int(v))); }
; __device__ __forceinline__ u32x4 pack8(const f32x4 a, const f32x4 b) { u32x4 w; w.x = cvt_pk_bf16(a.x, a.y); w.y = cvt_pk_bf16(a.z, a.w); w.z = cvt_pk_bf16(b.x, b.y); w.w = cvt_pk_bf16(b.z, b.w); return w; }
; __host__ __device__ __forceinline__ size_t xs_off(int row, int col) { return (size_t)(row >> 8) * (256 * D) + (size_t)(col >> 6) * (256 * 64) + (size_t)((row & 255) * 64 + (col & 63)); }
;     template <bool INF32, int M0, int M1> __device__ __forceinline__ void half(f32x4 (&acc)[2][2][4][2], int ai, int b, int row0, int col, int pn, int wc, int fr, int fq) const {
;     ...
;         for (int m = M0; m < M1; ++m) { const int row = row0 + ai * 128 + m * 16; float ss = 0.f;
; #pragma unroll
;             for (int bj = 0; bj < 2; ++bj) { const size_t o = (size_t)row * D + col + bj * 128;
;                 const f32x4 x0 = xv[m][bj][0] + gt[bj][0] * acc[ai][bj][m][0], x1 = xv[m][bj][1] + gt[bj][1] * acc[ai][bj][m][1];
;                 if (out_f32) { *(f32x4*)((float*)xout + o) = x0; *(f32x4*)((float*)xout + o + 4) = x1; }
;                 else { const f32x8_t ff = {x0.x, x0.y, x0.z, x0.w, x1.x, x1.y, x1.z, x1.w}; *(f16x8_t*)((bf16_t*)xout + o) = __builtin_convertvector(ff, f16x8_t); }
;                 ss += ((x0.x * x0.x + x0.y * x0.y) + (x0.z * x0.z + x0.w * x0.w)) + ((x1.x * x1.x + x1.y * x1.y) + (x1.z * x1.z + x1.w * x1.w));
;                 if (XS) *(u32x4*)(XS + xs_off(row0, col) + (ai * 128 + m * 16) * 64 + bj * (2 * 256 * 64)) = pack8(x0 * gs[bj][0], x1 * gs[bj][1]); }
;             { const int ln = fr + 16 * fq; ss += bperm(ss, ln ^ 16); ss += bperm(ss, ln ^ 32); }
;             if (fq == 0) RSS[(size_t)row * 32 + pn * 4 + wc] = ss; }
.LBB0_1475:
	v_mul_f32_e32 v95, v95, v95
	v_mul_f32_e32 v91, v91, v91
	v_mul_f32_e32 v87, v87, v87
	v_mul_f32_e32 v83, v83, v83
	v_fmac_f32_e32 v95, v94, v94
	v_mul_f32_e32 v94, v97, v97
	v_fmac_f32_e32 v91, v90, v90
	v_mul_f32_e32 v90, v93, v93
	v_fmac_f32_e32 v87, v86, v86
	v_mul_f32_e32 v86, v89, v89
	v_fmac_f32_e32 v83, v82, v82
	v_mul_f32_e32 v82, v85, v85
	v_fmac_f32_e32 v94, v96, v96
	v_fmac_f32_e32 v90, v92, v92
	v_fmac_f32_e32 v86, v88, v88
	v_fmac_f32_e32 v82, v84, v84
	v_add_f32_e32 v94, v95, v94
	v_add_f32_e32 v90, v91, v90
	v_add_f32_e32 v86, v87, v86
	v_add_f32_e32 v82, v83, v82
	v_add_f32_e32 v90, v94, v90
	v_add_f32_e32 v82, v86, v82
	v_add_f32_e32 v82, v90, v82
	ds_bpermute_b32 v83, v186, v82
	s_waitcnt lgkmcnt(0)
	v_add_f32_e32 v82, v82, v83
	ds_bpermute_b32 v83, v187, v82
	s_and_saveexec_b64 s[30:31], s[10:11]
	s_cbranch_execz .LBB0_1477
	v_lshlrev_b64 v[84:85], 7, v[220:221]
	v_bfe_u32 v85, v84, 7, 4
	v_lshl_add_u32 v84, v85, 2, v84
	v_lshlrev_b32_e32 v85, 7, v85
	v_sub_u32_e32 v84, v84, v85
	v_mov_b32_e32 v85, 0
	v_lshl_add_u64 v[84:85], s[20:21], 0, v[84:85]
	v_lshl_add_u64 v[84:85], s[28:29], 2, v[84:85]
	s_mul_i32 s44, s28, 15
	s_lshl4_add_u32 s44, s67, s44
	s_lshl_b32 s44, s44, 2
	v_lshl_add_u64 v[84:85], v[84:85], 0, s[44:45]
	s_waitcnt lgkmcnt(0)
	v_add_f32_e32 v82, v82, v83
	global_store_dword v[84:85], v82, off

; __device__ __forceinline__ float bperm(float v, int src_lane) { return __int_as_float(__builtin_amdgcn_ds_bpermute(src_lane << 2, __float_as_int(v))); }
; __device__ __forceinline__ u32x4 pack8(const f32x4 a, const f32x4 b) { u32x4 w; w.x = cvt_pk_bf16(a.x, a.y); w.y = cvt_pk_bf16(a.z, a.w); w.z = cvt_pk_bf16(b.x, b.y); w.w = cvt_pk_bf16(b.z, b.w); return w; }
; __host__ __device__ __forceinline__ size_t xs_off(int row, int col) { return (size_t)(row >> 8) * (256 * D) + (size_t)(col >> 6) * (256 * 64) + (size_t)((row & 255) * 64 + (col & 63)); }
;     template <bool INF32, int M0, int M1> __device__ __forceinline__ void half(f32x4 (&acc)[2][2][4][2], int ai, int b, int row0, int col, int pn, int wc, int fr, int fq) const {
;     ...
;         for (int m = M0; m < M1; ++m) { const int row = row0 + ai * 128 + m * 16; float ss = 0.f;
; #pragma unroll
;             for (int bj = 0; bj < 2; ++bj) { const size_t o = (size_t)row * D + col + bj * 128;
;                 const f32x4 x0 = xv[m][bj][0] + gt[bj][0] * acc[ai][bj][m][0], x1 = xv[m][bj][1] + gt[bj][1] * acc[ai][bj][m][1];
;                 if (out_f32) { *(f32x4*)((float*)xout + o) = x0; *(f32x4*)((float*)xout + o + 4) = x1; }
;                 else { const f32x8_t ff = {x0.x, x0.y, x0.z, x0.w, x1.x, x1.y, x1.z, x1.w}; *(f16x8_t*)((bf16_t*)xout + o) = __builtin_convertvector(ff, f16x8_t); }
;                 ss += ((x0.x * x0.x + x0.y * x0.y) + (x0.z * x0.z + x0.w * x0.w)) + ((x1.x * x1.x + x1.y * x1.y) + (x1.z * x1.z + x1.w * x1.w));
;                 if (XS) *(u32x4*)(XS + xs_off(row0, col) + (ai * 128 + m * 16) * 64 + bj * (2 * 256 * 64)) = pack8(x0 * gs[bj][0], x1 * gs[bj][1]); }
;             { const int ln = fr + 16 * fq; ss += bperm(ss, ln ^ 16); ss += bperm(ss, ln ^ 32); }
;             if (fq == 0) RSS[(size_t)row * 32 + pn * 4 + wc] = ss; }
.LBB0_1481:
	v_mul_f32_e32 v79, v79, v79
	v_mul_f32_e32 v75, v75, v75
	v_mul_f32_e32 v71, v71, v71
	v_mul_f32_e32 v67, v67, v67
	v_fmac_f32_e32 v79, v78, v78
	v_mul_f32_e32 v78, v81, v81
	v_fmac_f32_e32 v75, v74, v74
	v_mul_f32_e32 v74, v77, v77
	v_fmac_f32_e32 v71, v70, v70
	v_mul_f32_e32 v70, v73, v73
	v_fmac_f32_e32 v67, v66, v66
	v_mul_f32_e32 v66, v69, v69
	v_fmac_f32_e32 v78, v80, v80
	v_fmac_f32_e32 v74, v76, v76
	v_fmac_f32_e32 v70, v72, v72
	v_fmac_f32_e32 v66, v68, v68
	v_add_f32_e32 v78, v79, v78
	v_add_f32_e32 v74, v75, v74
	v_add_f32_e32 v70, v71, v70
	v_add_f32_e32 v66, v67, v66
	v_add_f32_e32 v74, v78, v74
	v_add_f32_e32 v66, v70, v66
	v_add_f32_e32 v66, v74, v66
	ds_bpermute_b32 v67, v186, v66
	s_waitcnt lgkmcnt(0)
	v_add_f32_e32 v66, v66, v67
	ds_bpermute_b32 v67, v187, v66
	s_and_saveexec_b64 s[30:31], s[10:11]
	s_cbranch_execz .LBB0_1483
	v_lshlrev_b64 v[68:69], 7, v[216:217]
	v_bfe_u32 v69, v68, 7, 4
	v_lshl_add_u32 v68, v69, 2, v68
	v_lshlrev_b32_e32 v69, 7, v69
	v_sub_u32_e32 v68, v68, v69
	v_mov_b32_e32 v69, 0
	v_lshl_add_u64 v[68:69], s[20:21], 0, v[68:69]
	v_lshl_add_u64 v[68:69], s[28:29], 2, v[68:69]
	s_mul_i32 s44, s28, 15
	s_lshl4_add_u32 s44, s67, s44
	s_lshl_b32 s44, s44, 2
	v_lshl_add_u64 v[68:69], v[68:69], 0, s[44:45]
	s_waitcnt lgkmcnt(0)
	v_add_f32_e32 v66, v66, v67
	global_store_dword v[68:69], v66, off

; __device__ __forceinline__ float bperm(float v, int src_lane) { return __int_as_float(__builtin_amdgcn_ds_bpermute(src_lane << 2, __float_as_int(v))); }
; __device__ __forceinline__ u32x4 pack8(const f32x4 a, const f32x4 b) { u32x4 w; w.x = cvt_pk_bf16(a.x, a.y); w.y = cvt_pk_bf16(a.z, a.w); w.z = cvt_pk_bf16(b.x, b.y); w.w = cvt_pk_bf16(b.z, b.w); return w; }
; __host__ __device__ __forceinline__ size_t xs_off(int row, int col) { return (size_t)(row >> 8) * (256 * D) + (size_t)(col >> 6) * (256 * 64) + (size_t)((row & 255) * 64 + (col & 63)); }
;     template <bool INF32, int M0, int M1> __device__ __forceinline__ void half(f32x4 (&acc)[2][2][4][2], int ai, int b, int row0, int col, int pn, int wc, int fr, int fq) const {
;     ...
;         for (int m = M0; m < M1; ++m) { const int row = row0 + ai * 128 + m * 16; float ss = 0.f;
; #pragma unroll
;             for (int bj = 0; bj < 2; ++bj) { const size_t o = (size_t)row * D + col + bj * 128;
;                 const f32x4 x0 = xv[m][bj][0] + gt[bj][0] * acc[ai][bj][m][0], x1 = xv[m][bj][1] + gt[bj][1] * acc[ai][bj][m][1];
;                 if (out_f32) { *(f32x4*)((float*)xout + o) = x0; *(f32x4*)((float*)xout + o + 4) = x1; }
;                 else { const f32x8_t ff = {x0.x, x0.y, x0.z, x0.w, x1.x, x1.y, x1.z, x1.w}; *(f16x8_t*)((bf16_t*)xout + o) = __builtin_convertvector(ff, f16x8_t); }
;                 ss += ((x0.x * x0.x + x0.y * x0.y) + (x0.z * x0.z + x0.w * x0.w)) + ((x1.x * x1.x + x1.y * x1.y) + (x1.z * x1.z + x1.w * x1.w));
;                 if (XS) *(u32x4*)(XS + xs_off(row0, col) + (ai * 128 + m * 16) * 64 + bj * (2 * 256 * 64)) = pack8(x0 * gs[bj][0], x1 * gs[bj][1]); }
;             { const int ln = fr + 16 * fq; ss += bperm(ss, ln ^ 16); ss += bperm(ss, ln ^ 32); }
;             if (fq == 0) RSS[(size_t)row * 32 + pn * 4 + wc] = ss; }
.LBB0_1495:
	v_mul_f32_e32 v63, v63, v63
	v_mul_f32_e32 v59, v59, v59
	v_mul_f32_e32 v55, v55, v55
	v_mul_f32_e32 v51, v51, v51
	v_fmac_f32_e32 v63, v62, v62
	v_mul_f32_e32 v62, v65, v65
	v_fmac_f32_e32 v59, v58, v58
	v_mul_f32_e32 v58, v61, v61
	v_fmac_f32_e32 v55, v54, v54
	v_mul_f32_e32 v54, v57, v57
	v_fmac_f32_e32 v51, v50, v50
	v_mul_f32_e32 v50, v53, v53
	v_fmac_f32_e32 v62, v64, v64
	v_fmac_f32_e32 v58, v60, v60
	v_fmac_f32_e32 v54, v56, v56
	v_fmac_f32_e32 v50, v52, v52
	v_add_f32_e32 v62, v63, v62
	v_add_f32_e32 v58, v59, v58
	v_add_f32_e32 v54, v55, v54
	v_add_f32_e32 v50, v51, v50
	v_add_f32_e32 v58, v62, v58
	v_add_f32_e32 v50, v54, v50
	v_add_f32_e32 v50, v58, v50
	ds_bpermute_b32 v51, v186, v50
	s_waitcnt lgkmcnt(0)
	v_add_f32_e32 v50, v50, v51
	ds_bpermute_b32 v51, v187, v50
	s_and_saveexec_b64 s[30:31], s[10:11]
	s_cbranch_execz .LBB0_1497
	v_lshlrev_b64 v[52:53], 7, v[142:143]
	v_bfe_u32 v53, v52, 7, 4
	v_lshl_add_u32 v52, v53, 2, v52
	v_lshlrev_b32_e32 v53, 7, v53
	v_sub_u32_e32 v52, v52, v53
	v_mov_b32_e32 v53, 0
	v_lshl_add_u64 v[52:53], s[20:21], 0, v[52:53]
	v_lshl_add_u64 v[52:53], s[28:29], 2, v[52:53]
	s_mul_i32 s44, s28, 15
	s_lshl4_add_u32 s44, s67, s44
	s_lshl_b32 s44, s44, 2
	v_lshl_add_u64 v[52:53], v[52:53], 0, s[44:45]
	s_waitcnt lgkmcnt(0)
	v_add_f32_e32 v50, v50, v51
	global_store_dword v[52:53], v50, off

; __device__ __forceinline__ float bperm(float v, int src_lane) { return __int_as_float(__builtin_amdgcn_ds_bpermute(src_lane << 2, __float_as_int(v))); }
; __device__ __forceinline__ u32x4 pack8(const f32x4 a, const f32x4 b) { u32x4 w; w.x = cvt_pk_bf16(a.x, a.y); w.y = cvt_pk_bf16(a.z, a.w); w.z = cvt_pk_bf16(b.x, b.y); w.w = cvt_pk_bf16(b.z, b.w); return w; }
; __host__ __device__ __forceinline__ size_t xs_off(int row, int col) { return (size_t)(row >> 8) * (256 * D) + (size_t)(col >> 6) * (256 * 64) + (size_t)((row & 255) * 64 + (col & 63)); }
;     template <bool INF32, int M0, int M1> __device__ __forceinline__ void half(f32x4 (&acc)[2][2][4][2], int ai, int b, int row0, int col, int pn, int wc, int fr, int fq) const {
;     ...
;         for (int m = M0; m < M1; ++m) { const int row = row0 + ai * 128 + m * 16; float ss = 0.f;
; #pragma unroll
;             for (int bj = 0; bj < 2; ++bj) { const size_t o = (size_t)row * D + col + bj * 128;
;                 const f32x4 x0 = xv[m][bj][0] + gt[bj][0] * acc[ai][bj][m][0], x1 = xv[m][bj][1] + gt[bj][1] * acc[ai][bj][m][1];
;                 if (out_f32) { *(f32x4*)((float*)xout + o) = x0; *(f32x4*)((float*)xout + o + 4) = x1; }
;                 else { const f32x8_t ff = {x0.x, x0.y, x0.z, x0.w, x1.x, x1.y, x1.z, x1.w}; *(f16x8_t*)((bf16_t*)xout + o) = __builtin_convertvector(ff, f16x8_t); }
;                 ss += ((x0.x * x0.x + x0.y * x0.y) + (x0.z * x0.z + x0.w * x0.w)) + ((x1.x * x1.x + x1.y * x1.y) + (x1.z * x1.z + x1.w * x1.w));
;                 if (XS) *(u32x4*)(XS + xs_off(row0, col) + (ai * 128 + m * 16) * 64 + bj * (2 * 256 * 64)) = pack8(x0 * gs[bj][0], x1 * gs[bj][1]); }
;             { const int ln = fr + 16 * fq; ss += bperm(ss, ln ^ 16); ss += bperm(ss, ln ^ 32); }
;             if (fq == 0) RSS[(size_t)row * 32 + pn * 4 + wc] = ss; }
.LBB0_1501:
	v_mul_f32_e32 v47, v47, v47
	v_mul_f32_e32 v43, v43, v43
	v_mul_f32_e32 v39, v39, v39
	v_mul_f32_e32 v35, v35, v35
	v_fmac_f32_e32 v47, v46, v46
	v_mul_f32_e32 v46, v49, v49
	v_fmac_f32_e32 v43, v42, v42
	v_mul_f32_e32 v42, v45, v45
	v_fmac_f32_e32 v39, v38, v38
	v_mul_f32_e32 v38, v41, v41
	v_fmac_f32_e32 v35, v34, v34
	v_mul_f32_e32 v34, v37, v37
	v_fmac_f32_e32 v46, v48, v48
	v_fmac_f32_e32 v42, v44, v44
	v_fmac_f32_e32 v38, v40, v40
	v_fmac_f32_e32 v34, v36, v36
	v_add_f32_e32 v46, v47, v46
	v_add_f32_e32 v42, v43, v42
	v_add_f32_e32 v38, v39, v38
	v_add_f32_e32 v34, v35, v34
	v_add_f32_e32 v42, v46, v42
	v_add_f32_e32 v34, v38, v34
	v_add_f32_e32 v34, v42, v34
	ds_bpermute_b32 v35, v186, v34
	s_waitcnt lgkmcnt(0)
	v_add_f32_e32 v34, v34, v35
	ds_bpermute_b32 v35, v187, v34
	s_and_saveexec_b64 s[30:31], s[10:11]
	s_cbranch_execz .LBB0_1503
	v_lshlrev_b64 v[36:37], 7, v[138:139]
	v_bfe_u32 v37, v36, 7, 4
	v_lshl_add_u32 v36, v37, 2, v36
	v_lshlrev_b32_e32 v37, 7, v37
	v_sub_u32_e32 v36, v36, v37
	v_mov_b32_e32 v37, 0
	v_lshl_add_u64 v[36:37], s[20:21], 0, v[36:37]
	v_lshl_add_u64 v[36:37], s[28:29], 2, v[36:37]
	s_mul_i32 s44, s28, 15
	s_lshl4_add_u32 s44, s67, s44
	s_lshl_b32 s44, s44, 2
	v_lshl_add_u64 v[36:37], v[36:37], 0, s[44:45]
	s_waitcnt lgkmcnt(0)
	v_add_f32_e32 v34, v34, v35
	global_store_dword v[36:37], v34, off

; __device__ __forceinline__ float bperm(float v, int src_lane) { return __int_as_float(__builtin_amdgcn_ds_bpermute(src_lane << 2, __float_as_int(v))); }
; __device__ __forceinline__ u32x4 pack8(const f32x4 a, const f32x4 b) { u32x4 w; w.x = cvt_pk_bf16(a.x, a.y); w.y = cvt_pk_bf16(a.z, a.w); w.z = cvt_pk_bf16(b.x, b.y); w.w = cvt_pk_bf16(b.z, b.w); return w; }
; __host__ __device__ __forceinline__ size_t xs_off(int row, int col) { return (size_t)(row >> 8) * (256 * D) + (size_t)(col >> 6) * (256 * 64) + (size_t)((row & 255) * 64 + (col & 63)); }
;     template <bool INF32, int M0, int M1> __device__ __forceinline__ void half(f32x4 (&acc)[2][2][4][2], int ai, int b, int row0, int col, int pn, int wc, int fr, int fq) const {
;     ...
;         for (int m = M0; m < M1; ++m) { const int row = row0 + ai * 128 + m * 16; float ss = 0.f;
; #pragma unroll
;             for (int bj = 0; bj < 2; ++bj) { const size_t o = (size_t)row * D + col + bj * 128;
;                 const f32x4 x0 = xv[m][bj][0] + gt[bj][0] * acc[ai][bj][m][0], x1 = xv[m][bj][1] + gt[bj][1] * acc[ai][bj][m][1];
;                 if (out_f32) { *(f32x4*)((float*)xout + o) = x0; *(f32x4*)((float*)xout + o + 4) = x1; }
;                 else { const f32x8_t ff = {x0.x, x0.y, x0.z, x0.w, x1.x, x1.y, x1.z, x1.w}; *(f16x8_t*)((bf16_t*)xout + o) = __builtin_convertvector(ff, f16x8_t); }
;                 ss += ((x0.x * x0.x + x0.y * x0.y) + (x0.z * x0.z + x0.w * x0.w)) + ((x1.x * x1.x + x1.y * x1.y) + (x1.z * x1.z + x1.w * x1.w));
;                 if (XS) *(u32x4*)(XS + xs_off(row0, col) + (ai * 128 + m * 16) * 64 + bj * (2 * 256 * 64)) = pack8(x0 * gs[bj][0], x1 * gs[bj][1]); }
;             { const int ln = fr + 16 * fq; ss += bperm(ss, ln ^ 16); ss += bperm(ss, ln ^ 32); }
;             if (fq == 0) RSS[(size_t)row * 32 + pn * 4 + wc] = ss; }
.LBB0_1507:
	v_mul_f32_e32 v31, v31, v31
	v_mul_f32_e32 v27, v27, v27
	v_mul_f32_e32 v23, v23, v23
	v_mul_f32_e32 v19, v19, v19
	v_fmac_f32_e32 v31, v30, v30
	v_mul_f32_e32 v30, v33, v33
	v_fmac_f32_e32 v27, v26, v26
	v_mul_f32_e32 v26, v29, v29
	v_fmac_f32_e32 v23, v22, v22
	v_mul_f32_e32 v22, v25, v25
	v_fmac_f32_e32 v19, v18, v18
	v_mul_f32_e32 v18, v21, v21
	v_fmac_f32_e32 v30, v32, v32
	v_fmac_f32_e32 v26, v28, v28
	v_fmac_f32_e32 v22, v24, v24
	v_fmac_f32_e32 v18, v20, v20
	v_add_f32_e32 v30, v31, v30
	v_add_f32_e32 v26, v27, v26
	v_add_f32_e32 v22, v23, v22
	v_add_f32_e32 v18, v19, v18
	v_add_f32_e32 v26, v30, v26
	v_add_f32_e32 v18, v22, v18
	v_add_f32_e32 v18, v26, v18
	ds_bpermute_b32 v19, v186, v18
	s_waitcnt lgkmcnt(0)
	v_add_f32_e32 v18, v18, v19
	ds_bpermute_b32 v19, v187, v18
	s_and_saveexec_b64 s[30:31], s[10:11]
	s_cbranch_execz .LBB0_1509
	v_lshlrev_b64 v[20:21], 7, v[134:135]
	v_bfe_u32 v21, v20, 7, 4
	v_lshl_add_u32 v20, v21, 2, v20
	v_lshlrev_b32_e32 v21, 7, v21
	v_sub_u32_e32 v20, v20, v21
	v_mov_b32_e32 v21, 0
	v_lshl_add_u64 v[20:21], s[20:21], 0, v[20:21]
	v_lshl_add_u64 v[20:21], s[28:29], 2, v[20:21]
	s_mul_i32 s44, s28, 15
	s_lshl4_add_u32 s44, s67, s44
	s_lshl_b32 s44, s44, 2
	v_lshl_add_u64 v[20:21], v[20:21], 0, s[44:45]
	s_waitcnt lgkmcnt(0)
	v_add_f32_e32 v18, v18, v19
	global_store_dword v[20:21], v18, off

; __device__ __forceinline__ float bperm(float v, int src_lane) { return __int_as_float(__builtin_amdgcn_ds_bpermute(src_lane << 2, __float_as_int(v))); }
; __device__ __forceinline__ u32x4 pack8(const f32x4 a, const f32x4 b) { u32x4 w; w.x = cvt_pk_bf16(a.x, a.y); w.y = cvt_pk_bf16(a.z, a.w); w.z = cvt_pk_bf16(b.x, b.y); w.w = cvt_pk_bf16(b.z, b.w); return w; }
; __host__ __device__ __forceinline__ size_t xs_off(int row, int col) { return (size_t)(row >> 8) * (256 * D) + (size_t)(col >> 6) * (256 * 64) + (size_t)((row & 255) * 64 + (col & 63)); }
;     template <bool INF32, int M0, int M1> __device__ __forceinline__ void half(f32x4 (&acc)[2][2][4][2], int ai, int b, int row0, int col, int pn, int wc, int fr, int fq) const {
;     ...
;         for (int m = M0; m < M1; ++m) { const int row = row0 + ai * 128 + m * 16; float ss = 0.f;
; #pragma unroll
;             for (int bj = 0; bj < 2; ++bj) { const size_t o = (size_t)row * D + col + bj * 128;
;                 const f32x4 x0 = xv[m][bj][0] + gt[bj][0] * acc[ai][bj][m][0], x1 = xv[m][bj][1] + gt[bj][1] * acc[ai][bj][m][1];
;                 if (out_f32) { *(f32x4*)((float*)xout + o) = x0; *(f32x4*)((float*)xout + o + 4) = x1; }
;                 else { const f32x8_t ff = {x0.x, x0.y, x0.z, x0.w, x1.x, x1.y, x1.z, x1.w}; *(f16x8_t*)((bf16_t*)xout + o) = __builtin_convertvector(ff, f16x8_t); }
;                 ss += ((x0.x * x0.x + x0.y * x0.y) + (x0.z * x0.z + x0.w * x0.w)) + ((x1.x * x1.x + x1.y * x1.y) + (x1.z * x1.z + x1.w * x1.w));
;                 if (XS) *(u32x4*)(XS + xs_off(row0, col) + (ai * 128 + m * 16) * 64 + bj * (2 * 256 * 64)) = pack8(x0 * gs[bj][0], x1 * gs[bj][1]); }
;             { const int ln = fr + 16 * fq; ss += bperm(ss, ln ^ 16); ss += bperm(ss, ln ^ 32); }
;             if (fq == 0) RSS[(size_t)row * 32 + pn * 4 + wc] = ss; }
.LBB0_1513:
	v_mul_f32_e32 v0, v15, v15
	v_mul_f32_e32 v11, v11, v11
	v_mul_f32_e32 v7, v7, v7
	v_mul_f32_e32 v3, v3, v3
	v_fmac_f32_e32 v0, v14, v14
	v_mul_f32_e32 v14, v17, v17
	v_fmac_f32_e32 v11, v10, v10
	v_mul_f32_e32 v10, v13, v13
	v_fmac_f32_e32 v7, v6, v6
	v_mul_f32_e32 v6, v9, v9
	v_fmac_f32_e32 v3, v2, v2
	v_mul_f32_e32 v2, v5, v5
	v_fmac_f32_e32 v14, v16, v16
	v_fmac_f32_e32 v10, v12, v12
	v_fmac_f32_e32 v6, v8, v8
	v_fmac_f32_e32 v2, v4, v4
	v_add_f32_e32 v0, v0, v14
	v_add_f32_e32 v10, v11, v10
	v_add_f32_e32 v6, v7, v6
	v_add_f32_e32 v2, v3, v2
	v_add_f32_e32 v0, v0, v10
	v_add_f32_e32 v2, v6, v2
	v_add_f32_e32 v0, v0, v2
	ds_bpermute_b32 v2, v186, v0
	s_waitcnt lgkmcnt(0)
	v_add_f32_e32 v0, v0, v2
	ds_bpermute_b32 v2, v187, v0
	s_and_saveexec_b64 s[8:9], s[10:11]
	s_cbranch_execz .LBB0_1515
	s_waitcnt lgkmcnt(0)
	v_add_f32_e32 v0, v0, v2
	v_lshlrev_b64 v[2:3], 7, v[130:131]
	v_bfe_u32 v3, v2, 7, 4
	v_lshl_add_u32 v2, v3, 2, v2
	v_lshlrev_b32_e32 v3, 7, v3
	v_sub_u32_e32 v2, v2, v3
	v_mov_b32_e32 v3, 0
	v_lshl_add_u64 v[2:3], s[20:21], 0, v[2:3]
	v_lshl_add_u64 v[2:3], s[28:29], 2, v[2:3]
	s_mul_i32 s44, s28, 15
	s_lshl4_add_u32 s44, s67, s44
	s_lshl_b32 s44, s44, 2
	v_lshl_add_u64 v[2:3], v[2:3], 0, s[44:45]
	global_store_dword v[2:3], v0, off

; __device__ __forceinline__ float bperm(float v, int src_lane) { return __int_as_float(__builtin_amdgcn_ds_bpermute(src_lane << 2, __float_as_int(v))); }
; __global__ void __launch_bounds__(NTHR, 2) mk_fwd(MKArgs args) {
;     ...
;         const float* RSS1 = (const float*)(wsl + O_RSS1); const float* fin_g = args.in[16]; const bf16_t* X = (const bf16_t*)(wsl + O_X);
;         const int lane = tid & 63, wv = wid_s;
;         const bool byg = (G == 256);
;         for (int row = byg ? 2048 * (cid & 7) + (cid >> 3) * NWAVES + wv : cid * NWAVES + wv; row < (byg ? 2048 * (cid & 7) + 2048 : M); row += (byg ? 32 : G) * NWAVES) {
;             float s = (lane < 32) ? RSS1[(size_t)row * 32 + lane] : 0.f;
; #pragma unroll
;             for (int o = 32; o >= 1; o >>= 1) s += bperm(s, lane ^ o);
;             const float r = rsqrtf(s * (1.f / D) + EPS);
;             float* orow = args.out + (size_t)row * D; const bf16_t* xrow = X + (size_t)row * D;
; #pragma unroll
;             for (int j = 0; j < 4; ++j) { const int c = j * 512 + lane * 8; const f16x8_t hh = *(const f16x8_t*)(xrow + c); const f32x8_t ff = __builtin_convertvector(hh, f32x8_t);
;                 const f32x4 g0 = *(const f32x4*)(fin_g + c), g1 = *(const f32x4*)(fin_g + c + 4);
;                 *(f32x4*)(orow + c) = (f32x4){ff[0], ff[1], ff[2], ff[3]} * r * g0; *(f32x4*)(orow + c + 4) = (f32x4){ff[4], ff[5], ff[6], ff[7]} * r * g1; }
.LBB0_1596:
	s_add_i32 s10, s3, s6
	s_addk_i32 s2, 0x800
	s_and_b64 s[4:5], s[0:1], exec
	s_cselect_b32 s11, s2, 0x4000
	s_cmp_ge_i32 s10, s11
	s_cbranch_scc1 .LBB0_1601
	s_lshl_b32 s2, s38, 3
	s_and_b64 s[0:1], s[0:1], exec
	s_cselect_b32 s2, 0x100, s2
	s_ashr_i32 s1, s3, 31
	s_add_u32 s0, s6, s3
	s_addc_u32 s1, 0, s1
	s_and_b32 s100, s0, 15
	s_lshl_b32 s100, s100, 2
	s_andn2_b32 s4, s0, 15
	s_mov_b32 s5, s1
	s_lshl_b64 s[4:5], s[4:5], 7
	s_add_u32 s4, s4, s100
	s_addc_u32 s5, s5, 0
	s_add_u32 s3, s8, s4
	s_addc_u32 s5, s9, s5
	s_waitcnt vmcnt(0)
	v_and_b32_e32 v18, 63, v0
	v_mov_b32_e32 v11, 0
	s_add_u32 s4, s76, s3
	v_lshlrev_b32_e32 v6, 2, v18
	v_mov_b32_e32 v7, v11
	s_addc_u32 s5, s77, s5
	v_xor_b32_e32 v12, 0x80, v6
	v_xor_b32_e32 v13, 64, v6
	v_xor_b32_e32 v14, 32, v6
	v_xor_b32_e32 v15, 16, v6
	v_xor_b32_e32 v16, 8, v6
	v_xor_b32_e32 v17, 4, v6
	v_lshlrev_b32_e32 v6, 4, v6
	v_lshl_add_u64 v[6:7], s[4:5], 0, v[6:7]
	s_mov_b64 s[4:5], 0x304000
	s_ashr_i32 s3, s2, 31
	v_lshl_add_u64 v[6:7], v[6:7], 0, s[4:5]
	s_lshl_b64 s[4:5], s[2:3], 7
	s_lshl_b64 s[6:7], s[0:1], 13
	s_add_u32 s6, s74, s6
	v_lshlrev_b32_e32 v10, 5, v18
	s_addc_u32 s7, s75, s7
	v_lshl_add_u64 v[8:9], s[6:7], 0, v[10:11]
	s_mov_b64 s[6:7], 0x1000
	v_lshl_add_u64 v[8:9], v[8:9], 0, s[6:7]
	s_lshl_b64 s[6:7], s[2:3], 13
	s_and_b32 s100, s0, 15
	s_andn2_b32 s0, s0, 15
	s_lshl_b64 s[0:1], s[0:1], 12
	s_lshl_b32 s100, s100, 6
	s_add_u32 s0, s0, s100
	s_addc_u32 s1, s1, 0
	s_add_u32 s0, s8, s0
	s_addc_u32 s1, s9, s1
	s_add_u32 s0, s76, s0
	v_lshl_add_u64 v[0:1], s[72:73], 0, v[10:11]
	s_waitcnt lgkmcnt(0)
	v_or_b32_e32 v2, 0x1000, v10
	v_or_b32_e32 v4, 0x1800, v10
	v_and_b32_e32 v10, 3, v18
	v_lshlrev_b32_e32 v10, 4, v10
	v_bfe_u32 v44, v18, 2, 2
	v_lshl_or_b32 v10, v44, 11, v10
	v_bfe_u32 v44, v18, 4, 1
	v_lshl_or_b32 v10, v44, 10, v10
	v_bfe_u32 v44, v18, 5, 1
	v_lshl_or_b32 v10, v44, 13, v10
	s_addc_u32 s1, s77, s1
	v_mov_b32_e32 v3, v11
	v_mov_b32_e32 v5, v11
	v_lshl_add_u64 v[10:11], s[0:1], 0, v[10:11]
	s_mov_b64 s[0:1], 0x18104000
	v_cmp_gt_u32_e32 vcc, 32, v18
	v_lshl_add_u64 v[2:3], s[72:73], 0, v[2:3]
	v_lshl_add_u64 v[4:5], s[72:73], 0, v[4:5]
	v_lshl_add_u64 v[10:11], v[10:11], 0, s[0:1]
	s_lshl_b64 s[8:9], s[2:3], 12
	v_mov_b32_e32 v18, 0x358637bd
	s_mov_b32 s3, 0x800000
	s_branch .LBB0_1599
